# combined: ml_out final-stage weight loads hoisted; filter MLP output layer from prefetched registers; rg in-tile scans by hand (immediate LDS offsets, gate values kept in registers); hy_conv input sta
# speedup vs baseline: 1.0990x; 1.0060x over previous
; __device__ void filters_phase(unsigned char* lds, const Params& p) {
;     ...
;   for (int tile = blockIdx.x; tile < 576; tile += gridDim.x) {
;     const int l = tile / 288, pt = tile % 288;
;     const int posidx0 = pt * 8;
;     const int L = (posidx0 < 2048) ? 2048 : 256;
;     const int pos0 = (posidx0 < 2048) ? posidx0 : posidx0 - 2048;
;     const float* w1 = p.in[10] + l * 33 * 64;
;     const float* b1 = p.in[11] + l * 64;
;     const float* w2 = p.in[12] + l * 64 * 64;
;     const float* b2 = p.in[13] + l * 64;
;     const float* w3 = p.in[14] + l * 64 * 512;
;     const float* b3 = p.in[15] + l * 512;
;     const float* fq = p.in[16] + l * 128;
;     ...
;       for (int i = 0; i < 64; ++i) {
;         const float wv = w3[i * 512 + col];
.LBB0_161:
	s_mul_hi_i32 s6, s26, 0x38e38e39
	s_lshr_b32 s7, s6, 31
	s_ashr_i32 s28, s6, 6
	s_add_i32 s28, s28, s7
	s_mul_i32 s6, s28, 0x120
	s_sub_i32 s6, s26, s6
	s_lshl_b32 s14, s6, 3
	s_add_i32 s7, s14, 0xfffff800
	s_cmpk_lt_i32 s6, 0x100
	s_movk_i32 s6, 0x800
	s_cselect_b32 s15, s6, 0x100
	s_cselect_b32 s27, s14, s7
	v_readlane_b32 s56, v252, 54
	v_readlane_b32 s57, v252, 55
	s_lshl_b32 s58, s28, 17
	s_add_u32 s56, s56, s58
	s_addc_u32 s57, s57, 0
	v_lshlrev_b32_e32 v246, 2, v195
	global_load_dword v154, v246, s[56:57]
	v_add_u32_e32 v246, 0x800, v246
	global_load_dword v155, v246, s[56:57]
	v_add_u32_e32 v246, 0x800, v246
	global_load_dword v156, v246, s[56:57]
	v_add_u32_e32 v246, 0x800, v246
	global_load_dword v157, v246, s[56:57]
	v_add_u32_e32 v246, 0x800, v246
	global_load_dword v158, v246, s[56:57]
	v_add_u32_e32 v246, 0x800, v246
	global_load_dword v159, v246, s[56:57]
	v_add_u32_e32 v246, 0x800, v246
	global_load_dword v160, v246, s[56:57]
	v_add_u32_e32 v246, 0x800, v246
	global_load_dword v161, v246, s[56:57]
	v_add_u32_e32 v246, 0x800, v246
	global_load_dword v162, v246, s[56:57]
	v_add_u32_e32 v246, 0x800, v246
	global_load_dword v163, v246, s[56:57]
	v_add_u32_e32 v246, 0x800, v246
	global_load_dword v164, v246, s[56:57]
	v_add_u32_e32 v246, 0x800, v246
	global_load_dword v165, v246, s[56:57]
	v_add_u32_e32 v246, 0x800, v246
	global_load_dword v166, v246, s[56:57]
	v_add_u32_e32 v246, 0x800, v246
	global_load_dword v167, v246, s[56:57]
	v_add_u32_e32 v246, 0x800, v246
	global_load_dword v168, v246, s[56:57]
	v_add_u32_e32 v246, 0x800, v246
	global_load_dword v169, v246, s[56:57]
	v_add_u32_e32 v246, 0x800, v246
	global_load_dword v170, v246, s[56:57]
	v_add_u32_e32 v246, 0x800, v246
	global_load_dword v171, v246, s[56:57]
	v_add_u32_e32 v246, 0x800, v246
	global_load_dword v172, v246, s[56:57]
	v_add_u32_e32 v246, 0x800, v246
	global_load_dword v173, v246, s[56:57]
	v_add_u32_e32 v246, 0x800, v246
	global_load_dword v174, v246, s[56:57]
	v_add_u32_e32 v246, 0x800, v246
	global_load_dword v175, v246, s[56:57]
	v_add_u32_e32 v246, 0x800, v246
	global_load_dword v176, v246, s[56:57]
	v_add_u32_e32 v246, 0x800, v246
	global_load_dword v177, v246, s[56:57]
	v_add_u32_e32 v246, 0x800, v246
	global_load_dword v178, v246, s[56:57]
	v_add_u32_e32 v246, 0x800, v246
	global_load_dword v179, v246, s[56:57]
	v_add_u32_e32 v246, 0x800, v246
	global_load_dword v180, v246, s[56:57]
	v_add_u32_e32 v246, 0x800, v246
	global_load_dword v181, v246, s[56:57]
	v_add_u32_e32 v246, 0x800, v246
	global_load_dword v182, v246, s[56:57]
	v_add_u32_e32 v246, 0x800, v246
	global_load_dword v183, v246, s[56:57]
	v_add_u32_e32 v246, 0x800, v246
	global_load_dword v184, v246, s[56:57]
	v_add_u32_e32 v246, 0x800, v246
	global_load_dword v185, v246, s[56:57]
	v_add_u32_e32 v246, 0x800, v246
	global_load_dword v200, v246, s[56:57]
	v_add_u32_e32 v246, 0x800, v246
	global_load_dword v201, v246, s[56:57]
	v_add_u32_e32 v246, 0x800, v246
	global_load_dword v202, v246, s[56:57]
	v_add_u32_e32 v246, 0x800, v246
	global_load_dword v203, v246, s[56:57]
	v_add_u32_e32 v246, 0x800, v246
	global_load_dword v204, v246, s[56:57]
	v_add_u32_e32 v246, 0x800, v246
	global_load_dword v205, v246, s[56:57]
	v_add_u32_e32 v246, 0x800, v246
	global_load_dword v206, v246, s[56:57]
	v_add_u32_e32 v246, 0x800, v246
	global_load_dword v207, v246, s[56:57]
	v_add_u32_e32 v246, 0x800, v246
	global_load_dword v208, v246, s[56:57]
	v_add_u32_e32 v246, 0x800, v246
	global_load_dword v209, v246, s[56:57]
	v_add_u32_e32 v246, 0x800, v246
	global_load_dword v210, v246, s[56:57]
	v_add_u32_e32 v246, 0x800, v246
	global_load_dword v211, v246, s[56:57]
	v_add_u32_e32 v246, 0x800, v246
	global_load_dword v212, v246, s[56:57]
	v_add_u32_e32 v246, 0x800, v246
	global_load_dword v213, v246, s[56:57]
	v_add_u32_e32 v246, 0x800, v246
	global_load_dword v214, v246, s[56:57]
	v_add_u32_e32 v246, 0x800, v246
	global_load_dword v215, v246, s[56:57]
	v_add_u32_e32 v246, 0x800, v246
	global_load_dword v216, v246, s[56:57]
	v_add_u32_e32 v246, 0x800, v246
	global_load_dword v217, v246, s[56:57]
	v_add_u32_e32 v246, 0x800, v246
	global_load_dword v218, v246, s[56:57]
	v_add_u32_e32 v246, 0x800, v246
	global_load_dword v219, v246, s[56:57]
	v_add_u32_e32 v246, 0x800, v246
	global_load_dword v230, v246, s[56:57]
	v_add_u32_e32 v246, 0x800, v246
	global_load_dword v231, v246, s[56:57]
	v_add_u32_e32 v246, 0x800, v246
	global_load_dword v232, v246, s[56:57]
	v_add_u32_e32 v246, 0x800, v246
	global_load_dword v233, v246, s[56:57]
	s_and_saveexec_b64 s[16:17], s[0:1]
	s_cbranch_execz .LBB0_178
; __device__ void filters_phase(unsigned char* lds, const Params& p) {
;     ...
;     if (tid < 8 * 33) {
;       const int pp = tid / 33, f = tid % 33;
;       const float pos = (float)(pos0 + pp);
;       float v;
;       if (f == 0) v = pos / (float)(L - 1);
;       else {
;         const int bi = (f - 1) & 15;
;         const float fr = 1e-4f + (float)bi * ((15.0f - 1e-4f) / 15.0f);
;         const float kk = (float)(2.0 * 3.14159265358979323846 / (double)L);
;         const float ang = (kk * fr) * pos;
;         v = (f <= 16) ? cosf(ang) : -sinf(ang);
;       }
	v_add_u32_e32 v19, s27, v1
	v_cvt_f32_i32_e32 v19, v19
	s_and_saveexec_b64 s[6:7], s[2:3]
	s_xor_b64 s[18:19], exec, s[6:7]
	s_cbranch_execz .LBB0_175
	s_mov_b32 s8, 0x54442d18
	v_cvt_f64_u32_e32 v[48:49], s15
	s_mov_b32 s9, 0x401921fb
	v_div_scale_f64 v[50:51], s[6:7], v[48:49], v[48:49], s[8:9]
	v_rcp_f64_e32 v[52:53], v[50:51]
	v_div_scale_f64 v[54:55], vcc, s[8:9], v[48:49], s[8:9]
	s_brev_b32 s6, 18
	v_fma_f64 v[56:57], -v[50:51], v[52:53], 1.0
	v_fmac_f64_e32 v[52:53], v[52:53], v[56:57]
	v_fma_f64 v[56:57], -v[50:51], v[52:53], 1.0
	v_fmac_f64_e32 v[52:53], v[52:53], v[56:57]
	v_mul_f64 v[56:57], v[54:55], v[52:53]
	v_fma_f64 v[50:51], -v[50:51], v[56:57], v[54:55]
	v_div_fmas_f64 v[50:51], v[50:51], v[52:53], v[56:57]
	v_div_fixup_f64 v[48:49], v[50:51], v[48:49], s[8:9]
	v_cvt_f32_f64_e32 v21, v[48:49]
	v_mul_f32_e32 v21, v5, v21
	v_mul_f32_e32 v19, v21, v19
	v_and_b32_e32 v21, 0x7fffffff, v19
	v_cmp_nlt_f32_e64 s[20:21], |v19|, s6
	s_and_saveexec_b64 s[6:7], s[4:5]
	s_xor_b64 s[22:23], exec, s[6:7]
	s_cbranch_execz .LBB0_169
	s_and_saveexec_b64 s[6:7], s[20:21]
	s_xor_b64 s[24:25], exec, s[6:7]
	s_cbranch_execz .LBB0_166
	v_lshrrev_b32_e32 v23, 23, v21
	v_add_u32_e32 v23, 0xffffff88, v23
	v_cmp_lt_u32_e32 vcc, 63, v23
	v_not_b32_e32 v25, 63
	v_not_b32_e32 v27, 31
	v_cndmask_b32_e32 v25, 0, v25, vcc
	v_add_u32_e32 v23, v25, v23
	v_cmp_lt_u32_e64 s[6:7], 31, v23
	s_mov_b32 s10, 0xfe5163ab
	s_nop 0
	v_cndmask_b32_e64 v25, 0, v27, s[6:7]
	v_add_u32_e32 v23, v25, v23
	v_cmp_lt_u32_e64 s[8:9], 31, v23
	s_nop 1
	v_cndmask_b32_e64 v25, 0, v27, s[8:9]
	v_add_u32_e32 v23, v25, v23
	v_and_b32_e32 v25, 0x7fffff, v21
	v_or_b32_e32 v25, 0x800000, v25
	v_mad_u64_u32 v[48:49], s[10:11], v25, s10, 0
	v_mov_b32_e32 v192, v49
	s_mov_b32 s10, 0x3c439041
	v_mad_u64_u32 v[50:51], s[10:11], v25, s10, v[192:193]
	v_mov_b32_e32 v192, v51
	s_mov_b32 s10, 0xdb629599
	v_mad_u64_u32 v[52:53], s[10:11], v25, s10, v[192:193]
	v_mov_b32_e32 v192, v53
	s_mov_b32 s10, 0xf534ddc0
	v_mad_u64_u32 v[54:55], s[10:11], v25, s10, v[192:193]
	v_mov_b32_e32 v192, v55
	s_mov_b32 s10, 0xfc2757d1
	v_mad_u64_u32 v[56:57], s[10:11], v25, s10, v[192:193]
	v_mov_b32_e32 v192, v57
	s_mov_b32 s10, 0x4e441529
	v_mad_u64_u32 v[58:59], s[10:11], v25, s10, v[192:193]
	v_mov_b32_e32 v192, v59
	s_mov_b32 s10, 0xa2f9836e
	v_mad_u64_u32 v[60:61], s[10:11], v25, s10, v[192:193]
	v_cndmask_b32_e32 v27, v58, v54, vcc
	v_cndmask_b32_e32 v25, v60, v56, vcc
	v_cndmask_b32_e32 v31, v61, v58, vcc
	v_cndmask_b32_e64 v29, v25, v27, s[6:7]
	v_cndmask_b32_e64 v25, v31, v25, s[6:7]
	v_cndmask_b32_e32 v31, v56, v52, vcc
	v_cndmask_b32_e64 v27, v27, v31, s[6:7]
	v_cndmask_b32_e64 v25, v25, v29, s[8:9]
	v_cndmask_b32_e64 v29, v29, v27, s[8:9]
	v_sub_u32_e32 v33, 32, v23
	v_alignbit_b32 v35, v25, v29, v33
	v_cmp_eq_u32_e64 s[10:11], 0, v23
	v_cndmask_b32_e32 v48, v52, v48, vcc
	s_nop 0
	v_cndmask_b32_e64 v23, v35, v25, s[10:11]
	v_cndmask_b32_e32 v25, v54, v50, vcc
	v_cndmask_b32_e64 v31, v31, v25, s[6:7]
	v_cndmask_b32_e64 v27, v27, v31, s[8:9]
	v_alignbit_b32 v35, v29, v27, v33
	v_cndmask_b32_e64 v29, v35, v29, s[10:11]
	v_bfe_u32 v49, v23, 29, 1
	v_cndmask_b32_e64 v25, v25, v48, s[6:7]
	v_alignbit_b32 v35, v23, v29, 30
	v_sub_u32_e32 v50, 0, v49
	v_cndmask_b32_e64 v25, v31, v25, s[8:9]
	v_xor_b32_e32 v35, v35, v50
	v_alignbit_b32 v31, v27, v25, v33
	v_cndmask_b32_e64 v27, v31, v27, s[10:11]
	v_ffbh_u32_e32 v31, v35
	v_alignbit_b32 v29, v29, v27, 30
	v_min_u32_e32 v31, 32, v31
	v_alignbit_b32 v25, v27, v25, 30
	v_xor_b32_e32 v29, v29, v50
	v_sub_u32_e32 v33, 31, v31
	v_xor_b32_e32 v25, v25, v50
	v_alignbit_b32 v35, v35, v29, v33
	v_alignbit_b32 v25, v29, v25, v33
	v_alignbit_b32 v27, v35, v25, 9
	v_ffbh_u32_e32 v29, v27
	v_min_u32_e32 v29, 32, v29
	v_lshrrev_b32_e32 v37, 29, v23
	v_not_b32_e32 v33, v29
	v_alignbit_b32 v25, v27, v25, v33
	v_lshlrev_b32_e32 v27, 31, v37
	v_or_b32_e32 v33, 0x33000000, v27
	v_add_lshl_u32 v29, v29, v31, 23
	v_lshrrev_b32_e32 v25, 9, v25
	v_sub_u32_e32 v29, v33, v29
	v_or_b32_e32 v27, 0.5, v27
	v_lshlrev_b32_e32 v31, 23, v31
	v_or_b32_e32 v25, v29, v25
	v_lshrrev_b32_e32 v29, 9, v35
	v_sub_u32_e32 v27, v27, v31
	v_or_b32_e32 v27, v29, v27
	v_mul_f32_e32 v29, 0x3fc90fda, v27
	s_mov_b32 s6, 0x3fc90fda
	v_fma_f32 v31, v27, s6, -v29
	v_fmac_f32_e32 v31, 0x33a22168, v27
	v_fmac_f32_e32 v31, 0x3fc90fda, v25
	v_lshrrev_b32_e32 v23, 30, v23
	v_add_f32_e32 v25, v29, v31
	v_add_u32_e32 v23, v49, v23

; __device__ void filters_phase(unsigned char* lds, const Params& p) {
;     ...
;     __syncthreads();
;     {
;       const int pp = tid >> 6, j = tid & 63;
;       float s = b1[j];
;       for (int f = 0; f < 33; ++f) s += feats[pp * 33 + f] * w1[f * 64 + j];
;       h1[pp * 64 + j] = sinf(fq[j] * s);
;     }
.LBB0_178:
	s_or_b64 exec, exec, s[16:17]
	s_mul_i32 s6, s28, 0x840
	s_ashr_i32 s7, s6, 31
	v_readlane_b32 s40, v252, 42
	s_lshl_b64 s[6:7], s[6:7], 2
	v_readlane_b32 s44, v252, 46
	v_readlane_b32 s45, v252, 47
	s_add_u32 s6, s44, s6
	s_addc_u32 s7, s45, s7
	s_lshl_b32 s16, s28, 6
	s_ashr_i32 s17, s16, 31
	v_lshl_add_u64 v[48:49], s[16:17], 2, v[38:39]
	s_waitcnt lgkmcnt(0)
	s_waitcnt vmcnt(0)
	s_barrier
	global_load_dword v57, v[48:49], off
	v_lshlrev_b32_e32 v192, 2, v0
	global_load_dword v100, v192, s[6:7]
	global_load_dword v101, v192, s[6:7] offset:256
	global_load_dword v102, v192, s[6:7] offset:512
	global_load_dword v103, v192, s[6:7] offset:768
	global_load_dword v104, v192, s[6:7] offset:1024
	global_load_dword v105, v192, s[6:7] offset:1280
	global_load_dword v106, v192, s[6:7] offset:1536
	v_lshlrev_b32_e32 v21, 2, v18
	v_lshlrev_b32_e32 v19, 2, v20
	global_load_dword v58, v21, s[6:7]
	v_lshlrev_b32_e32 v25, 2, v22
	v_lshlrev_b32_e32 v23, 2, v24
	v_lshlrev_b32_e32 v29, 2, v26
	v_lshlrev_b32_e32 v27, 2, v28
	global_load_dword v59, v19, s[6:7]
	global_load_dword v60, v25, s[6:7]
	global_load_dword v61, v23, s[6:7]
	global_load_dword v62, v29, s[6:7]
	global_load_dword v63, v27, s[6:7]
	global_load_dword v107, v192, s[6:7] offset:1792
	global_load_dword v108, v192, s[6:7] offset:2048
	global_load_dword v109, v192, s[6:7] offset:2304
	global_load_dword v110, v192, s[6:7] offset:2560
	global_load_dword v111, v192, s[6:7] offset:2816
	global_load_dword v112, v192, s[6:7] offset:3072
	global_load_dword v113, v192, s[6:7] offset:3328
	global_load_dword v114, v192, s[6:7] offset:3584
	global_load_dword v115, v192, s[6:7] offset:3840
	v_lshlrev_b32_e32 v56, 2, v4
	v_lshlrev_b32_e32 v55, 2, v6
	v_lshlrev_b32_e32 v54, 2, v8
	v_lshlrev_b32_e32 v53, 2, v10
	v_lshlrev_b32_e32 v52, 2, v12
	v_lshlrev_b32_e32 v51, 2, v14
	v_lshlrev_b32_e32 v50, 2, v16
	global_load_dword v116, v56, s[6:7]
	global_load_dword v117, v55, s[6:7]
	global_load_dword v118, v54, s[6:7]
	global_load_dword v119, v53, s[6:7]
	global_load_dword v120, v52, s[6:7]
	global_load_dword v121, v51, s[6:7]
	global_load_dword v122, v50, s[6:7]
	v_lshlrev_b32_e32 v33, 2, v30
	v_lshlrev_b32_e32 v31, 2, v32
	v_lshlrev_b32_e32 v35, 2, v34
	global_load_dword v64, v33, s[6:7]
	global_load_dword v65, v31, s[6:7]
	global_load_dword v66, v35, s[6:7]
	v_lshlrev_b32_e32 v37, 2, v36
	s_lshl_b32 s8, s28, 7
	global_load_dword v67, v37, s[6:7]
	s_ashr_i32 s9, s8, 31
	v_lshl_add_u64 v[48:49], s[8:9], 2, v[40:41]
	global_load_dword v123, v[48:49], off
	ds_read2_b32 v[68:69], v17 offset1:1
	ds_read2_b32 v[70:71], v17 offset0:2 offset1:3
	ds_read2_b32 v[72:73], v17 offset0:4 offset1:5
	ds_read2_b32 v[74:75], v17 offset0:6 offset1:7
	ds_read2_b32 v[76:77], v17 offset0:8 offset1:9
	ds_read2_b32 v[78:79], v17 offset0:10 offset1:11
	ds_read2_b32 v[80:81], v17 offset0:12 offset1:13
	ds_read2_b32 v[82:83], v17 offset0:14 offset1:15
	ds_read2_b32 v[84:85], v17 offset0:16 offset1:17
	ds_read2_b32 v[86:87], v17 offset0:18 offset1:19
	ds_read2_b32 v[88:89], v17 offset0:20 offset1:21
	ds_read_b32 v124, v17 offset:88
	ds_read2_b32 v[90:91], v17 offset0:23 offset1:24
	ds_read2_b32 v[92:93], v17 offset0:25 offset1:26
	ds_read2_b32 v[94:95], v17 offset0:27 offset1:28
	ds_read2_b32 v[96:97], v17 offset0:29 offset1:30
	ds_read2_b32 v[98:99], v17 offset0:31 offset1:32
	s_brev_b32 s6, 18
	v_readlane_b32 s41, v252, 43
	v_readlane_b32 s42, v252, 44
	v_readlane_b32 s43, v252, 45
	v_readlane_b32 s46, v252, 48
	v_readlane_b32 s47, v252, 49
	v_readlane_b32 s48, v252, 50
	v_readlane_b32 s49, v252, 51
	v_readlane_b32 s50, v252, 52
	v_readlane_b32 s51, v252, 53
	v_readlane_b32 s52, v252, 54
	v_readlane_b32 s53, v252, 55
	v_readlane_b32 s54, v252, 56
	v_readlane_b32 s55, v252, 57
	s_waitcnt vmcnt(23) lgkmcnt(3)
	v_pk_mul_f32 v[60:61], v[92:93], v[60:61]
	v_fmac_f32_e32 v57, v68, v100
	v_fmac_f32_e32 v57, v69, v101
	v_fmac_f32_e32 v57, v70, v102
	v_fmac_f32_e32 v57, v71, v103
	v_fmac_f32_e32 v57, v72, v104
	v_fmac_f32_e32 v57, v73, v105
	v_fmac_f32_e32 v57, v74, v106
	s_waitcnt vmcnt(20)
	v_fmac_f32_e32 v57, v75, v107
	s_waitcnt vmcnt(19)
	v_fmac_f32_e32 v57, v76, v108
	s_waitcnt vmcnt(18)
	v_fmac_f32_e32 v57, v77, v109
	s_waitcnt vmcnt(17)
	v_fmac_f32_e32 v57, v78, v110
	s_waitcnt vmcnt(16)
	v_fmac_f32_e32 v57, v79, v111
	s_waitcnt vmcnt(15)
	v_fmac_f32_e32 v57, v80, v112
	s_waitcnt vmcnt(14)
	v_fmac_f32_e32 v57, v81, v113
	s_waitcnt vmcnt(13)
	v_fmac_f32_e32 v57, v82, v114
	s_waitcnt vmcnt(12)
	v_fmac_f32_e32 v57, v83, v115
	s_waitcnt vmcnt(11)
	v_fmac_f32_e32 v57, v84, v116
	s_waitcnt vmcnt(10)
	v_fmac_f32_e32 v57, v85, v117
	s_waitcnt vmcnt(9)
	v_fmac_f32_e32 v57, v86, v118
	s_waitcnt vmcnt(8)
	v_fmac_f32_e32 v57, v87, v119
	s_waitcnt vmcnt(7)
	v_fmac_f32_e32 v57, v88, v120
	s_waitcnt vmcnt(6)
	v_fmac_f32_e32 v57, v89, v121
	v_pk_mul_f32 v[58:59], v[90:91], v[58:59]
	s_waitcnt vmcnt(5)
	v_fmac_f32_e32 v57, v124, v122
	v_add_f32_e32 v57, v57, v58
	v_add_f32_e32 v57, v57, v59
	v_add_f32_e32 v57, v57, v60
	s_waitcnt lgkmcnt(2)
	v_pk_mul_f32 v[62:63], v[94:95], v[62:63]
	v_add_f32_e32 v57, v57, v61
	v_add_f32_e32 v57, v57, v62
	v_add_f32_e32 v57, v57, v63
	s_waitcnt vmcnt(3) lgkmcnt(1)
	v_pk_mul_f32 v[58:59], v[96:97], v[64:65]
	s_nop 0
	v_add_f32_e32 v57, v57, v58
	v_add_f32_e32 v57, v57, v59
	s_waitcnt vmcnt(1) lgkmcnt(0)
	v_pk_mul_f32 v[58:59], v[98:99], v[66:67]
	s_nop 0
	v_add_f32_e32 v57, v57, v58
	v_add_f32_e32 v57, v57, v59
	s_waitcnt vmcnt(0)
	v_mul_f32_e32 v57, v123, v57
	v_and_b32_e32 v58, 0x7fffffff, v57
	v_cmp_nlt_f32_e64 s[6:7], |v57|, s6
	s_and_saveexec_b64 s[8:9], s[6:7]
	s_xor_b64 s[18:19], exec, s[8:9]
	s_cbranch_execz .LBB0_180
; __device__ void filters_phase(unsigned char* lds, const Params& p) {
;     ...
;       h1[pp * 64 + j] = sinf(fq[j] * s);
	v_lshrrev_b32_e32 v59, 23, v58
	v_add_u32_e32 v59, 0xffffff88, v59
	v_cmp_lt_u32_e32 vcc, 63, v59
	v_not_b32_e32 v60, 63
	v_not_b32_e32 v61, 31
	v_cndmask_b32_e32 v60, 0, v60, vcc
	v_add_u32_e32 v59, v60, v59
	v_cmp_lt_u32_e64 s[6:7], 31, v59
	s_mov_b32 s10, 0xfe5163ab
	v_mov_b32_e32 v63, v193
	v_cndmask_b32_e64 v60, 0, v61, s[6:7]
	v_add_u32_e32 v59, v60, v59
	v_cmp_lt_u32_e64 s[8:9], 31, v59
	v_mov_b32_e32 v65, v193
	v_mov_b32_e32 v67, v193
	v_cndmask_b32_e64 v60, 0, v61, s[8:9]
	v_add_u32_e32 v59, v60, v59
	v_and_b32_e32 v60, 0x7fffff, v58
	v_or_b32_e32 v74, 0x800000, v60
	v_mad_u64_u32 v[60:61], s[10:11], v74, s10, 0
	v_mov_b32_e32 v62, v61
	s_mov_b32 s10, 0x3c439041
	v_mad_u64_u32 v[62:63], s[10:11], v74, s10, v[62:63]
	v_mov_b32_e32 v64, v63
	s_mov_b32 s10, 0xdb629599
	v_mad_u64_u32 v[64:65], s[10:11], v74, s10, v[64:65]
	v_mov_b32_e32 v66, v65
	s_mov_b32 s10, 0xf534ddc0
	v_mad_u64_u32 v[66:67], s[10:11], v74, s10, v[66:67]
	v_mov_b32_e32 v68, v67
	v_mov_b32_e32 v69, v193
	s_mov_b32 s10, 0xfc2757d1
	v_mad_u64_u32 v[68:69], s[10:11], v74, s10, v[68:69]
	v_mov_b32_e32 v70, v69
	v_mov_b32_e32 v71, v193
	s_mov_b32 s10, 0x4e441529
	v_mad_u64_u32 v[70:71], s[10:11], v74, s10, v[70:71]
	v_mov_b32_e32 v72, v71
	v_mov_b32_e32 v73, v193
	s_mov_b32 s10, 0xa2f9836e
	v_mad_u64_u32 v[72:73], s[10:11], v74, s10, v[72:73]
	v_cndmask_b32_e32 v61, v70, v66, vcc
	v_cndmask_b32_e32 v63, v72, v68, vcc
	v_cndmask_b32_e32 v67, v73, v70, vcc
	v_cndmask_b32_e64 v65, v63, v61, s[6:7]
	v_cndmask_b32_e64 v63, v67, v63, s[6:7]
	v_cndmask_b32_e32 v67, v68, v64, vcc
	v_cndmask_b32_e64 v61, v61, v67, s[6:7]
	v_cndmask_b32_e64 v63, v63, v65, s[8:9]
	v_cndmask_b32_e64 v65, v65, v61, s[8:9]
	v_sub_u32_e32 v68, 32, v59
	v_alignbit_b32 v69, v63, v65, v68
	v_cmp_eq_u32_e64 s[10:11], 0, v59
	v_cndmask_b32_e32 v62, v66, v62, vcc
	v_cndmask_b32_e32 v60, v64, v60, vcc
	v_cndmask_b32_e64 v59, v69, v63, s[10:11]
	v_cndmask_b32_e64 v63, v67, v62, s[6:7]
	v_cndmask_b32_e64 v61, v61, v63, s[8:9]
	v_alignbit_b32 v66, v65, v61, v68
	v_cndmask_b32_e64 v65, v66, v65, s[10:11]
	v_bfe_u32 v69, v59, 29, 1
	v_cndmask_b32_e64 v60, v62, v60, s[6:7]
	v_alignbit_b32 v66, v59, v65, 30
	v_sub_u32_e32 v70, 0, v69
	v_cndmask_b32_e64 v60, v63, v60, s[8:9]
	v_xor_b32_e32 v66, v66, v70
	v_alignbit_b32 v62, v61, v60, v68
	v_cndmask_b32_e64 v61, v62, v61, s[10:11]
	v_ffbh_u32_e32 v63, v66
	v_alignbit_b32 v62, v65, v61, 30
	v_min_u32_e32 v63, 32, v63
	v_alignbit_b32 v60, v61, v60, 30
	v_xor_b32_e32 v62, v62, v70
	v_sub_u32_e32 v64, 31, v63
	v_xor_b32_e32 v60, v60, v70
	v_alignbit_b32 v65, v66, v62, v64
	v_alignbit_b32 v60, v62, v60, v64
	v_alignbit_b32 v61, v65, v60, 9
	v_ffbh_u32_e32 v62, v61
	v_min_u32_e32 v62, 32, v62
	v_lshrrev_b32_e32 v67, 29, v59
	v_not_b32_e32 v64, v62
	v_alignbit_b32 v60, v61, v60, v64
	v_lshlrev_b32_e32 v61, 31, v67
	v_or_b32_e32 v64, 0x33000000, v61
	v_add_lshl_u32 v62, v62, v63, 23
	v_lshrrev_b32_e32 v60, 9, v60
	v_sub_u32_e32 v62, v64, v62
	v_or_b32_e32 v61, 0.5, v61
	v_lshlrev_b32_e32 v63, 23, v63
	v_or_b32_e32 v60, v62, v60
	v_lshrrev_b32_e32 v62, 9, v65
	v_sub_u32_e32 v61, v61, v63
	v_or_b32_e32 v61, v62, v61
	v_mul_f32_e32 v62, 0x3fc90fda, v61
	s_mov_b32 s6, 0x3fc90fda
	v_fma_f32 v63, v61, s6, -v62
	v_fmac_f32_e32 v63, 0x33a22168, v61
	v_fmac_f32_e32 v63, 0x3fc90fda, v60
	v_lshrrev_b32_e32 v59, 30, v59
	v_add_f32_e32 v60, v62, v63
	v_add_u32_e32 v59, v69, v59

; __device__ void filters_phase(unsigned char* lds, const Params& p) {
;     ...
;     __syncthreads();
;     {
;       const int col = tid;
;       const int dir = col >> 8, c = col & 255;
;       float acc[8];
; #pragma unroll
;       for (int pp = 0; pp < 8; ++pp) acc[pp] = b3[col];
;       for (int i = 0; i < 64; ++i) {
;         const float wv = w3[i * 512 + col];
; #pragma unroll
;         for (int pp = 0; pp < 8; ++pp) acc[pp] += h2[pp * 64 + i] * wv;
;       }
.LBB0_186:
	s_or_b64 exec, exec, s[6:7]
	v_mul_f32_e32 v27, v25, v25
	v_mov_b32_e32 v29, 0x3c0881c4
	v_fmamk_f32 v29, v27, 0xb94c1982, v29
	v_fmaak_f32 v29, v27, v29, 0xbe2aaa9d
	v_mul_f32_e32 v29, v27, v29
	v_fmac_f32_e32 v25, v25, v29
	v_mov_b32_e32 v29, 0xbab64f3b
	v_fmamk_f32 v29, v27, 0x37d75334, v29
	s_lshl_b32 s6, s28, 15
	v_fmaak_f32 v29, v27, v29, 0x3d2aabf7
	s_ashr_i32 s7, s6, 31
	v_readlane_b32 s40, v252, 42
	v_fmaak_f32 v29, v27, v29, 0xbf000004
	s_lshl_b64 s[10:11], s[6:7], 2
	v_readlane_b32 s52, v252, 54
	v_fma_f32 v27, v27, v29, 1.0
	v_and_b32_e32 v29, 1, v23
	v_lshlrev_b32_e32 v23, 30, v23
	v_readlane_b32 s53, v252, 55
	s_add_u32 s6, s52, s10
	v_cmp_eq_u32_e32 vcc, 0, v29
	v_and_b32_e32 v23, 0x80000000, v23
	v_xor_b32_e32 v21, v21, v19
	s_addc_u32 s7, s53, s11
	s_lshl_b32 s8, s28, 9
	v_cndmask_b32_e32 v25, v27, v25, vcc
	v_xor_b32_e32 v21, v21, v23
	s_movk_i32 s16, 0x1f8
	s_ashr_i32 s9, s8, 31
	v_xor_b32_e32 v21, v21, v25
	v_cmp_class_f32_e64 vcc, v19, s16
	v_mov_b32_e32 v19, 0x7fc00000
	v_lshl_add_u64 v[48:49], s[8:9], 2, v[44:45]
	v_cndmask_b32_e32 v19, v19, v21, vcc
	ds_write_b32 v7, v19 offset:3104
	s_waitcnt lgkmcnt(0)
	s_barrier
	v_lshlrev_b32_e32 v246, 2, v195
	v_add_u32_e32 v246, 0x1c000, v246
	global_load_dword v234, v246, s[56:57]
	v_add_u32_e32 v246, 0x800, v246
	global_load_dword v235, v246, s[56:57]
	v_add_u32_e32 v246, 0x800, v246
	global_load_dword v236, v246, s[56:57]
	v_add_u32_e32 v246, 0x800, v246
	global_load_dword v237, v246, s[56:57]
	v_add_u32_e32 v246, 0x800, v246
	global_load_dword v240, v246, s[56:57]
	v_add_u32_e32 v246, 0x800, v246
	global_load_dword v241, v246, s[56:57]
	v_add_u32_e32 v246, 0x800, v246
	global_load_dword v242, v246, s[56:57]
	v_add_u32_e32 v246, 0x800, v246
	global_load_dword v243, v246, s[56:57]
	global_load_dword v54, v[48:49], off
	s_mov_b32 s8, 0
	v_mov_b32_e32 v56, v15
	v_lshl_add_u64 v[58:59], v[46:47], 0, s[10:11]
	s_mov_b64 s[10:11], 0x2000
	v_readlane_b32 s41, v252, 43
	v_readlane_b32 s42, v252, 44
	v_readlane_b32 s43, v252, 45
	v_readlane_b32 s44, v252, 46
	v_readlane_b32 s45, v252, 47
	v_readlane_b32 s46, v252, 48
	v_readlane_b32 s47, v252, 49
	v_readlane_b32 s48, v252, 50
	v_readlane_b32 s49, v252, 51
	v_readlane_b32 s50, v252, 52
	v_readlane_b32 s51, v252, 53
	v_readlane_b32 s54, v252, 56
	v_readlane_b32 s55, v252, 57
	s_waitcnt vmcnt(0)
	v_mov_b32_e32 v55, v54
	v_mov_b32_e32 v52, v54
	v_mov_b32_e32 v53, v54
	v_mov_b32_e32 v50, v54
	v_mov_b32_e32 v51, v54
	v_mov_b32_e32 v48, v54
	v_mov_b32_e32 v49, v54
	v_mov_b32_e32 v60, v54
	v_mov_b32_e32 v61, 0
	v_mov_b32_e32 v62, v54
	v_mov_b32_e32 v63, 0
	v_mov_b32_e32 v64, v54
	v_mov_b32_e32 v65, 0
	v_mov_b32_e32 v66, v54
	v_mov_b32_e32 v67, 0
	v_mov_b32_e32 v68, v54
	v_mov_b32_e32 v69, 0
	v_mov_b32_e32 v70, v54
	v_mov_b32_e32 v71, 0
	v_mov_b32_e32 v72, v54
	v_mov_b32_e32 v73, 0
	v_mov_b32_e32 v74, v54
	v_mov_b32_e32 v75, 0
	ds_read_b128 v[76:79], v193 offset:3104
	ds_read_b128 v[80:83], v193 offset:3120
	ds_read_b128 v[84:87], v193 offset:3136
	ds_read_b128 v[88:91], v193 offset:3152
	ds_read_b128 v[92:95], v193 offset:3360
	ds_read_b128 v[96:99], v193 offset:3376
	ds_read_b128 v[100:103], v193 offset:3392
	ds_read_b128 v[104:107], v193 offset:3408
	ds_read_b128 v[108:111], v193 offset:3616
	ds_read_b128 v[112:115], v193 offset:3632
	ds_read_b128 v[116:119], v193 offset:3648
	ds_read_b128 v[120:123], v193 offset:3664
	s_waitcnt lgkmcnt(8)
	v_pk_fma_f32 v[60:61], v[76:77], v[154:155], v[60:61]
	v_pk_fma_f32 v[60:61], v[78:79], v[156:157], v[60:61]
	v_pk_fma_f32 v[60:61], v[80:81], v[158:159], v[60:61]
	v_pk_fma_f32 v[60:61], v[82:83], v[160:161], v[60:61]
	v_pk_fma_f32 v[60:61], v[84:85], v[162:163], v[60:61]
	v_pk_fma_f32 v[60:61], v[86:87], v[164:165], v[60:61]
	v_pk_fma_f32 v[60:61], v[88:89], v[166:167], v[60:61]
	v_pk_fma_f32 v[60:61], v[90:91], v[168:169], v[60:61]
	ds_read_b128 v[76:79], v193 offset:3872
	ds_read_b128 v[80:83], v193 offset:3888
	ds_read_b128 v[84:87], v193 offset:3904
	ds_read_b128 v[88:91], v193 offset:3920
	s_waitcnt lgkmcnt(8)
	v_pk_fma_f32 v[62:63], v[92:93], v[154:155], v[62:63]
	v_pk_fma_f32 v[62:63], v[94:95], v[156:157], v[62:63]
	v_pk_fma_f32 v[62:63], v[96:97], v[158:159], v[62:63]
	v_pk_fma_f32 v[62:63], v[98:99], v[160:161], v[62:63]
	v_pk_fma_f32 v[62:63], v[100:101], v[162:163], v[62:63]
	v_pk_fma_f32 v[62:63], v[102:103], v[164:165], v[62:63]
	v_pk_fma_f32 v[62:63], v[104:105], v[166:167], v[62:63]
	v_pk_fma_f32 v[62:63], v[106:107], v[168:169], v[62:63]
	ds_read_b128 v[92:95], v193 offset:4128
	ds_read_b128 v[96:99], v193 offset:4144
	ds_read_b128 v[100:103], v193 offset:4160
	ds_read_b128 v[104:107], v193 offset:4176
	s_waitcnt lgkmcnt(8)
	v_pk_fma_f32 v[64:65], v[108:109], v[154:155], v[64:65]
	v_pk_fma_f32 v[64:65], v[110:111], v[156:157], v[64:65]
	v_pk_fma_f32 v[64:65], v[112:113], v[158:159], v[64:65]
	v_pk_fma_f32 v[64:65], v[114:115], v[160:161], v[64:65]
	v_pk_fma_f32 v[64:65], v[116:117], v[162:163], v[64:65]
	v_pk_fma_f32 v[64:65], v[118:119], v[164:165], v[64:65]
	v_pk_fma_f32 v[64:65], v[120:121], v[166:167], v[64:65]
	v_pk_fma_f32 v[64:65], v[122:123], v[168:169], v[64:65]
	ds_read_b128 v[108:111], v193 offset:4384
	ds_read_b128 v[112:115], v193 offset:4400
	ds_read_b128 v[116:119], v193 offset:4416
	ds_read_b128 v[120:123], v193 offset:4432
	s_waitcnt lgkmcnt(8)
; __device__ void filters_phase(unsigned char* lds, const Params& p) {
;     ...
;       for (int i = 0; i < 64; ++i) {
;         const float wv = w3[i * 512 + col];
; #pragma unroll
;         for (int pp = 0; pp < 8; ++pp) acc[pp] += h2[pp * 64 + i] * wv;
;       }
	v_pk_fma_f32 v[66:67], v[76:77], v[154:155], v[66:67]
	v_pk_fma_f32 v[66:67], v[78:79], v[156:157], v[66:67]
	v_pk_fma_f32 v[66:67], v[80:81], v[158:159], v[66:67]
	v_pk_fma_f32 v[66:67], v[82:83], v[160:161], v[66:67]
	v_pk_fma_f32 v[66:67], v[84:85], v[162:163], v[66:67]
	v_pk_fma_f32 v[66:67], v[86:87], v[164:165], v[66:67]
	v_pk_fma_f32 v[66:67], v[88:89], v[166:167], v[66:67]
	v_pk_fma_f32 v[66:67], v[90:91], v[168:169], v[66:67]
	ds_read_b128 v[76:79], v193 offset:4640
	ds_read_b128 v[80:83], v193 offset:4656
	ds_read_b128 v[84:87], v193 offset:4672
	ds_read_b128 v[88:91], v193 offset:4688
	s_waitcnt lgkmcnt(8)
	v_pk_fma_f32 v[68:69], v[92:93], v[154:155], v[68:69]
	v_pk_fma_f32 v[68:69], v[94:95], v[156:157], v[68:69]
	v_pk_fma_f32 v[68:69], v[96:97], v[158:159], v[68:69]
	v_pk_fma_f32 v[68:69], v[98:99], v[160:161], v[68:69]
	v_pk_fma_f32 v[68:69], v[100:101], v[162:163], v[68:69]
	v_pk_fma_f32 v[68:69], v[102:103], v[164:165], v[68:69]
	v_pk_fma_f32 v[68:69], v[104:105], v[166:167], v[68:69]
	v_pk_fma_f32 v[68:69], v[106:107], v[168:169], v[68:69]
	ds_read_b128 v[92:95], v193 offset:4896
	ds_read_b128 v[96:99], v193 offset:4912
	ds_read_b128 v[100:103], v193 offset:4928
	ds_read_b128 v[104:107], v193 offset:4944
	s_waitcnt lgkmcnt(8)
	v_pk_fma_f32 v[70:71], v[108:109], v[154:155], v[70:71]
	v_pk_fma_f32 v[70:71], v[110:111], v[156:157], v[70:71]
	v_pk_fma_f32 v[70:71], v[112:113], v[158:159], v[70:71]
	v_pk_fma_f32 v[70:71], v[114:115], v[160:161], v[70:71]
	v_pk_fma_f32 v[70:71], v[116:117], v[162:163], v[70:71]
	v_pk_fma_f32 v[70:71], v[118:119], v[164:165], v[70:71]
	v_pk_fma_f32 v[70:71], v[120:121], v[166:167], v[70:71]
	v_pk_fma_f32 v[70:71], v[122:123], v[168:169], v[70:71]
	ds_read_b128 v[108:111], v193 offset:3168
	ds_read_b128 v[112:115], v193 offset:3184
	ds_read_b128 v[116:119], v193 offset:3200
	ds_read_b128 v[120:123], v193 offset:3216
	s_waitcnt lgkmcnt(8)
	v_pk_fma_f32 v[72:73], v[76:77], v[154:155], v[72:73]
	v_pk_fma_f32 v[72:73], v[78:79], v[156:157], v[72:73]
	v_pk_fma_f32 v[72:73], v[80:81], v[158:159], v[72:73]
	v_pk_fma_f32 v[72:73], v[82:83], v[160:161], v[72:73]
	v_pk_fma_f32 v[72:73], v[84:85], v[162:163], v[72:73]
	v_pk_fma_f32 v[72:73], v[86:87], v[164:165], v[72:73]
	v_pk_fma_f32 v[72:73], v[88:89], v[166:167], v[72:73]
	v_pk_fma_f32 v[72:73], v[90:91], v[168:169], v[72:73]
	ds_read_b128 v[76:79], v193 offset:3424
	ds_read_b128 v[80:83], v193 offset:3440
	ds_read_b128 v[84:87], v193 offset:3456
	ds_read_b128 v[88:91], v193 offset:3472
	s_waitcnt lgkmcnt(8)
	v_pk_fma_f32 v[74:75], v[92:93], v[154:155], v[74:75]
	v_pk_fma_f32 v[74:75], v[94:95], v[156:157], v[74:75]
	v_pk_fma_f32 v[74:75], v[96:97], v[158:159], v[74:75]
	v_pk_fma_f32 v[74:75], v[98:99], v[160:161], v[74:75]
	v_pk_fma_f32 v[74:75], v[100:101], v[162:163], v[74:75]
	v_pk_fma_f32 v[74:75], v[102:103], v[164:165], v[74:75]
	v_pk_fma_f32 v[74:75], v[104:105], v[166:167], v[74:75]
	v_pk_fma_f32 v[74:75], v[106:107], v[168:169], v[74:75]
	ds_read_b128 v[92:95], v193 offset:3680
	ds_read_b128 v[96:99], v193 offset:3696
	ds_read_b128 v[100:103], v193 offset:3712
	ds_read_b128 v[104:107], v193 offset:3728
	s_waitcnt lgkmcnt(8)
	v_pk_fma_f32 v[60:61], v[108:109], v[170:171], v[60:61]
	v_pk_fma_f32 v[60:61], v[110:111], v[172:173], v[60:61]
	v_pk_fma_f32 v[60:61], v[112:113], v[174:175], v[60:61]
	v_pk_fma_f32 v[60:61], v[114:115], v[176:177], v[60:61]
	v_pk_fma_f32 v[60:61], v[116:117], v[178:179], v[60:61]
	v_pk_fma_f32 v[60:61], v[118:119], v[180:181], v[60:61]
	v_pk_fma_f32 v[60:61], v[120:121], v[182:183], v[60:61]
	v_pk_fma_f32 v[60:61], v[122:123], v[184:185], v[60:61]
	ds_read_b128 v[108:111], v193 offset:3936
	ds_read_b128 v[112:115], v193 offset:3952
	ds_read_b128 v[116:119], v193 offset:3968
	ds_read_b128 v[120:123], v193 offset:3984
	s_waitcnt lgkmcnt(8)
	v_pk_fma_f32 v[62:63], v[76:77], v[170:171], v[62:63]
	v_pk_fma_f32 v[62:63], v[78:79], v[172:173], v[62:63]
	v_pk_fma_f32 v[62:63], v[80:81], v[174:175], v[62:63]
	v_pk_fma_f32 v[62:63], v[82:83], v[176:177], v[62:63]
	v_pk_fma_f32 v[62:63], v[84:85], v[178:179], v[62:63]
	v_pk_fma_f32 v[62:63], v[86:87], v[180:181], v[62:63]
	v_pk_fma_f32 v[62:63], v[88:89], v[182:183], v[62:63]
	v_pk_fma_f32 v[62:63], v[90:91], v[184:185], v[62:63]
	ds_read_b128 v[76:79], v193 offset:4192
	ds_read_b128 v[80:83], v193 offset:4208
	ds_read_b128 v[84:87], v193 offset:4224
	ds_read_b128 v[88:91], v193 offset:4240
	s_waitcnt lgkmcnt(8)
	v_pk_fma_f32 v[64:65], v[92:93], v[170:171], v[64:65]
	v_pk_fma_f32 v[64:65], v[94:95], v[172:173], v[64:65]
	v_pk_fma_f32 v[64:65], v[96:97], v[174:175], v[64:65]
	v_pk_fma_f32 v[64:65], v[98:99], v[176:177], v[64:65]
	v_pk_fma_f32 v[64:65], v[100:101], v[178:179], v[64:65]
	v_pk_fma_f32 v[64:65], v[102:103], v[180:181], v[64:65]
	v_pk_fma_f32 v[64:65], v[104:105], v[182:183], v[64:65]
	v_pk_fma_f32 v[64:65], v[106:107], v[184:185], v[64:65]
	ds_read_b128 v[92:95], v193 offset:4448
	ds_read_b128 v[96:99], v193 offset:4464
	ds_read_b128 v[100:103], v193 offset:4480
	ds_read_b128 v[104:107], v193 offset:4496
	s_waitcnt lgkmcnt(8)
	v_pk_fma_f32 v[66:67], v[108:109], v[170:171], v[66:67]
	v_pk_fma_f32 v[66:67], v[110:111], v[172:173], v[66:67]
	v_pk_fma_f32 v[66:67], v[112:113], v[174:175], v[66:67]
	v_pk_fma_f32 v[66:67], v[114:115], v[176:177], v[66:67]
	v_pk_fma_f32 v[66:67], v[116:117], v[178:179], v[66:67]
	v_pk_fma_f32 v[66:67], v[118:119], v[180:181], v[66:67]
	v_pk_fma_f32 v[66:67], v[120:121], v[182:183], v[66:67]
	v_pk_fma_f32 v[66:67], v[122:123], v[184:185], v[66:67]
	ds_read_b128 v[108:111], v193 offset:4704
	ds_read_b128 v[112:115], v193 offset:4720
	ds_read_b128 v[116:119], v193 offset:4736
	ds_read_b128 v[120:123], v193 offset:4752
	s_waitcnt lgkmcnt(8)
; __device__ void filters_phase(unsigned char* lds, const Params& p) {
;     ...
;       for (int i = 0; i < 64; ++i) {
;         const float wv = w3[i * 512 + col];
; #pragma unroll
;         for (int pp = 0; pp < 8; ++pp) acc[pp] += h2[pp * 64 + i] * wv;
;       }
	v_pk_fma_f32 v[68:69], v[76:77], v[170:171], v[68:69]
	v_pk_fma_f32 v[68:69], v[78:79], v[172:173], v[68:69]
	v_pk_fma_f32 v[68:69], v[80:81], v[174:175], v[68:69]
	v_pk_fma_f32 v[68:69], v[82:83], v[176:177], v[68:69]
	v_pk_fma_f32 v[68:69], v[84:85], v[178:179], v[68:69]
	v_pk_fma_f32 v[68:69], v[86:87], v[180:181], v[68:69]
	v_pk_fma_f32 v[68:69], v[88:89], v[182:183], v[68:69]
	v_pk_fma_f32 v[68:69], v[90:91], v[184:185], v[68:69]
	ds_read_b128 v[76:79], v193 offset:4960
	ds_read_b128 v[80:83], v193 offset:4976
	ds_read_b128 v[84:87], v193 offset:4992
	ds_read_b128 v[88:91], v193 offset:5008
	s_waitcnt lgkmcnt(8)
	v_pk_fma_f32 v[70:71], v[92:93], v[170:171], v[70:71]
	v_pk_fma_f32 v[70:71], v[94:95], v[172:173], v[70:71]
	v_pk_fma_f32 v[70:71], v[96:97], v[174:175], v[70:71]
	v_pk_fma_f32 v[70:71], v[98:99], v[176:177], v[70:71]
	v_pk_fma_f32 v[70:71], v[100:101], v[178:179], v[70:71]
	v_pk_fma_f32 v[70:71], v[102:103], v[180:181], v[70:71]
	v_pk_fma_f32 v[70:71], v[104:105], v[182:183], v[70:71]
	v_pk_fma_f32 v[70:71], v[106:107], v[184:185], v[70:71]
	ds_read_b128 v[92:95], v193 offset:3232
	ds_read_b128 v[96:99], v193 offset:3248
	ds_read_b128 v[100:103], v193 offset:3264
	ds_read_b128 v[104:107], v193 offset:3280
	s_waitcnt lgkmcnt(8)
	v_pk_fma_f32 v[72:73], v[108:109], v[170:171], v[72:73]
	v_pk_fma_f32 v[72:73], v[110:111], v[172:173], v[72:73]
	v_pk_fma_f32 v[72:73], v[112:113], v[174:175], v[72:73]
	v_pk_fma_f32 v[72:73], v[114:115], v[176:177], v[72:73]
	v_pk_fma_f32 v[72:73], v[116:117], v[178:179], v[72:73]
	v_pk_fma_f32 v[72:73], v[118:119], v[180:181], v[72:73]
	v_pk_fma_f32 v[72:73], v[120:121], v[182:183], v[72:73]
	v_pk_fma_f32 v[72:73], v[122:123], v[184:185], v[72:73]
	ds_read_b128 v[108:111], v193 offset:3488
	ds_read_b128 v[112:115], v193 offset:3504
	ds_read_b128 v[116:119], v193 offset:3520
	ds_read_b128 v[120:123], v193 offset:3536
	s_waitcnt lgkmcnt(8)
	v_pk_fma_f32 v[74:75], v[76:77], v[170:171], v[74:75]
	v_pk_fma_f32 v[74:75], v[78:79], v[172:173], v[74:75]
	v_pk_fma_f32 v[74:75], v[80:81], v[174:175], v[74:75]
	v_pk_fma_f32 v[74:75], v[82:83], v[176:177], v[74:75]
	v_pk_fma_f32 v[74:75], v[84:85], v[178:179], v[74:75]
	v_pk_fma_f32 v[74:75], v[86:87], v[180:181], v[74:75]
	v_pk_fma_f32 v[74:75], v[88:89], v[182:183], v[74:75]
	v_pk_fma_f32 v[74:75], v[90:91], v[184:185], v[74:75]
	ds_read_b128 v[76:79], v193 offset:3744
	ds_read_b128 v[80:83], v193 offset:3760
	ds_read_b128 v[84:87], v193 offset:3776
	ds_read_b128 v[88:91], v193 offset:3792
	s_waitcnt lgkmcnt(8)
	v_pk_fma_f32 v[60:61], v[92:93], v[200:201], v[60:61]
	v_pk_fma_f32 v[60:61], v[94:95], v[202:203], v[60:61]
	v_pk_fma_f32 v[60:61], v[96:97], v[204:205], v[60:61]
	v_pk_fma_f32 v[60:61], v[98:99], v[206:207], v[60:61]
	v_pk_fma_f32 v[60:61], v[100:101], v[208:209], v[60:61]
	v_pk_fma_f32 v[60:61], v[102:103], v[210:211], v[60:61]
	v_pk_fma_f32 v[60:61], v[104:105], v[212:213], v[60:61]
	v_pk_fma_f32 v[60:61], v[106:107], v[214:215], v[60:61]
	ds_read_b128 v[92:95], v193 offset:4000
	ds_read_b128 v[96:99], v193 offset:4016
	ds_read_b128 v[100:103], v193 offset:4032
	ds_read_b128 v[104:107], v193 offset:4048
	s_waitcnt lgkmcnt(8)
	v_pk_fma_f32 v[62:63], v[108:109], v[200:201], v[62:63]
	v_pk_fma_f32 v[62:63], v[110:111], v[202:203], v[62:63]
	v_pk_fma_f32 v[62:63], v[112:113], v[204:205], v[62:63]
	v_pk_fma_f32 v[62:63], v[114:115], v[206:207], v[62:63]
	v_pk_fma_f32 v[62:63], v[116:117], v[208:209], v[62:63]
	v_pk_fma_f32 v[62:63], v[118:119], v[210:211], v[62:63]
	v_pk_fma_f32 v[62:63], v[120:121], v[212:213], v[62:63]
	v_pk_fma_f32 v[62:63], v[122:123], v[214:215], v[62:63]
	ds_read_b128 v[108:111], v193 offset:4256
	ds_read_b128 v[112:115], v193 offset:4272
	ds_read_b128 v[116:119], v193 offset:4288
	ds_read_b128 v[120:123], v193 offset:4304
	s_waitcnt lgkmcnt(8)
	v_pk_fma_f32 v[64:65], v[76:77], v[200:201], v[64:65]
	v_pk_fma_f32 v[64:65], v[78:79], v[202:203], v[64:65]
	v_pk_fma_f32 v[64:65], v[80:81], v[204:205], v[64:65]
	v_pk_fma_f32 v[64:65], v[82:83], v[206:207], v[64:65]
	v_pk_fma_f32 v[64:65], v[84:85], v[208:209], v[64:65]
	v_pk_fma_f32 v[64:65], v[86:87], v[210:211], v[64:65]
	v_pk_fma_f32 v[64:65], v[88:89], v[212:213], v[64:65]
	v_pk_fma_f32 v[64:65], v[90:91], v[214:215], v[64:65]
	ds_read_b128 v[76:79], v193 offset:4512
	ds_read_b128 v[80:83], v193 offset:4528
	ds_read_b128 v[84:87], v193 offset:4544
	ds_read_b128 v[88:91], v193 offset:4560
	s_waitcnt lgkmcnt(8)
	v_pk_fma_f32 v[66:67], v[92:93], v[200:201], v[66:67]
	v_pk_fma_f32 v[66:67], v[94:95], v[202:203], v[66:67]
	v_pk_fma_f32 v[66:67], v[96:97], v[204:205], v[66:67]
	v_pk_fma_f32 v[66:67], v[98:99], v[206:207], v[66:67]
	v_pk_fma_f32 v[66:67], v[100:101], v[208:209], v[66:67]
	v_pk_fma_f32 v[66:67], v[102:103], v[210:211], v[66:67]
	v_pk_fma_f32 v[66:67], v[104:105], v[212:213], v[66:67]
	v_pk_fma_f32 v[66:67], v[106:107], v[214:215], v[66:67]
	ds_read_b128 v[92:95], v193 offset:4768
	ds_read_b128 v[96:99], v193 offset:4784
	ds_read_b128 v[100:103], v193 offset:4800
	ds_read_b128 v[104:107], v193 offset:4816
	s_waitcnt lgkmcnt(8)
	v_pk_fma_f32 v[68:69], v[108:109], v[200:201], v[68:69]
	v_pk_fma_f32 v[68:69], v[110:111], v[202:203], v[68:69]
	v_pk_fma_f32 v[68:69], v[112:113], v[204:205], v[68:69]
	v_pk_fma_f32 v[68:69], v[114:115], v[206:207], v[68:69]
	v_pk_fma_f32 v[68:69], v[116:117], v[208:209], v[68:69]
	v_pk_fma_f32 v[68:69], v[118:119], v[210:211], v[68:69]
	v_pk_fma_f32 v[68:69], v[120:121], v[212:213], v[68:69]
	v_pk_fma_f32 v[68:69], v[122:123], v[214:215], v[68:69]
	ds_read_b128 v[108:111], v193 offset:5024
	ds_read_b128 v[112:115], v193 offset:5040
	ds_read_b128 v[116:119], v193 offset:5056
	ds_read_b128 v[120:123], v193 offset:5072
	s_waitcnt lgkmcnt(8)
; __device__ void filters_phase(unsigned char* lds, const Params& p) {
;     ...
;       for (int i = 0; i < 64; ++i) {
;         const float wv = w3[i * 512 + col];
; #pragma unroll
;         for (int pp = 0; pp < 8; ++pp) acc[pp] += h2[pp * 64 + i] * wv;
;       }
	v_pk_fma_f32 v[70:71], v[76:77], v[200:201], v[70:71]
	v_pk_fma_f32 v[70:71], v[78:79], v[202:203], v[70:71]
	v_pk_fma_f32 v[70:71], v[80:81], v[204:205], v[70:71]
	v_pk_fma_f32 v[70:71], v[82:83], v[206:207], v[70:71]
	v_pk_fma_f32 v[70:71], v[84:85], v[208:209], v[70:71]
	v_pk_fma_f32 v[70:71], v[86:87], v[210:211], v[70:71]
	v_pk_fma_f32 v[70:71], v[88:89], v[212:213], v[70:71]
	v_pk_fma_f32 v[70:71], v[90:91], v[214:215], v[70:71]
	ds_read_b128 v[76:79], v193 offset:3296
	ds_read_b128 v[80:83], v193 offset:3312
	ds_read_b128 v[84:87], v193 offset:3328
	ds_read_b128 v[88:91], v193 offset:3344
	s_waitcnt lgkmcnt(8)
	v_pk_fma_f32 v[72:73], v[92:93], v[200:201], v[72:73]
	v_pk_fma_f32 v[72:73], v[94:95], v[202:203], v[72:73]
	v_pk_fma_f32 v[72:73], v[96:97], v[204:205], v[72:73]
	v_pk_fma_f32 v[72:73], v[98:99], v[206:207], v[72:73]
	v_pk_fma_f32 v[72:73], v[100:101], v[208:209], v[72:73]
	v_pk_fma_f32 v[72:73], v[102:103], v[210:211], v[72:73]
	v_pk_fma_f32 v[72:73], v[104:105], v[212:213], v[72:73]
	v_pk_fma_f32 v[72:73], v[106:107], v[214:215], v[72:73]
	ds_read_b128 v[92:95], v193 offset:3552
	ds_read_b128 v[96:99], v193 offset:3568
	ds_read_b128 v[100:103], v193 offset:3584
	ds_read_b128 v[104:107], v193 offset:3600
	s_waitcnt lgkmcnt(8)
	v_pk_fma_f32 v[74:75], v[108:109], v[200:201], v[74:75]
	v_pk_fma_f32 v[74:75], v[110:111], v[202:203], v[74:75]
	v_pk_fma_f32 v[74:75], v[112:113], v[204:205], v[74:75]
	v_pk_fma_f32 v[74:75], v[114:115], v[206:207], v[74:75]
	v_pk_fma_f32 v[74:75], v[116:117], v[208:209], v[74:75]
	v_pk_fma_f32 v[74:75], v[118:119], v[210:211], v[74:75]
	v_pk_fma_f32 v[74:75], v[120:121], v[212:213], v[74:75]
	v_pk_fma_f32 v[74:75], v[122:123], v[214:215], v[74:75]
	ds_read_b128 v[108:111], v193 offset:3808
	ds_read_b128 v[112:115], v193 offset:3824
	ds_read_b128 v[116:119], v193 offset:3840
	ds_read_b128 v[120:123], v193 offset:3856
	s_waitcnt lgkmcnt(8)
	v_pk_fma_f32 v[60:61], v[76:77], v[216:217], v[60:61]
	v_pk_fma_f32 v[60:61], v[78:79], v[218:219], v[60:61]
	v_pk_fma_f32 v[60:61], v[80:81], v[230:231], v[60:61]
	v_pk_fma_f32 v[60:61], v[82:83], v[232:233], v[60:61]
	v_pk_fma_f32 v[60:61], v[84:85], v[234:235], v[60:61]
	v_pk_fma_f32 v[60:61], v[86:87], v[236:237], v[60:61]
	v_pk_fma_f32 v[60:61], v[88:89], v[240:241], v[60:61]
	v_pk_fma_f32 v[60:61], v[90:91], v[242:243], v[60:61]
	ds_read_b128 v[76:79], v193 offset:4064
	ds_read_b128 v[80:83], v193 offset:4080
	ds_read_b128 v[84:87], v193 offset:4096
	ds_read_b128 v[88:91], v193 offset:4112
	s_waitcnt lgkmcnt(8)
	v_pk_fma_f32 v[62:63], v[92:93], v[216:217], v[62:63]
	v_pk_fma_f32 v[62:63], v[94:95], v[218:219], v[62:63]
	v_pk_fma_f32 v[62:63], v[96:97], v[230:231], v[62:63]
	v_pk_fma_f32 v[62:63], v[98:99], v[232:233], v[62:63]
	v_pk_fma_f32 v[62:63], v[100:101], v[234:235], v[62:63]
	v_pk_fma_f32 v[62:63], v[102:103], v[236:237], v[62:63]
	v_pk_fma_f32 v[62:63], v[104:105], v[240:241], v[62:63]
	v_pk_fma_f32 v[62:63], v[106:107], v[242:243], v[62:63]
	ds_read_b128 v[92:95], v193 offset:4320
	ds_read_b128 v[96:99], v193 offset:4336
	ds_read_b128 v[100:103], v193 offset:4352
	ds_read_b128 v[104:107], v193 offset:4368
	s_waitcnt lgkmcnt(8)
	v_pk_fma_f32 v[64:65], v[108:109], v[216:217], v[64:65]
	v_pk_fma_f32 v[64:65], v[110:111], v[218:219], v[64:65]
	v_pk_fma_f32 v[64:65], v[112:113], v[230:231], v[64:65]
	v_pk_fma_f32 v[64:65], v[114:115], v[232:233], v[64:65]
	v_pk_fma_f32 v[64:65], v[116:117], v[234:235], v[64:65]
	v_pk_fma_f32 v[64:65], v[118:119], v[236:237], v[64:65]
	v_pk_fma_f32 v[64:65], v[120:121], v[240:241], v[64:65]
	v_pk_fma_f32 v[64:65], v[122:123], v[242:243], v[64:65]
	ds_read_b128 v[108:111], v193 offset:4576
	ds_read_b128 v[112:115], v193 offset:4592
	ds_read_b128 v[116:119], v193 offset:4608
	ds_read_b128 v[120:123], v193 offset:4624
	s_waitcnt lgkmcnt(8)
	v_pk_fma_f32 v[66:67], v[76:77], v[216:217], v[66:67]
	v_pk_fma_f32 v[66:67], v[78:79], v[218:219], v[66:67]
	v_pk_fma_f32 v[66:67], v[80:81], v[230:231], v[66:67]
	v_pk_fma_f32 v[66:67], v[82:83], v[232:233], v[66:67]
	v_pk_fma_f32 v[66:67], v[84:85], v[234:235], v[66:67]
	v_pk_fma_f32 v[66:67], v[86:87], v[236:237], v[66:67]
	v_pk_fma_f32 v[66:67], v[88:89], v[240:241], v[66:67]
	v_pk_fma_f32 v[66:67], v[90:91], v[242:243], v[66:67]
	ds_read_b128 v[76:79], v193 offset:4832
	ds_read_b128 v[80:83], v193 offset:4848
	ds_read_b128 v[84:87], v193 offset:4864
	ds_read_b128 v[88:91], v193 offset:4880
	s_waitcnt lgkmcnt(8)
	v_pk_fma_f32 v[68:69], v[92:93], v[216:217], v[68:69]
	v_pk_fma_f32 v[68:69], v[94:95], v[218:219], v[68:69]
	v_pk_fma_f32 v[68:69], v[96:97], v[230:231], v[68:69]
	v_pk_fma_f32 v[68:69], v[98:99], v[232:233], v[68:69]
	v_pk_fma_f32 v[68:69], v[100:101], v[234:235], v[68:69]
	v_pk_fma_f32 v[68:69], v[102:103], v[236:237], v[68:69]
	v_pk_fma_f32 v[68:69], v[104:105], v[240:241], v[68:69]
	v_pk_fma_f32 v[68:69], v[106:107], v[242:243], v[68:69]
	ds_read_b128 v[92:95], v193 offset:5088
	ds_read_b128 v[96:99], v193 offset:5104
	ds_read_b128 v[100:103], v193 offset:5120
	ds_read_b128 v[104:107], v193 offset:5136
	s_waitcnt lgkmcnt(8)
	v_pk_fma_f32 v[70:71], v[108:109], v[216:217], v[70:71]
	v_pk_fma_f32 v[70:71], v[110:111], v[218:219], v[70:71]
	v_pk_fma_f32 v[70:71], v[112:113], v[230:231], v[70:71]
	v_pk_fma_f32 v[70:71], v[114:115], v[232:233], v[70:71]
	v_pk_fma_f32 v[70:71], v[116:117], v[234:235], v[70:71]
	v_pk_fma_f32 v[70:71], v[118:119], v[236:237], v[70:71]
	v_pk_fma_f32 v[70:71], v[120:121], v[240:241], v[70:71]
	v_pk_fma_f32 v[70:71], v[122:123], v[242:243], v[70:71]
	s_waitcnt lgkmcnt(4)
; __device__ void filters_phase(unsigned char* lds, const Params& p) {
;     ...
;       for (int i = 0; i < 64; ++i) {
;         const float wv = w3[i * 512 + col];
; #pragma unroll
;         for (int pp = 0; pp < 8; ++pp) acc[pp] += h2[pp * 64 + i] * wv;
;       }
;       const float mind = -3.0701134573253944f, maxd = -15.350567286626973f;
;       const float delta = fabsf(mind + (float)c * ((maxd - mind) / 255.0f));
;       float* dst = filt + ((size_t)(l * 256 + c) * 2 + dir) * LTOT + posidx0;
; #pragma unroll
;       for (int pp = 0; pp < 8; ++pp) {
;         const float t = (float)(pos0 + pp) / (float)(L - 1);
;         dst[pp] = acc[pp] * expf(-t * delta);
	v_pk_fma_f32 v[72:73], v[76:77], v[216:217], v[72:73]
	v_pk_fma_f32 v[72:73], v[78:79], v[218:219], v[72:73]
	v_pk_fma_f32 v[72:73], v[80:81], v[230:231], v[72:73]
	v_pk_fma_f32 v[72:73], v[82:83], v[232:233], v[72:73]
	v_pk_fma_f32 v[72:73], v[84:85], v[234:235], v[72:73]
	v_pk_fma_f32 v[72:73], v[86:87], v[236:237], v[72:73]
	v_pk_fma_f32 v[72:73], v[88:89], v[240:241], v[72:73]
	v_pk_fma_f32 v[72:73], v[90:91], v[242:243], v[72:73]
	s_waitcnt lgkmcnt(0)
	v_pk_fma_f32 v[74:75], v[92:93], v[216:217], v[74:75]
	v_pk_fma_f32 v[74:75], v[94:95], v[218:219], v[74:75]
	v_pk_fma_f32 v[74:75], v[96:97], v[230:231], v[74:75]
	v_pk_fma_f32 v[74:75], v[98:99], v[232:233], v[74:75]
	v_pk_fma_f32 v[74:75], v[100:101], v[234:235], v[74:75]
	v_pk_fma_f32 v[74:75], v[102:103], v[236:237], v[74:75]
	v_pk_fma_f32 v[74:75], v[104:105], v[240:241], v[74:75]
	v_pk_fma_f32 v[74:75], v[106:107], v[242:243], v[74:75]
	v_add_f32_e32 v54, v60, v61
	v_add_f32_e32 v55, v62, v63
	v_add_f32_e32 v52, v64, v65
	v_add_f32_e32 v53, v66, v67
	v_add_f32_e32 v50, v68, v69
	v_add_f32_e32 v51, v70, v71
	v_add_f32_e32 v48, v72, v73
	v_add_f32_e32 v49, v74, v75
	s_add_i32 s15, s15, -1
	v_cvt_f32_u32_e32 v19, s15
	v_cvt_f32_i32_e32 v21, s27
	v_readlane_b32 s6, v251, 18
	v_readlane_b32 s7, v251, 19
	v_lshl_or_b32 v56, s28, 8, v11
	v_ashrrev_i32_e32 v57, 31, v56
	v_mov_b64_e32 v[58:59], s[6:7]
	v_div_scale_f32 v23, s[6:7], v19, v19, -v21
	v_rcp_f32_e32 v25, v23
	v_lshl_add_u64 v[56:57], v[56:57], 1, v[2:3]
	s_movk_i32 s8, 0x2400
	v_mad_u64_u32 v[58:59], s[6:7], v56, s8, v[58:59]
	v_fma_f32 v27, -v23, v25, 1.0
	v_fmac_f32_e32 v25, v27, v25
	v_div_scale_f32 v27, vcc, -v21, v19, -v21
	v_mul_f32_e32 v29, v27, v25
	v_fma_f32 v31, -v23, v29, v27
	v_fmac_f32_e32 v29, v31, v25
	v_fma_f32 v23, -v23, v29, v27
	v_div_fmas_f32 v23, v23, v25, v29
	v_div_fixup_f32 v21, v23, v19, -v21
	v_mul_f32_e64 v21, |v13|, v21
	v_mad_i32_i24 v59, v57, s8, v59
	v_mul_f32_e32 v23, 0x3fb8aa3b, v21
	s_mov_b32 s8, 0x3fb8aa3b
	v_fma_f32 v25, v21, s8, -v23
	v_rndne_f32_e32 v27, v23
	v_fmac_f32_e32 v25, 0x32a5705f, v21
	v_sub_f32_e32 v23, v23, v27
	v_add_f32_e32 v23, v23, v25
	s_or_b32 s6, s27, 1
	v_exp_f32_e32 v23, v23
	v_cvt_i32_f32_e32 v25, v27
	v_cvt_f32_i32_e32 v27, s6
	s_mov_b32 s9, 0xc2ce8ed0
	v_cmp_ngt_f32_e32 vcc, s9, v21
	v_ldexp_f32 v23, v23, v25
	v_div_scale_f32 v25, s[6:7], v19, v19, -v27
	v_rcp_f32_e32 v29, v25
	s_mov_b32 s10, 0x42b17218
	s_ashr_i32 s15, s14, 31
	v_cndmask_b32_e32 v23, 0, v23, vcc
	v_cmp_nlt_f32_e32 vcc, s10, v21
	v_fma_f32 v21, -v25, v29, 1.0
	v_lshl_add_u64 v[56:57], s[14:15], 2, v[58:59]
	v_cndmask_b32_e32 v58, v225, v23, vcc
	v_fmac_f32_e32 v29, v21, v29
	v_div_scale_f32 v21, vcc, -v27, v19, -v27
	v_mul_f32_e32 v23, v21, v29
	v_fma_f32 v31, -v25, v23, v21
	v_fmac_f32_e32 v23, v31, v29
	v_fma_f32 v21, -v25, v23, v21
	v_div_fmas_f32 v21, v21, v29, v23
	v_div_fixup_f32 v21, v21, v19, -v27
	v_mul_f32_e64 v21, |v13|, v21
	v_mul_f32_e32 v23, 0x3fb8aa3b, v21
	v_fma_f32 v25, v21, s8, -v23
	v_rndne_f32_e32 v27, v23
	v_fmac_f32_e32 v25, 0x32a5705f, v21
	v_sub_f32_e32 v23, v23, v27
	s_or_b32 s6, s27, 2
	v_add_f32_e32 v23, v23, v25
	v_cvt_f32_i32_e32 v25, s6
	v_exp_f32_e32 v23, v23
	v_cvt_i32_f32_e32 v27, v27
	v_cmp_ngt_f32_e32 vcc, s9, v21
	v_div_scale_f32 v29, s[6:7], v19, v19, -v25
	v_rcp_f32_e32 v31, v29
	v_ldexp_f32 v23, v23, v27
	v_cndmask_b32_e32 v23, 0, v23, vcc
	s_or_b32 s6, s27, 3
	v_fma_f32 v27, -v29, v31, 1.0
	v_fmac_f32_e32 v31, v27, v31
	v_div_scale_f32 v27, vcc, -v25, v19, -v25
	v_mul_f32_e32 v33, v27, v31
	v_fma_f32 v35, -v29, v33, v27
	v_fmac_f32_e32 v33, v35, v31
	v_fma_f32 v27, -v29, v33, v27
	v_div_fmas_f32 v27, v27, v31, v33
	v_div_fixup_f32 v25, v27, v19, -v25
	v_mul_f32_e64 v25, |v13|, v25
	v_mul_f32_e32 v27, 0x3fb8aa3b, v25
	v_fma_f32 v29, v25, s8, -v27
	v_rndne_f32_e32 v31, v27
	v_fmac_f32_e32 v29, 0x32a5705f, v25
	v_sub_f32_e32 v27, v27, v31
	v_add_f32_e32 v27, v27, v29
	v_cvt_f32_i32_e32 v29, s6
	v_exp_f32_e32 v27, v27
	v_cvt_i32_f32_e32 v31, v31
	v_cmp_nlt_f32_e32 vcc, s10, v21
	v_div_scale_f32 v33, s[6:7], v19, v19, -v29
	v_rcp_f32_e32 v35, v33
	v_cndmask_b32_e32 v59, v225, v23, vcc
	v_ldexp_f32 v21, v27, v31
	s_or_b32 s6, s27, 4
	v_fma_f32 v23, -v33, v35, 1.0
	v_fmac_f32_e32 v35, v23, v35
	v_div_scale_f32 v23, vcc, -v29, v19, -v29
	v_mul_f32_e32 v27, v23, v35
	v_fma_f32 v31, -v33, v27, v23
	v_fmac_f32_e32 v27, v31, v35
	v_fma_f32 v23, -v33, v27, v23
	v_div_fmas_f32 v23, v23, v35, v27
; __device__ void filters_phase(unsigned char* lds, const Params& p) {
;     ...
;       const float mind = -3.0701134573253944f, maxd = -15.350567286626973f;
;       const float delta = fabsf(mind + (float)c * ((maxd - mind) / 255.0f));
;       float* dst = filt + ((size_t)(l * 256 + c) * 2 + dir) * LTOT + posidx0;
; #pragma unroll
;       for (int pp = 0; pp < 8; ++pp) {
;         const float t = (float)(pos0 + pp) / (float)(L - 1);
;         dst[pp] = acc[pp] * expf(-t * delta);
;       }
;     }
;     __syncthreads();
	v_div_fixup_f32 v23, v23, v19, -v29
	v_mul_f32_e64 v23, |v13|, v23
	v_mul_f32_e32 v27, 0x3fb8aa3b, v23
	v_fma_f32 v29, v23, s8, -v27
	v_rndne_f32_e32 v31, v27
	v_fmac_f32_e32 v29, 0x32a5705f, v23
	v_sub_f32_e32 v27, v27, v31
	v_add_f32_e32 v27, v27, v29
	v_cmp_ngt_f32_e32 vcc, s9, v25
	v_exp_f32_e32 v27, v27
	v_cvt_i32_f32_e32 v29, v31
	v_cndmask_b32_e32 v21, 0, v21, vcc
	v_cmp_nlt_f32_e32 vcc, s10, v25
	v_cvt_f32_i32_e32 v25, s6
	v_pk_mul_f32 v[58:59], v[58:59], v[54:55]
	v_cndmask_b32_e32 v54, v225, v21, vcc
	v_ldexp_f32 v21, v27, v29
	v_div_scale_f32 v27, s[6:7], v19, v19, -v25
	v_rcp_f32_e32 v29, v27
	v_cmp_ngt_f32_e32 vcc, s9, v23
	s_or_b32 s6, s27, 5
	s_add_i32 s26, s26, s90
	v_cndmask_b32_e32 v21, 0, v21, vcc
	v_cmp_nlt_f32_e32 vcc, s10, v23
	s_nop 1
	v_cndmask_b32_e32 v55, v225, v21, vcc
	v_fma_f32 v21, -v27, v29, 1.0
	v_fmac_f32_e32 v29, v21, v29
	v_div_scale_f32 v21, vcc, -v25, v19, -v25
	v_mul_f32_e32 v23, v21, v29
	v_fma_f32 v31, -v27, v23, v21
	v_fmac_f32_e32 v23, v31, v29
	v_fma_f32 v21, -v27, v23, v21
	v_div_fmas_f32 v21, v21, v29, v23
	v_div_fixup_f32 v21, v21, v19, -v25
	v_mul_f32_e64 v21, |v13|, v21
	v_mul_f32_e32 v23, 0x3fb8aa3b, v21
	v_fma_f32 v25, v21, s8, -v23
	v_rndne_f32_e32 v27, v23
	v_fmac_f32_e32 v25, 0x32a5705f, v21
	v_sub_f32_e32 v23, v23, v27
	v_add_f32_e32 v23, v23, v25
	v_exp_f32_e32 v23, v23
	v_cvt_i32_f32_e32 v25, v27
	v_cvt_f32_i32_e32 v27, s6
	v_cmp_ngt_f32_e32 vcc, s9, v21
	v_pk_mul_f32 v[60:61], v[54:55], v[52:53]
	v_ldexp_f32 v23, v23, v25
	v_div_scale_f32 v25, s[6:7], v19, v19, -v27
	v_rcp_f32_e32 v29, v25
	v_cndmask_b32_e32 v23, 0, v23, vcc
	v_cmp_nlt_f32_e32 vcc, s10, v21
	s_or_b32 s6, s27, 6
	v_fma_f32 v21, -v25, v29, 1.0
	v_cndmask_b32_e32 v52, v225, v23, vcc
	v_fmac_f32_e32 v29, v21, v29
	v_div_scale_f32 v21, vcc, -v27, v19, -v27
	v_mul_f32_e32 v23, v21, v29
	v_fma_f32 v31, -v25, v23, v21
	v_fmac_f32_e32 v23, v31, v29
	v_fma_f32 v21, -v25, v23, v21
	v_div_fmas_f32 v21, v21, v29, v23
	v_div_fixup_f32 v21, v21, v19, -v27
	v_mul_f32_e64 v21, |v13|, v21
	v_mul_f32_e32 v23, 0x3fb8aa3b, v21
	v_fma_f32 v25, v21, s8, -v23
	v_rndne_f32_e32 v27, v23
	v_fmac_f32_e32 v25, 0x32a5705f, v21
	v_sub_f32_e32 v23, v23, v27
	v_add_f32_e32 v23, v23, v25
	v_cvt_f32_i32_e32 v25, s6
	v_exp_f32_e32 v23, v23
	v_cvt_i32_f32_e32 v27, v27
	v_cmp_ngt_f32_e32 vcc, s9, v21
	v_div_scale_f32 v29, s[6:7], v19, v19, -v25
	v_rcp_f32_e32 v31, v29
	v_ldexp_f32 v23, v23, v27
	v_cndmask_b32_e32 v23, 0, v23, vcc
	s_or_b32 s6, s27, 7
	v_fma_f32 v27, -v29, v31, 1.0
	v_fmac_f32_e32 v31, v27, v31
	v_div_scale_f32 v27, vcc, -v25, v19, -v25
	v_mul_f32_e32 v33, v27, v31
	v_fma_f32 v35, -v29, v33, v27
	v_fmac_f32_e32 v33, v35, v31
	v_fma_f32 v27, -v29, v33, v27
	v_div_fmas_f32 v27, v27, v31, v33
	v_div_fixup_f32 v25, v27, v19, -v25
	v_mul_f32_e64 v25, |v13|, v25
	v_mul_f32_e32 v27, 0x3fb8aa3b, v25
	v_fma_f32 v29, v25, s8, -v27
	v_rndne_f32_e32 v31, v27
	v_fmac_f32_e32 v29, 0x32a5705f, v25
	v_sub_f32_e32 v27, v27, v31
	v_add_f32_e32 v27, v27, v29
	v_cvt_f32_i32_e32 v29, s6
	v_exp_f32_e32 v27, v27
	v_cvt_i32_f32_e32 v31, v31
	v_cmp_nlt_f32_e32 vcc, s10, v21
	v_div_scale_f32 v33, s[6:7], v19, v19, -v29
	v_rcp_f32_e32 v35, v33
	v_cndmask_b32_e32 v53, v225, v23, vcc
	v_ldexp_f32 v21, v27, v31
	v_pk_mul_f32 v[50:51], v[52:53], v[50:51]
	v_fma_f32 v23, -v33, v35, 1.0
	v_fmac_f32_e32 v35, v23, v35
	v_div_scale_f32 v23, vcc, -v29, v19, -v29
	v_mul_f32_e32 v27, v23, v35
	v_fma_f32 v31, -v33, v27, v23
	v_fmac_f32_e32 v27, v31, v35
	v_fma_f32 v23, -v33, v27, v23
	v_div_fmas_f32 v23, v23, v35, v27
	v_div_fixup_f32 v19, v23, v19, -v29
	v_mul_f32_e64 v19, |v13|, v19
	v_mul_f32_e32 v23, 0x3fb8aa3b, v19
	v_fma_f32 v27, v19, s8, -v23
	v_rndne_f32_e32 v29, v23
	v_fmac_f32_e32 v27, 0x32a5705f, v19
	v_sub_f32_e32 v23, v23, v29
	v_add_f32_e32 v23, v23, v27
	v_exp_f32_e32 v23, v23
	v_cvt_i32_f32_e32 v27, v29
	v_cmp_ngt_f32_e32 vcc, s9, v25
	s_cmpk_gt_i32 s26, 0x23f
	global_store_dwordx4 v[56:57], v[58:61], off
	v_cndmask_b32_e32 v21, 0, v21, vcc
	v_cmp_nlt_f32_e32 vcc, s10, v25
	s_nop 1
	v_cndmask_b32_e32 v52, v225, v21, vcc
	v_ldexp_f32 v21, v23, v27
	v_cmp_ngt_f32_e32 vcc, s9, v19
	s_nop 1
	v_cndmask_b32_e32 v21, 0, v21, vcc
	v_cmp_nlt_f32_e32 vcc, s10, v19
	s_nop 1
	v_cndmask_b32_e32 v53, v225, v21, vcc
	v_pk_mul_f32 v[52:53], v[52:53], v[48:49]
	global_store_dwordx4 v[56:57], v[50:53], off offset:16
	s_barrier
	s_cbranch_scc0 .LBB0_161
	s_branch .LBB0_190

; __device__ __forceinline__ bf16_t f2bf(float f) { return (bf16_t)(pack2(f, 0.f) & 0xffffu); }
; __device__ void hy_conv_sub(unsigned char* lds, const Params& p, int l, int c, int L, int posoff) {
;     ...
;   for (int idx = tid; idx < 8 * HY_CL; idx += 512) {
;     const int cc = idx / HY_CL, m = idx - cc * HY_CL;
;     const int n = m - cc - HY_OFF;
;     const int a = n <= 0 ? -n : n;
;     const int ac = a < L ? a : L - 1;
;     const float* base = (n <= 0) ? hf : hb;
;     const float v = base[ac];
;     cp[idx] = f2bf(a < L ? v : 0.f);
;   }
.LBB0_414:
	v_mov_b32_e32 v0, v195
	s_add_i32 s8, s6, s22
	s_mov_b32 s0, 0x8100
	s_ashr_i32 s9, s8, 31
	s_movk_i32 s4, 0x800
	s_mov_b64 s[12:13], exec
	s_mul_i32 s1, s8, 0x4800
	v_readlane_b32 s2, v251, 18
	s_mul_hi_i32 s0, s8, 0x4800
	v_readlane_b32 s3, v251, 19
	s_add_u32 s14, s2, s1
	s_addc_u32 s15, s3, s0
	v_add_u32_e32 v28, 0xfffff7e9, v0
	v_sub_u32_e32 v29, 0, v28
	v_max_i32_e32 v19, v28, v29
	v_cmp_lt_i32_e32 vcc, 0, v28
	v_min_i32_e32 v29, 0x7ff, v19
	v_lshlrev_b32_e32 v29, 2, v29
	v_cndmask_b32_e32 v30, 0, v238, vcc
	v_add_u32_e32 v1, v29, v30
	global_load_dword v10, v1, s[14:15]
	v_add_u32_e32 v28, 0xfffff9e9, v0
	v_sub_u32_e32 v29, 0, v28
	v_max_i32_e32 v20, v28, v29
	v_cmp_lt_i32_e32 vcc, 0, v28
	v_min_i32_e32 v29, 0x7ff, v20
	v_lshlrev_b32_e32 v29, 2, v29
	v_cndmask_b32_e32 v30, 0, v238, vcc
	v_add_u32_e32 v2, v29, v30
	global_load_dword v11, v2, s[14:15]
	v_add_u32_e32 v28, 0xfffffbe9, v0
	v_sub_u32_e32 v29, 0, v28
	v_max_i32_e32 v21, v28, v29
	v_cmp_lt_i32_e32 vcc, 0, v28
	v_min_i32_e32 v29, 0x7ff, v21
	v_lshlrev_b32_e32 v29, 2, v29
	v_cndmask_b32_e32 v30, 0, v238, vcc
	v_add_u32_e32 v3, v29, v30
	global_load_dword v12, v3, s[14:15]
	v_add_u32_e32 v28, 0xfffffde9, v0
	v_sub_u32_e32 v29, 0, v28
	v_max_i32_e32 v22, v28, v29
	v_cmp_lt_i32_e32 vcc, 0, v28
	v_min_i32_e32 v29, 0x7ff, v22
	v_lshlrev_b32_e32 v29, 2, v29
	v_cndmask_b32_e32 v30, 0, v238, vcc
	v_add_u32_e32 v4, v29, v30
	global_load_dword v13, v4, s[14:15]
	v_add_u32_e32 v28, 0xffffffe9, v0
	v_sub_u32_e32 v29, 0, v28
	v_max_i32_e32 v23, v28, v29
	v_cmp_lt_i32_e32 vcc, 0, v28
	v_min_i32_e32 v29, 0x7ff, v23
	v_lshlrev_b32_e32 v29, 2, v29
	v_cndmask_b32_e32 v30, 0, v238, vcc
	v_add_u32_e32 v5, v29, v30
	global_load_dword v14, v5, s[14:15]
	v_add_u32_e32 v28, 0x1e9, v0
	v_sub_u32_e32 v29, 0, v28
	v_max_i32_e32 v24, v28, v29
	v_cmp_lt_i32_e32 vcc, 0, v28
	v_min_i32_e32 v29, 0x7ff, v24
	v_lshlrev_b32_e32 v29, 2, v29
	v_cndmask_b32_e32 v30, 0, v238, vcc
	v_add_u32_e32 v6, v29, v30
	global_load_dword v15, v6, s[14:15]
	v_add_u32_e32 v28, 0x3e9, v0
	v_sub_u32_e32 v29, 0, v28
	v_max_i32_e32 v25, v28, v29
	v_cmp_lt_i32_e32 vcc, 0, v28
	v_min_i32_e32 v29, 0x7ff, v25
	v_lshlrev_b32_e32 v29, 2, v29
	v_cndmask_b32_e32 v30, 0, v238, vcc
	v_add_u32_e32 v7, v29, v30
	global_load_dword v16, v7, s[14:15]
	v_add_u32_e32 v28, 0x5e9, v0
	v_sub_u32_e32 v29, 0, v28
	v_max_i32_e32 v26, v28, v29
	v_cmp_lt_i32_e32 vcc, 0, v28
	v_min_i32_e32 v29, 0x7ff, v26
	v_lshlrev_b32_e32 v29, 2, v29
	v_cndmask_b32_e32 v30, 0, v238, vcc
	v_add_u32_e32 v8, v29, v30
	global_load_dword v17, v8, s[14:15]
	v_add_u32_e32 v28, 0x7e9, v0
	v_sub_u32_e32 v29, 0, v28
	v_max_i32_e32 v27, v28, v29
	v_cmp_lt_i32_e32 vcc, 0, v28
	v_min_i32_e32 v29, 0x7ff, v27
	v_lshlrev_b32_e32 v29, 2, v29
	v_cndmask_b32_e32 v30, 0, v238, vcc
	v_add_u32_e32 v9, v29, v30
	global_load_dword v18, v9, s[14:15]
	v_lshlrev_b32_e32 v31, 1, v0
	v_add_u32_e32 v32, -14, v31
	v_add_u32_e32 v33, 0x1ff2, v31
	s_waitcnt vmcnt(7)
	v_cmp_gt_i32_e32 vcc, 0x800, v20
	v_cvt_pk_bf16_f32 v11, v11, v11
	s_nop 0
	v_cndmask_b32_e32 v11, 0, v11, vcc
	ds_write_b16 v31, v11 offset:1010
	ds_write_b16 v31, v11 offset:9268
	ds_write_b16 v31, v11 offset:17526
	ds_write_b16 v31, v11 offset:25784
	ds_write_b16 v31, v11 offset:34042
	ds_write_b16 v31, v11 offset:42300
	ds_write_b16 v31, v11 offset:50558
	ds_write_b16 v31, v11 offset:58816
	s_waitcnt vmcnt(6)
	v_cmp_gt_i32_e32 vcc, 0x800, v21
	v_cvt_pk_bf16_f32 v12, v12, v12
	s_nop 0
	v_cndmask_b32_e32 v12, 0, v12, vcc
	ds_write_b16 v31, v12 offset:2034
	ds_write_b16 v31, v12 offset:10292
	ds_write_b16 v31, v12 offset:18550
	ds_write_b16 v31, v12 offset:26808
	ds_write_b16 v31, v12 offset:35066
	ds_write_b16 v31, v12 offset:43324
	ds_write_b16 v31, v12 offset:51582
	ds_write_b16 v31, v12 offset:59840
	s_waitcnt vmcnt(5)
	v_cmp_gt_i32_e32 vcc, 0x800, v22
	v_cvt_pk_bf16_f32 v13, v13, v13
	s_nop 0
	v_cndmask_b32_e32 v13, 0, v13, vcc
	ds_write_b16 v31, v13 offset:3058
	ds_write_b16 v31, v13 offset:11316
	ds_write_b16 v31, v13 offset:19574
	ds_write_b16 v31, v13 offset:27832
	ds_write_b16 v31, v13 offset:36090
	ds_write_b16 v31, v13 offset:44348
	ds_write_b16 v31, v13 offset:52606
	ds_write_b16 v31, v13 offset:60864
	s_waitcnt vmcnt(4)
	v_cmp_gt_i32_e32 vcc, 0x800, v23
	v_cvt_pk_bf16_f32 v14, v14, v14
	s_nop 0
	v_cndmask_b32_e32 v14, 0, v14, vcc
	ds_write_b16 v31, v14 offset:4082
	ds_write_b16 v31, v14 offset:12340
	ds_write_b16 v31, v14 offset:20598
	ds_write_b16 v31, v14 offset:28856
	ds_write_b16 v31, v14 offset:37114
	ds_write_b16 v31, v14 offset:45372
	ds_write_b16 v31, v14 offset:53630
	ds_write_b16 v31, v14 offset:61888
	s_waitcnt vmcnt(3)
	v_cmp_gt_i32_e32 vcc, 0x800, v24
	v_cvt_pk_bf16_f32 v15, v15, v15
	s_nop 0
	v_cndmask_b32_e32 v15, 0, v15, vcc
	ds_write_b16 v31, v15 offset:5106
	ds_write_b16 v31, v15 offset:13364
	ds_write_b16 v31, v15 offset:21622
	ds_write_b16 v31, v15 offset:29880
	ds_write_b16 v31, v15 offset:38138
	ds_write_b16 v31, v15 offset:46396
	ds_write_b16 v31, v15 offset:54654
	ds_write_b16 v31, v15 offset:62912
	s_waitcnt vmcnt(2)
; __device__ void hy_conv_sub(unsigned char* lds, const Params& p, int l, int c, int L, int posoff) {
;     ...
;   for (int idx = tid; idx < 8 * (L >> 3); idx += 512) {
;     const int bb = idx / (L >> 3), q = idx - bb * (L >> 3);
;     *(uint4*)(uL + bb * 2048 + q * 8) = *(const uint4*)(uT + ((size_t)c * 8 + bb) * LTOT + posoff + q * 8);
;   }
;   __syncthreads();
;   const float bias = p.in[17][l * 256 + c];
;   const int ngroups = L >> 7, ksteps = L >> 5;
;   for (int g = w; g < ngroups; g += 8) {
;     f32x4 acc[8];
; #pragma unroll
;     for (int i = 0; i < 8; ++i) acc[i] = (f32x4){0.f, 0.f, 0.f, 0.f};
;     const bf16_t* abase = cp + (lr & 7) * HY_CL + HY_OFF + 8 * lg - 8 * (lr >> 3) - 128 * g;
;     const bf16_t* bbase = uL + (lr & 7) * 2048 + lg * 8;
;     bf16x8 a[8];
; #pragma unroll
;     for (int mi = 2; mi < 8; ++mi) a[(-mi) & 7] = ldfrag(abase - 16 * mi);
	v_cmp_gt_i32_e32 vcc, 0x800, v25
	v_cvt_pk_bf16_f32 v16, v16, v16
	s_nop 0
	v_cndmask_b32_e32 v16, 0, v16, vcc
	ds_write_b16 v31, v16 offset:6130
	ds_write_b16 v31, v16 offset:14388
	ds_write_b16 v31, v16 offset:22646
	ds_write_b16 v31, v16 offset:30904
	ds_write_b16 v31, v16 offset:39162
	ds_write_b16 v31, v16 offset:47420
	ds_write_b16 v31, v16 offset:55678
	ds_write_b16 v31, v16 offset:63936
	s_waitcnt vmcnt(1)
	v_cmp_gt_i32_e32 vcc, 0x800, v26
	v_cvt_pk_bf16_f32 v17, v17, v17
	s_nop 0
	v_cndmask_b32_e32 v17, 0, v17, vcc
	ds_write_b16 v31, v17 offset:7154
	ds_write_b16 v31, v17 offset:15412
	ds_write_b16 v31, v17 offset:23670
	ds_write_b16 v31, v17 offset:31928
	ds_write_b16 v31, v17 offset:40186
	ds_write_b16 v31, v17 offset:48444
	ds_write_b16 v31, v17 offset:56702
	ds_write_b16 v31, v17 offset:64960
	s_waitcnt vmcnt(8)
	v_cmp_gt_i32_e32 vcc, 0x800, v19
	v_cvt_pk_bf16_f32 v10, v10, v10
	s_nop 0
	v_cndmask_b32_e32 v10, 0, v10, vcc
	ds_write_b16 v31, v10 offset:57792
	v_cmp_le_u32_e32 vcc, 1, v0
	s_and_b64 exec, exec, vcc
	ds_write_b16 v31, v10 offset:49534
	v_cmp_le_u32_e32 vcc, 2, v0
	s_and_b64 exec, exec, vcc
	ds_write_b16 v31, v10 offset:41276
	v_cmp_le_u32_e32 vcc, 3, v0
	s_and_b64 exec, exec, vcc
	ds_write_b16 v31, v10 offset:33018
	v_cmp_le_u32_e32 vcc, 4, v0
	s_and_b64 exec, exec, vcc
	ds_write_b16 v31, v10 offset:24760
	v_cmp_le_u32_e32 vcc, 5, v0
	s_and_b64 exec, exec, vcc
	ds_write_b16 v31, v10 offset:16502
	v_cmp_le_u32_e32 vcc, 6, v0
	s_and_b64 exec, exec, vcc
	ds_write_b16 v31, v10 offset:8244
	v_cmp_le_u32_e32 vcc, 7, v0
	s_and_b64 exec, exec, vcc
	ds_write_b16 v32, v10
	s_mov_b64 exec, s[12:13]
	s_waitcnt vmcnt(0)
	v_cmp_gt_i32_e32 vcc, 0x800, v27
	v_cvt_pk_bf16_f32 v18, v18, v18
	s_nop 0
	v_cndmask_b32_e32 v18, 0, v18, vcc
	v_cmp_ge_u32_e32 vcc, 38, v0
	s_and_b64 exec, exec, vcc
	ds_write_b16 v33, v18
	v_cmp_ge_u32_e32 vcc, 37, v0
	s_and_b64 exec, exec, vcc
	ds_write_b16 v33, v18 offset:8258
	v_cmp_ge_u32_e32 vcc, 36, v0
	s_and_b64 exec, exec, vcc
	ds_write_b16 v33, v18 offset:16516
	v_cmp_ge_u32_e32 vcc, 35, v0
	s_and_b64 exec, exec, vcc
	ds_write_b16 v33, v18 offset:24774
	v_cmp_ge_u32_e32 vcc, 34, v0
	s_and_b64 exec, exec, vcc
	ds_write_b16 v33, v18 offset:33032
	v_cmp_ge_u32_e32 vcc, 33, v0
	s_and_b64 exec, exec, vcc
	ds_write_b16 v33, v18 offset:41290
	v_cmp_ge_u32_e32 vcc, 32, v0
	s_and_b64 exec, exec, vcc
	ds_write_b16 v33, v18 offset:49548
	v_cmp_ge_u32_e32 vcc, 31, v0
	s_and_b64 exec, exec, vcc
	ds_write_b16 v33, v18 offset:57806
	s_mov_b64 exec, s[12:13]
	v_readlane_b32 s14, v251, 31
	v_readlane_b32 s15, v251, 32
	s_movk_i32 s16, 0x1200
	v_readlane_b32 s4, v253, 39
	s_mul_i32 s2, s6, 0x9000
	v_lshrrev_b32_e32 v1, 8, v0
	v_and_b32_e32 v3, 0xff, v0
	v_mul_u32_u24_e32 v1, 0x1200, v1
	v_lshl_add_u32 v1, v3, 4, v1
	s_add_u32 s2, s14, s2
	s_addc_u32 s3, s15, 0
	global_load_dwordx4 v[4:7], v1, s[2:3]
	v_add_u32_e32 v3, 0x2400, v1
	global_load_dwordx4 v[8:11], v3, s[2:3]
	v_add_u32_e32 v3, 0x4800, v1
	global_load_dwordx4 v[12:15], v3, s[2:3]
	v_add_u32_e32 v3, 0x6c00, v1
	global_load_dwordx4 v[16:19], v3, s[2:3]
	v_lshl_add_u32 v2, v0, 4, s4
	s_waitcnt vmcnt(3)
	ds_write_b128 v2, v[4:7]
	s_waitcnt vmcnt(2)
	ds_write_b128 v2, v[8:11] offset:8192
	s_waitcnt vmcnt(1)
	ds_write_b128 v2, v[12:15] offset:16384
	s_waitcnt vmcnt(0)
	ds_write_b128 v2, v[16:19] offset:24576
	v_ashrrev_i32_e32 v60, 6, v0
	v_cmp_gt_i32_e32 vcc, 16, v60
	s_waitcnt lgkmcnt(0)
	s_barrier
	s_and_saveexec_b64 s[2:3], vcc
	s_cbranch_execz .LBB0_444
	v_readlane_b32 s40, v250, 40
	s_lshl_b64 s[0:1], s[8:9], 2
	v_readlane_b32 s42, v250, 42
	v_readlane_b32 s43, v250, 43
	s_add_u32 s0, s42, s0
	s_addc_u32 s1, s43, s1
	global_load_dword v56, v193, s[0:1]
	v_and_b32_e32 v192, 15, v0
	v_bfe_u32 v1, v0, 4, 2
	v_and_b32_e32 v6, 7, v0
	v_readlane_b32 s0, v253, 39
	v_mul_u32_u24_e32 v7, 0x2040, v6
	v_lshlrev_b32_e32 v61, 4, v1
	v_and_b32_e32 v3, 8, v0
	v_lshl_add_u32 v64, v192, 12, s0
	v_readlane_b32 s0, v252, 3
	v_add3_u32 v2, 0, v7, v61
	v_lshlrev_b32_e32 v3, 1, v3
	s_ashr_i32 s7, s6, 31
	v_readlane_b32 s1, v252, 4
	v_lshlrev_b32_e32 v0, 1, v0
	v_sub_u32_e32 v62, v2, v3
	v_lshl_add_u64 v[2:3], s[6:7], 3, v[192:193]
	v_mov_b64_e32 v[4:5], s[0:1]
	s_movk_i32 s4, 0x1200
	v_and_b32_e32 v0, 16, v0
	v_lshlrev_b32_e32 v63, 2, v1
	v_mad_u64_u32 v[58:59], s[0:1], v2, s4, v[4:5]
	v_sub_u32_e32 v0, v7, v0
	v_lshlrev_b32_e32 v1, 8, v60
	v_sub_u32_e32 v0, v0, v1
	s_add_i32 s0, 0, 0x1000
	v_cmp_gt_u32_e32 vcc, 8, v192
	v_mad_i32_i24 v59, v3, s4, v59
	v_add_u32_e32 v65, s0, v0
	v_lshl_add_u32 v66, v6, 12, 0
	s_mov_b64 s[4:5], 0
	v_readlane_b32 s41, v250, 41
	v_readlane_b32 s44, v250, 44
	v_readlane_b32 s45, v250, 45
	v_readlane_b32 s46, v250, 46
	v_readlane_b32 s47, v250, 47
	v_readlane_b32 s48, v250, 48
	v_readlane_b32 s49, v250, 49
	v_readlane_b32 s50, v250, 50
	v_readlane_b32 s51, v250, 51
	v_readlane_b32 s52, v250, 52
	v_readlane_b32 s53, v250, 53
	v_readlane_b32 s54, v250, 54
	v_readlane_b32 s55, v250, 55
	s_waitcnt vmcnt(0)
	v_mov_b32_e32 v57, v56
	s_branch .LBB0_440

; __device__ __forceinline__ float bf2f(bf16_t h) { return __uint_as_float(((unsigned)h) << 16); }
; __device__ void rg_tile(unsigned char* lds, const Params& p, int l, int b, int ck, int hh, bool outmode) {
;     ...
;   const bool isctx = ck < 4;
;   const int L = isctx ? 256 : 2048;
;   const int t0 = isctx ? ck * 64 : (ck - 4) * 64;
;   const int rowbase = isctx ? (NLAT + b * 256) : (b * 2048);
;   float car_pre = 0.f, gp_pre[8];
;   {
;     const int d_ = (tid >> 6) & 1, j_ = tid & 63;
;     if (outmode) {
;       car_pre = car[((size_t)(b * 36 + ck) * 2 + d_) * 256 + hh * 64 + j_];
; #pragma unroll
;       for (int q = 0; q < 8; ++q) gp_pre[q] = bf2f(z[(size_t)(rowbase + t0 + w * 8 + q) * ZS + 2816 + 256 + hh * 64 + lane]);
;     } else {
; #pragma unroll
;       for (int q = 0; q < 8; ++q) gp_pre[q] = 0.f;
;     }
;   }
;   const int chm_ = hh * 64 + (w & 3) * 16 + lr, dm_ = w >> 2;
;   const float br = p.in[22][(size_t)l * 1024 + (dm_ * 2 + 0) * 256 + chm_];
;   const float bi = p.in[22][(size_t)l * 1024 + (dm_ * 2 + 1) * 256 + chm_];
;   const float lam_ = p.in[23][(size_t)l * 512 + dm_ * 256 + chm_];
;   {
;     const int i = tid & 63, tq = tid >> 6;
;     const int ch = hh * 64 + i;
;     const float* wc = p.in[20] + (size_t)l * 4 * 256 + ch;
;     const float w0 = wc[0], w1 = wc[256], w2 = wc[512], w3 = wc[768];
; #pragma unroll
;     for (int ii = 0; ii < 8; ++ii) {
;       const int tt = tq * 8 + ii;
;       const int tp = t0 + tt;
;       const int tm1 = tp - 1 >= 0 ? tp - 1 : 0, tp1 = tp + 1 < L ? tp + 1 : L - 1, tp2 = tp + 2 < L ? tp + 2 : L - 1;
;       const float z0 = bf2f(z[(size_t)(rowbase + tm1) * ZS + 2816 + ch]);
;       const float z1 = bf2f(z[(size_t)(rowbase + tp) * ZS + 2816 + ch]);
;       const float z2 = bf2f(z[(size_t)(rowbase + tp1) * ZS + 2816 + ch]);
;       const float z3 = bf2f(z[(size_t)(rowbase + tp2) * ZS + 2816 + ch]);
.LBB0_708:
	s_and_b64 vcc, exec, s[0:1]
	s_cbranch_vccz .LBB0_812
	s_sub_i32 s0, s13, s30
	s_ashr_i32 s2, s0, 2
	s_abs_i32 s2, s2
	v_readlane_b32 s3, v254, 14
	s_mul_hi_u32 s3, s2, s3
	v_readlane_b32 s4, v254, 11
	s_mul_i32 s3, s3, s4
	s_sub_i32 s2, s2, s3
	s_and_b32 s1, s13, 3
	s_sub_i32 s3, s2, s4
	s_cmp_ge_u32 s2, s4
	s_cselect_b32 s2, s3, s2
	s_sub_i32 s3, s2, s4
	s_cmp_ge_u32 s2, s4
	s_cselect_b32 s2, s3, s2
	s_ashr_i32 s3, s0, 31
	s_xor_b32 s2, s2, s3
	s_sub_i32 s2, s2, s3
	v_readlane_b32 s4, v254, 22
	s_add_i32 s4, s2, s4
	s_abs_i32 s0, s0
	v_readlane_b32 s2, v254, 16
	s_mul_hi_u32 s2, s0, s2
	v_readlane_b32 s7, v254, 15
	s_mul_i32 s5, s2, s7
	s_sub_i32 s0, s0, s5
	s_add_i32 s5, s2, 1
	s_sub_i32 s6, s0, s7
	s_cmp_ge_u32 s0, s7
	s_cselect_b32 s2, s5, s2
	s_cselect_b32 s0, s6, s0
	s_add_i32 s5, s2, 1
	s_cmp_ge_u32 s0, s7
	s_cselect_b32 s0, s5, s2
	s_xor_b32 s0, s0, s3
	s_sub_i32 s5, s0, s3
	s_lshl_b32 s2, s4, 6
	s_lshl_b32 s0, s5, 8
	s_add_i32 s3, s2, 0xffffff00
	s_add_i32 s6, s0, 0x4000
	s_lshl_b32 s7, s5, 11
	s_cmp_lt_i32 s4, 4
	s_movk_i32 s0, 0x800
	s_mul_i32 s5, s5, 36
	s_cselect_b32 s0, 0x100, s0
	s_cselect_b32 s3, s2, s3
	s_cselect_b32 s2, s6, s7
	s_add_i32 s4, s5, s4
	v_mov_b32_e32 v52, v195
	v_readfirstlane_b32 s44, v195
	s_mov_b32 s47, s0
	s_mov_b32 s48, s2
	s_mov_b32 s49, s3
	s_lshl_b32 s50, s1, 7
	s_lshr_b32 s44, s44, 6
	s_lshl_b32 s45, s44, 3
	s_add_i32 s45, s45, s49
	s_add_i32 s46, s47, -1
	s_addk_i32 s50, 0x1600
	v_and_b32_e32 v185, 63, v195
	v_lshl_add_u32 v180, v185, 1, s50
	v_readlane_b32 s52, v254, 3
	v_readlane_b32 s53, v254, 4
	s_lshl_b32 s51, s1, 8
	v_lshl_add_u32 v181, v185, 2, s51
	s_nop 4
	global_load_dword v165, v181, s[52:53]
	global_load_dword v166, v181, s[52:53] offset:1024
	global_load_dword v167, v181, s[52:53] offset:2048
	global_load_dword v168, v181, s[52:53] offset:3072
	s_add_i32 s54, s45, s48
	s_mul_i32 s54, s54, 0x1a00
	s_and_b32 s56, s13, 3
	v_bfe_u32 v208, v195, 4, 2
	v_and_b32_e32 v209, 15, v195
	v_mul_u32_u24_e32 v210, 0x1a00, v208
	v_lshl_add_u32 v210, v209, 3, v210
	s_add_i32 s57, s54, s50
	s_addk_i32 s57, 0x200
	v_add_u32_e32 v210, s57, v210
	v_readlane_b32 s58, v254, 9
	v_readlane_b32 s59, v254, 10
	global_load_dwordx2 v[204:205], v210, s[88:89]
	v_add_u32_e32 v210, 0x6800, v210
	global_load_dwordx2 v[206:207], v210, s[88:89]
	s_lshl_b32 s57, s56, 8
	s_addk_i32 s57, 0xc00
	v_lshl_add_u32 v211, v209, 4, s57
	s_nop 1
	global_load_dwordx4 v[200:203], v211, s[58:59]
	v_add_u32_e32 v181, s54, v180
	s_add_i32 s55, s45, -1
	s_max_i32 s55, s55, 0
	s_add_i32 s55, s55, s48
	s_mul_i32 s55, s55, 0x1a00
	v_add_u32_e32 v184, s55, v180
	global_load_ushort v154, v184, s[88:89]
	global_load_ushort v155, v181, s[88:89]
	v_add_u32_e32 v181, 0x1a00, v181
	global_load_ushort v156, v181, s[88:89]
	v_add_u32_e32 v181, 0x1a00, v181
	global_load_ushort v157, v181, s[88:89]
	v_add_u32_e32 v181, 0x1a00, v181
	global_load_ushort v158, v181, s[88:89]
	v_add_u32_e32 v181, 0x1a00, v181
	global_load_ushort v159, v181, s[88:89]
	v_add_u32_e32 v181, 0x1a00, v181
	global_load_ushort v160, v181, s[88:89]
	v_add_u32_e32 v181, 0x1a00, v181
	global_load_ushort v161, v181, s[88:89]
	v_add_u32_e32 v181, 0x1a00, v181
	global_load_ushort v162, v181, s[88:89]
	s_add_i32 s55, s45, 8
	s_min_i32 s55, s55, s46
	s_add_i32 s55, s55, s48
	s_mul_i32 s55, s55, 0x1a00
	v_add_u32_e32 v184, s55, v180
	global_load_ushort v163, v184, s[88:89]
	s_add_i32 s55, s45, 9
	s_min_i32 s55, s55, s46
	s_add_i32 s55, s55, s48
	s_mul_i32 s55, s55, 0x1a00
	v_add_u32_e32 v184, s55, v180
	global_load_ushort v164, v184, s[88:89]
	s_mul_i32 s55, s44, 0x820
	v_lshl_add_u32 v182, v185, 2, s55
	s_mul_i32 s55, s44, 0x480
	v_lshl_add_u32 v183, v185, 1, s55
	s_ashr_i32 s5, s4, 31
	s_lshl_b32 s7, s1, 6
	v_ashrrev_i32_e32 v47, 6, v52
	s_lshl_b64 s[4:5], s[4:5], 11
	v_readlane_b32 s8, v252, 11
	v_and_b32_e32 v48, 1, v47
	v_readlane_b32 s9, v252, 12
	s_add_u32 s4, s8, s4
	s_addc_u32 s5, s9, s5
	v_lshlrev_b32_e32 v192, 10, v48
	v_and_b32_e32 v29, 63, v52
	v_lshl_add_u64 v[0:1], s[4:5], 0, v[192:193]
	s_lshl_b32 s96, s1, 8
	v_lshl_add_u64 v[0:1], v[0:1], 0, s[96:97]
	v_lshlrev_b32_e32 v192, 2, v29
	s_add_i32 s4, s3, s2
	v_lshlrev_b32_e32 v12, 3, v47
	v_lshl_add_u64 v[2:3], v[0:1], 0, v[192:193]
	v_add_u32_e32 v28, s4, v12
	v_mov_b64_e32 v[0:1], s[88:89]
	s_lshl_b32 s96, s1, 7
	s_movk_i32 s10, 0x1000
	s_nop 0
	s_nop 0
	global_load_dword v51, v[2:3], off
	s_add_i32 s6, s2, -1
	v_or_b32_e32 v7, s7, v29
	v_lshlrev_b32_e32 v32, 1, v7
	v_mov_b32_e32 v33, v193
	v_lshlrev_b32_e32 v39, 2, v7
	s_add_i32 s5, s0, -1
	s_nop 0
	s_nop 0
	s_nop 0
	s_nop 0
	v_and_b32_e32 v6, 15, v52
	s_nop 0
	v_lshlrev_b32_e32 v2, 4, v47
	v_ashrrev_i32_e32 v56, 8, v52
	v_and_or_b32 v55, v2, 48, v6
	v_lshlrev_b32_e32 v2, 9, v56
	v_readlane_b32 s8, v254, 12
	v_lshl_or_b32 v7, v56, 1, 1
	v_or_b32_e32 v4, s7, v55
	v_ashrrev_i32_e32 v3, 31, v2
	v_readlane_b32 s9, v254, 13
	v_lshlrev_b32_e32 v16, 8, v7
	v_lshlrev_b32_e32 v4, 2, v4
	v_lshl_add_u64 v[2:3], v[2:3], 2, s[8:9]
	v_mov_b32_e32 v5, v193
	v_ashrrev_i32_e32 v17, 31, v16
	v_lshl_add_u64 v[2:3], v[2:3], 0, v[4:5]
	v_lshl_add_u64 v[16:17], v[16:17], 2, s[8:9]
	v_lshl_add_u64 v[16:17], v[16:17], 0, v[4:5]
	global_load_dword v54, v[2:3], off
	global_load_dword v53, v[16:17], off
	v_and_b32_e32 v2, 0xffffff00, v52
	v_readlane_b32 s8, v254, 1
	v_ashrrev_i32_e32 v3, 31, v2
	v_readlane_b32 s9, v254, 2
	v_or_b32_e32 v37, 1, v12
	v_add_u32_e32 v30, 0, v192
	v_lshl_add_u64 v[2:3], v[2:3], 2, s[8:9]
	v_lshl_add_u64 v[2:3], v[2:3], 0, v[4:5]
	global_load_dword v16, v[2:3], off
	s_nop 0
	s_nop 0
	v_or_b32_e32 v38, 2, v12
	s_nop 0
	v_or_b32_e32 v40, 3, v12
	s_nop 0
; __device__ __forceinline__ bf16_t f2bf(float f) { return (bf16_t)(pack2(f, 0.f) & 0xffffu); }
; __device__ __forceinline__ float bf2f(bf16_t h) { return __uint_as_float(((unsigned)h) << 16); }
; __device__ void rg_tile(unsigned char* lds, const Params& p, int l, int b, int ck, int hh, bool outmode) {
;     ...
;     const int i = tid & 63, tq = tid >> 6;
;     const int ch = hh * 64 + i;
;     const float* wc = p.in[20] + (size_t)l * 4 * 256 + ch;
;     const float w0 = wc[0], w1 = wc[256], w2 = wc[512], w3 = wc[768];
; #pragma unroll
;     for (int ii = 0; ii < 8; ++ii) {
;       const int tt = tq * 8 + ii;
;       const int tp = t0 + tt;
;       const int tm1 = tp - 1 >= 0 ? tp - 1 : 0, tp1 = tp + 1 < L ? tp + 1 : L - 1, tp2 = tp + 2 < L ? tp + 2 : L - 1;
;       const float z0 = bf2f(z[(size_t)(rowbase + tm1) * ZS + 2816 + ch]);
;       const float z1 = bf2f(z[(size_t)(rowbase + tp) * ZS + 2816 + ch]);
;       const float z2 = bf2f(z[(size_t)(rowbase + tp1) * ZS + 2816 + ch]);
;       const float z3 = bf2f(z[(size_t)(rowbase + tp2) * ZS + 2816 + ch]);
;       float xr = w1 * z1;
;       xr += (tp - 1 >= 0 ? w0 : 0.f) * z0;
;       xr += (tp + 1 < L ? w2 : 0.f) * z2;
;       xr += (tp + 2 < L ? w3 : 0.f) * z3;
;       XR[tt * 65 + i] = xr;
;       XB[tt * 72 + i] = f2bf(xr);
;     }
;     const bf16_t* rgw = (const bf16_t*)(p.ws + OFF_RGW);
; #pragma unroll
;     for (int q = 0; q < 4; ++q) {
;       const int id = tid + 512 * q;
;       const int row = id >> 3, kc = id & 7;
;       *(uint4*)(WT + row * 72 + kc * 8) = *(const uint4*)(rgw + ((size_t)((l * 4 + (row >> 6)) * 4 + hh)) * 4096 + (row & 63) * 64 + kc * 8);
;     }
;   }
;   __syncthreads();
	s_nop 0
	s_nop 0
	s_nop 0
	s_nop 0
	s_nop 0
	v_or_b32_e32 v43, 4, v12
	s_nop 0
	s_movk_i32 s12, 0x104
	s_movk_i32 s11, 0x90
	s_nop 0
	v_or_b32_e32 v44, 5, v12
	v_or_b32_e32 v45, 6, v12
	v_add_u32_e32 v68, s3, v45
	s_nop 0
	v_add_u32_e32 v69, 2, v68
	v_min_i32_e32 v26, s5, v69
	v_or_b32_e32 v46, 7, v12
	v_add_u32_e32 v13, s2, v26
	v_add_u32_e32 v70, s3, v46
	v_mad_i64_i32 v[26:27], s[8:9], v13, s92, v[0:1]
	v_max_i32_e32 v12, 1, v70
	v_add_u32_e32 v12, s6, v12
	v_mad_u64_u32 v[12:13], s[6:7], v12, s92, v[0:1]
	v_lshl_add_u64 v[12:13], v[12:13], 0, v[32:33]
	v_add_u32_e32 v58, s2, v70
	v_add_co_u32_e32 v12, vcc, s10, v12
	v_mad_i64_i32 v[58:59], s[6:7], v58, s92, v[0:1]
	v_addc_co_u32_e32 v13, vcc, 0, v13, vcc
	v_ashrrev_i32_e32 v80, 3, v52
	s_nop 0
	global_load_ushort v78, v[12:13], off offset:1536
	v_readlane_b32 s2, v254, 5
	v_lshlrev_b32_e32 v12, 4, v52
	v_ashrrev_i32_e32 v33, 7, v52
	s_or_b32 s1, s1, s2
	v_and_b32_e32 v26, 0x70, v12
	v_and_b32_e32 v12, -4, v33
	v_add_u32_e32 v12, s1, v12
	v_ashrrev_i32_e32 v13, 31, v12
	v_readlane_b32 s2, v251, 22
	v_lshlrev_b64 v[12:13], 13, v[12:13]
	v_readlane_b32 s3, v251, 23
	v_lshlrev_b32_e32 v14, 7, v80
	v_and_b32_e32 v14, 0x1f80, v14
	v_lshl_add_u64 v[12:13], s[2:3], 0, v[12:13]
	v_mov_b32_e32 v15, v193
	v_lshl_add_u64 v[12:13], v[12:13], 0, v[14:15]
	v_mov_b32_e32 v27, v193
	v_lshl_add_u64 v[12:13], v[12:13], 0, v[26:27]
	s_nop 0
	global_load_dwordx4 v[12:15], v[12:13], off
	v_add_u32_e32 v0, 0x200, v52
	v_ashrrev_i32_e32 v82, 3, v0
	v_ashrrev_i32_e32 v0, 7, v0
	v_and_b32_e32 v0, -4, v0
	v_add_u32_e32 v0, s1, v0
	v_ashrrev_i32_e32 v1, 31, v0
	v_lshlrev_b64 v[0:1], 13, v[0:1]
	v_lshlrev_b32_e32 v18, 7, v82
	v_lshl_add_u64 v[0:1], s[2:3], 0, v[0:1]
	v_and_b32_e32 v18, 0x1f80, v18
	v_mov_b32_e32 v19, v193
	v_lshl_add_u64 v[0:1], v[0:1], 0, v[18:19]
	v_add_u32_e32 v18, 0x400, v52
	v_ashrrev_i32_e32 v83, 3, v18
	v_ashrrev_i32_e32 v18, 7, v18
	v_and_b32_e32 v18, -4, v18
	v_add_u32_e32 v18, s1, v18
	v_ashrrev_i32_e32 v19, 31, v18
	v_lshlrev_b64 v[18:19], 13, v[18:19]
	v_lshlrev_b32_e32 v20, 7, v83
	v_lshl_add_u64 v[18:19], s[2:3], 0, v[18:19]
	v_and_b32_e32 v20, 0x1f80, v20
	v_mov_b32_e32 v21, v193
	v_lshl_add_u64 v[18:19], v[18:19], 0, v[20:21]
	v_lshl_add_u64 v[0:1], v[0:1], 0, v[26:27]
	v_lshl_add_u64 v[22:23], v[18:19], 0, v[26:27]
	global_load_dwordx4 v[18:21], v[0:1], off
	s_nop 0
	global_load_dwordx4 v[22:25], v[22:23], off
	v_add_u32_e32 v0, 0x600, v52
	v_ashrrev_i32_e32 v84, 3, v0
	v_ashrrev_i32_e32 v0, 7, v0
	v_and_b32_e32 v0, -4, v0
	v_add_u32_e32 v0, s1, v0
	v_ashrrev_i32_e32 v1, 31, v0
	v_lshlrev_b64 v[0:1], 13, v[0:1]
	v_lshlrev_b32_e32 v58, 7, v84
	v_lshl_add_u64 v[0:1], s[2:3], 0, v[0:1]
	v_and_b32_e32 v58, 0x1f80, v58
	v_mov_b32_e32 v59, v193
	v_lshl_add_u64 v[0:1], v[0:1], 0, v[58:59]
	v_lshl_add_u64 v[0:1], v[0:1], 0, v[26:27]
	global_load_dwordx4 v[58:61], v[0:1], off
	s_waitcnt vmcnt(0)
	v_lshlrev_b32_e32 v1, 16, v78
	s_nop 0
	s_nop 0
	v_add_u32_e32 v0, 0, v26
	v_mad_u64_u32 v[2:3], s[0:1], v80, s11, v[0:1]
	ds_write_b128 v2, v[12:15] offset:25856
	v_mad_u64_u32 v[2:3], s[0:1], v82, s11, v[0:1]
	ds_write_b128 v2, v[18:21] offset:25856
	v_mad_u64_u32 v[2:3], s[0:1], v83, s11, v[0:1]
	v_mad_u64_u32 v[0:1], s[0:1], v84, s11, v[0:1]
	ds_write_b128 v2, v[22:25] offset:25856
	ds_write_b128 v0, v[58:61] offset:25856
	v_and_b32_e32 v0, 48, v52
	v_add_u32_e32 v0, 0, v0
	v_mad_u32_u24 v17, v6, s11, v0
	s_waitcnt vmcnt(0)
	v_lshlrev_b32_e32 v154, 16, v154
	v_lshlrev_b32_e32 v155, 16, v155
	v_lshlrev_b32_e32 v156, 16, v156
	v_lshlrev_b32_e32 v157, 16, v157
	v_lshlrev_b32_e32 v158, 16, v158
	v_lshlrev_b32_e32 v159, 16, v159
	v_lshlrev_b32_e32 v160, 16, v160
	v_lshlrev_b32_e32 v161, 16, v161
	v_lshlrev_b32_e32 v162, 16, v162
	v_lshlrev_b32_e32 v163, 16, v163
	v_lshlrev_b32_e32 v164, 16, v164
	s_cmp_ge_i32 s45, 1
	s_cselect_b64 s[56:57], -1, 0
	s_add_i32 s55, s45, 8
	s_cmp_lt_i32 s55, s47
	s_cselect_b64 s[58:59], -1, 0
	v_cndmask_b32_e64 v169, 0, v165, s[56:57]
	v_cndmask_b32_e64 v170, 0, v167, s[58:59]
	v_cndmask_b32_e64 v171, 0, v168, s[58:59]
	v_mul_f32_e32 v172, v166, v155
	v_fmac_f32_e32 v172, v169, v154
	v_fmac_f32_e32 v172, v167, v156
	v_fmac_f32_e32 v172, v168, v157
	v_mul_f32_e32 v173, v166, v156
	v_fmac_f32_e32 v173, v165, v155
	v_fmac_f32_e32 v173, v167, v157
	v_fmac_f32_e32 v173, v168, v158
	v_mul_f32_e32 v174, v166, v157
	v_fmac_f32_e32 v174, v165, v156
	v_fmac_f32_e32 v174, v167, v158
	v_fmac_f32_e32 v174, v168, v159
	v_mul_f32_e32 v175, v166, v158
	v_fmac_f32_e32 v175, v165, v157
	v_fmac_f32_e32 v175, v167, v159
	v_fmac_f32_e32 v175, v168, v160
	v_mul_f32_e32 v176, v166, v159
	v_fmac_f32_e32 v176, v165, v158
	v_fmac_f32_e32 v176, v167, v160
	v_fmac_f32_e32 v176, v168, v161
	v_mul_f32_e32 v177, v166, v160
	v_fmac_f32_e32 v177, v165, v159
	v_fmac_f32_e32 v177, v167, v161
	v_fmac_f32_e32 v177, v168, v162
	v_mul_f32_e32 v178, v166, v161
	v_fmac_f32_e32 v178, v165, v160
	v_fmac_f32_e32 v178, v167, v162
	v_fmac_f32_e32 v178, v171, v163
	v_mul_f32_e32 v179, v166, v162
	v_fmac_f32_e32 v179, v165, v161
	v_fmac_f32_e32 v179, v170, v163
	v_fmac_f32_e32 v179, v171, v164
	v_cvt_pk_bf16_f32 v184, v172, v172
	ds_write_b32 v182, v172
	ds_write_b16 v183, v184 offset:16640
	v_cvt_pk_bf16_f32 v184, v173, v173
	ds_write_b32 v182, v173 offset:260
	ds_write_b16 v183, v184 offset:16784
	v_cvt_pk_bf16_f32 v184, v174, v174
	ds_write_b32 v182, v174 offset:520
	ds_write_b16 v183, v184 offset:16928
	v_cvt_pk_bf16_f32 v184, v175, v175
	ds_write_b32 v182, v175 offset:780
	ds_write_b16 v183, v184 offset:17072
	v_cvt_pk_bf16_f32 v184, v176, v176
	ds_write_b32 v182, v176 offset:1040
	ds_write_b16 v183, v184 offset:17216
	v_cvt_pk_bf16_f32 v184, v177, v177
	ds_write_b32 v182, v177 offset:1300
	ds_write_b16 v183, v184 offset:17360
	v_cvt_pk_bf16_f32 v184, v178, v178
	ds_write_b32 v182, v178 offset:1560
	ds_write_b16 v183, v184 offset:17504
	v_cvt_pk_bf16_f32 v184, v179, v179
	ds_write_b32 v182, v179 offset:1820
	ds_write_b16 v183, v184 offset:17648
	s_waitcnt lgkmcnt(0)
	s_barrier
; __device__ __forceinline__ float fexp(float x) { return __expf(x); }
; __device__ __forceinline__ float sigm(float x) { return frcp(1.f + fexp(-x)); }
; __device__ __forceinline__ float softplusf(float x) { return fmaxf(x, 0.f) + __logf(1.f + fexp(-fabsf(x))); }
; __device__ void rg_tile(unsigned char* lds, const Params& p, int l, int b, int ck, int hh, bool outmode) {
;     ...
;   {
;     const int d = w >> 2, jf = w & 3;
;     f32x4 ar[4], ai[4];
; #pragma unroll
;     for (int i = 0; i < 4; ++i) { ar[i] = (f32x4){0.f, 0.f, 0.f, 0.f}; ai[i] = (f32x4){0.f, 0.f, 0.f, 0.f}; }
; #pragma unroll
;     for (int ks = 0; ks < 2; ++ks) {
;       const bf16x8 wr = ldfrag(WT + ((d * 2 + 0) * 64 + jf * 16 + lr) * 72 + ks * 32 + lg * 8);
;       const bf16x8 wi = ldfrag(WT + ((d * 2 + 1) * 64 + jf * 16 + lr) * 72 + ks * 32 + lg * 8);
; #pragma unroll
;       for (int tf = 0; tf < 4; ++tf) {
;         const bf16x8 xf = ldfrag(XB + (tf * 16 + lr) * 72 + ks * 32 + lg * 8);
;         ar[tf] = mfma16(xf, wr, ar[tf]);
;         ai[tf] = mfma16(xf, wi, ai[tf]);
;       }
;     }
;     const int j = jf * 16 + lr;
;     const int ch = hh * 64 + j;
;     const float sp = softplusf(-lam_);
; #pragma unroll
;     for (int tf = 0; tf < 4; ++tf)
; #pragma unroll
;       for (int jj = 0; jj < 4; ++jj) {
;         const int tt = tf * 16 + lg * 4 + jj;
;         const float r = sigm(ar[tf][jj] + br);
;         const float ig = sigm(ai[tf][jj] + bi);
;         const float la = -8.0f * r * sp;
;         const float a = fexp(la);
;         const float bq = __builtin_amdgcn_sqrtf(fmaxf(1.f - a * a, 0.f)) * ig * XR[tt * 65 + j];
;         AA[(d * 64 + tt) * 64 + j] = a;
;         BQ[(d * 64 + tt) * 64 + j] = bq;
;       }
	ds_read_b128 v[18:21], v17 offset:16640
	v_lshl_or_b32 v1, v56, 7, v55
	v_mad_u64_u32 v[2:3], s[0:1], v1, s11, v[0:1]
	v_lshl_or_b32 v1, v7, 6, v55
	ds_read_b128 v[12:15], v2 offset:25856
	v_mad_u64_u32 v[0:1], s[0:1], v1, s11, v[0:1]
	ds_read_b128 v[4:7], v2 offset:25920
	ds_read_b128 v[22:25], v17 offset:16704
	ds_read_b128 v[8:11], v0 offset:25856
	ds_read_b128 v[0:3], v0 offset:25920
	s_mov_b32 s0, 0xbfb8aa3b
	v_mul_f32_e64 v26, |v16|, s0
	s_waitcnt lgkmcnt(4)
	v_mfma_f32_16x16x32_bf16 v[58:61], v[18:21], v[12:15], 0
	v_exp_f32_e32 v26, v26
	s_mov_b32 s0, 0x800000
	v_max_f32_e64 v16, -v16, -v16
	s_waitcnt lgkmcnt(1)
	v_mfma_f32_16x16x32_bf16 v[18:21], v[18:21], v[8:11], 0
	v_max_f32_e32 v16, 0, v16
	v_bfe_u32 v82, v52, 4, 2
	ds_read_b128 v[62:65], v17 offset:18944
	ds_read_b128 v[66:69], v17 offset:19008
	s_waitcnt lgkmcnt(2)
	v_mfma_f32_16x16x32_bf16 v[74:77], v[22:25], v[0:3], v[18:21]
	v_lshlrev_b32_e32 v56, 12, v56
	v_and_b32_e32 v52, 0x1fffff80, v52
	s_nop 0
	v_add_f32_e32 v18, 1.0, v26
	v_cmp_gt_f32_e32 vcc, s0, v18
	v_mfma_f32_16x16x32_bf16 v[58:61], v[22:25], v[4:7], v[58:61]
	s_mov_b32 s0, 0x3f317217
	v_cndmask_b32_e64 v19, 0, 32, vcc
	v_ldexp_f32 v18, v18, v19
	v_log_f32_e32 v18, v18
	v_mov_b32_e32 v20, 0x41b17218
	v_cndmask_b32_e32 v20, 0, v20, vcc
	s_nop 1
	v_add_f32_e32 v59, v54, v59
	v_mul_f32_e32 v19, 0x3f317217, v18
	v_fma_f32 v19, v18, s0, -v19
	v_fmac_f32_e32 v19, 0x3377d1cf, v18
	s_mov_b32 s0, 0x7f800000
	v_fmac_f32_e32 v19, 0x3f317217, v18
	v_cmp_lt_f32_e64 s[0:1], |v18|, s0
	ds_read_b128 v[78:81], v17 offset:21248
	ds_read_b128 v[24:27], v17 offset:21312
	v_cndmask_b32_e64 v18, v18, v19, s[0:1]
	v_add_f32_e32 v19, v54, v58
	v_mul_f32_e32 v19, 0xbfb8aa3b, v19
	v_exp_f32_e32 v19, v19
	v_sub_f32_e32 v18, v18, v20
	v_add_f32_e32 v57, v16, v18
	v_add_f32_e32 v18, v53, v74
	v_add_f32_e32 v16, 1.0, v19
	v_rcp_f32_e32 v16, v16
	v_mul_f32_e32 v18, 0xbfb8aa3b, v18
	v_exp_f32_e32 v18, v18
	v_lshl_add_u32 v74, v55, 2, 0
	v_mul_f32_e32 v16, 0xc1000000, v16
	v_mul_f32_e32 v16, v57, v16
	v_mul_f32_e32 v16, 0x3fb8aa3b, v16
	v_exp_f32_e32 v58, v16
	v_add_f32_e32 v16, 1.0, v18
	v_rcp_f32_e32 v83, v16
	s_movk_i32 s0, 0x410
	v_fma_f32 v16, -v58, v58, 1.0
	v_max_f32_e32 v16, 0, v16
	v_sqrt_f32_e32 v84, v16
	v_mad_u32_u24 v16, v82, s0, v74
	ds_read_b32 v85, v16
	ds_read_b128 v[20:23], v17 offset:23552
	ds_read_b128 v[16:19], v17 offset:23616
	v_mul_f32_e32 v59, 0xbfb8aa3b, v59
	v_mul_f32_e32 v83, v83, v84
	v_lshlrev_b32_e32 v84, 8, v82
	v_or3_b32 v84, v84, v56, v55
	v_exp_f32_e32 v59, v59
	v_lshlrev_b32_e32 v84, 2, v84
	s_waitcnt lgkmcnt(2)
	v_mul_f32_e32 v83, v85, v83
	v_add_u32_e32 v85, 0, v84
	v_readlane_b32 s0, v253, 37
	ds_write_b32 v85, v58 offset:62720
	v_mfma_f32_16x16x32_bf16 v[70:73], v[62:65], v[12:15], 0
	v_add_u32_e32 v58, s0, v84
	ds_write_b32 v58, v83
	v_add_f32_e32 v58, 1.0, v59
	v_add_f32_e32 v59, v53, v75
	v_lshl_or_b32 v75, v82, 2, 1
	v_rcp_f32_e32 v58, v58
	v_mad_u32_u24 v74, v75, s12, v74
	v_lshlrev_b32_e32 v75, 6, v75
	v_or3_b32 v55, v75, v56, v55
	v_add_f32_e32 v56, v54, v60
	v_mul_f32_e32 v56, 0xbfb8aa3b, v56
	v_exp_f32_e32 v56, v56
	v_mul_f32_e32 v58, 0xc1000000, v58
	v_mul_f32_e32 v58, v57, v58
	v_mul_f32_e32 v58, 0x3fb8aa3b, v58
	v_mul_f32_e32 v59, 0xbfb8aa3b, v59
	v_exp_f32_e32 v58, v58
	v_add_f32_e32 v56, 1.0, v56
	v_exp_f32_e32 v59, v59
	v_rcp_f32_e32 v56, v56
	v_fma_f32 v82, -v58, v58, 1.0
	v_lshlrev_b32_e32 v55, 2, v55
	v_add_f32_e32 v59, 1.0, v59
	v_max_f32_e32 v82, 0, v82
	v_add_u32_e32 v60, 0, v55
	v_mul_f32_e32 v56, 0xc1000000, v56
	v_rcp_f32_e32 v59, v59
	v_sqrt_f32_e32 v82, v82
	ds_read_b32 v83, v74
	ds_write_b32 v60, v58 offset:62720
	v_add_f32_e32 v58, v53, v76
	v_mul_f32_e32 v56, v57, v56
	v_mul_f32_e32 v58, 0xbfb8aa3b, v58
	v_mul_f32_e32 v56, 0x3fb8aa3b, v56
	v_exp_f32_e32 v58, v58
	v_exp_f32_e32 v56, v56
	v_mul_f32_e32 v59, v59, v82
	s_waitcnt lgkmcnt(1)
	v_mul_f32_e32 v59, v83, v59
	v_add_u32_e32 v55, s0, v55
	ds_write_b32 v55, v59
	v_add_f32_e32 v55, 1.0, v58
	v_fma_f32 v58, -v56, v56, 1.0
	v_max_f32_e32 v58, 0, v58
	v_rcp_f32_e32 v55, v55
	v_sqrt_f32_e32 v58, v58
	ds_read_b32 v59, v74 offset:260
	v_mfma_f32_16x16x32_bf16 v[62:65], v[62:65], v[8:11], 0
	v_cmp_eq_u32_e32 vcc, 0, v48
	v_mul_f32_e32 v55, v55, v58
	v_or_b32_e32 v58, 0x200, v84
	s_waitcnt lgkmcnt(0)
	v_mul_f32_e32 v55, v55, v59
	v_add_f32_e32 v59, v54, v61
	v_mul_f32_e32 v59, 0xbfb8aa3b, v59
	v_exp_f32_e32 v59, v59
	v_add_u32_e32 v60, 0, v58
	ds_write_b32 v60, v56 offset:62720
	v_add_u32_e32 v56, s0, v58
	v_add_f32_e32 v58, 1.0, v59
	v_rcp_f32_e32 v58, v58
	v_add_f32_e32 v59, v53, v77
	v_mul_f32_e32 v59, 0xbfb8aa3b, v59
	v_mfma_f32_16x16x32_bf16 v[70:73], v[66:69], v[4:7], v[70:73]
	v_exp_f32_e32 v59, v59
	v_mul_f32_e32 v58, 0xc1000000, v58
	v_mul_f32_e32 v58, v57, v58
	v_mul_f32_e32 v58, 0x3fb8aa3b, v58
	v_exp_f32_e32 v75, v58
	ds_write_b32 v56, v55
	v_add_f32_e32 v55, 1.0, v59
	v_mfma_f32_16x16x32_bf16 v[58:61], v[66:69], v[0:3], v[62:65]
	v_fma_f32 v56, -v75, v75, 1.0
	v_max_f32_e32 v56, 0, v56
	v_rcp_f32_e32 v55, v55
	v_add_f32_e32 v62, v54, v70
	v_mul_f32_e32 v62, 0xbfb8aa3b, v62
	v_exp_f32_e32 v62, v62
	v_sqrt_f32_e32 v56, v56
	ds_read_b32 v76, v74 offset:520
	v_add_f32_e32 v58, v53, v58
	v_add_f32_e32 v62, 1.0, v62
	v_rcp_f32_e32 v62, v62
	v_mul_f32_e32 v58, 0xbfb8aa3b, v58
	v_exp_f32_e32 v58, v58
	v_mul_f32_e32 v55, v55, v56
	v_mul_f32_e32 v62, 0xc1000000, v62
	v_mul_f32_e32 v62, v57, v62
	v_mul_f32_e32 v62, 0x3fb8aa3b, v62
	v_exp_f32_e32 v66, v62
	v_or_b32_e32 v56, 0x300, v84
	s_waitcnt lgkmcnt(0)
; __device__ __forceinline__ float fexp(float x) { return __expf(x); }
; __device__ __forceinline__ float sigm(float x) { return frcp(1.f + fexp(-x)); }
; __device__ void rg_tile(unsigned char* lds, const Params& p, int l, int b, int ck, int hh, bool outmode) {
;     ...
; #pragma unroll
;     for (int tf = 0; tf < 4; ++tf)
; #pragma unroll
;       for (int jj = 0; jj < 4; ++jj) {
;         const int tt = tf * 16 + lg * 4 + jj;
;         const float r = sigm(ar[tf][jj] + br);
;         const float ig = sigm(ai[tf][jj] + bi);
;         const float la = -8.0f * r * sp;
;         const float a = fexp(la);
;         const float bq = __builtin_amdgcn_sqrtf(fmaxf(1.f - a * a, 0.f)) * ig * XR[tt * 65 + j];
;         AA[(d * 64 + tt) * 64 + j] = a;
;         BQ[(d * 64 + tt) * 64 + j] = bq;
;       }
	v_mul_f32_e32 v55, v55, v76
	v_add_u32_e32 v63, 0, v56
	v_add_u32_e32 v56, s0, v56
	ds_write_b32 v56, v55
	v_fma_f32 v56, -v66, v66, 1.0
	ds_write_b32 v63, v75 offset:62720
	v_add_f32_e32 v55, 1.0, v58
	v_max_f32_e32 v56, 0, v56
	v_rcp_f32_e32 v55, v55
	v_sqrt_f32_e32 v56, v56
	ds_read_b32 v58, v74 offset:3900
	v_add_f32_e32 v59, v53, v59
	v_mul_f32_e32 v59, 0xbfb8aa3b, v59
	v_mul_f32_e32 v55, v55, v56
	v_exp_f32_e32 v59, v59
	s_waitcnt lgkmcnt(0)
	v_mul_f32_e32 v55, v55, v58
	v_add_f32_e32 v58, v54, v71
	v_mul_f32_e32 v58, 0xbfb8aa3b, v58
	v_exp_f32_e32 v58, v58
	v_or_b32_e32 v56, 0x1000, v84
	v_add_u32_e32 v67, 0, v56
	v_add_u32_e32 v56, s0, v56
	v_add_f32_e32 v58, 1.0, v58
	v_rcp_f32_e32 v58, v58
	ds_write_b32 v56, v55
	ds_write_b32 v67, v66 offset:62720
	v_add_f32_e32 v55, 1.0, v59
	v_mul_f32_e32 v58, 0xc1000000, v58
	v_mul_f32_e32 v58, v57, v58
	v_mul_f32_e32 v58, 0x3fb8aa3b, v58
	v_exp_f32_e32 v58, v58
	v_rcp_f32_e32 v55, v55
	ds_read_b32 v59, v74 offset:4160
	v_mfma_f32_16x16x32_bf16 v[62:65], v[78:81], v[12:15], 0
	v_fma_f32 v56, -v58, v58, 1.0
	v_max_f32_e32 v56, 0, v56
	v_sqrt_f32_e32 v56, v56
	v_mfma_f32_16x16x32_bf16 v[62:65], v[24:27], v[4:7], v[62:65]
	v_mul_f32_e32 v55, v55, v56
	s_waitcnt lgkmcnt(0)
	v_mul_f32_e32 v55, v55, v59
	v_add_f32_e32 v59, v54, v72
	v_mul_f32_e32 v59, 0xbfb8aa3b, v59
	v_exp_f32_e32 v59, v59
	v_or_b32_e32 v56, 0x1100, v84
	v_add_u32_e32 v70, 0, v56
	ds_write_b32 v70, v58 offset:62720
	v_add_f32_e32 v58, 1.0, v59
	v_rcp_f32_e32 v58, v58
	v_add_f32_e32 v59, v53, v60
	v_mul_f32_e32 v59, 0xbfb8aa3b, v59
	v_exp_f32_e32 v59, v59
	v_mul_f32_e32 v58, 0xc1000000, v58
	v_mul_f32_e32 v58, v57, v58
	v_mul_f32_e32 v58, 0x3fb8aa3b, v58
	v_exp_f32_e32 v58, v58
	v_add_u32_e32 v56, s0, v56
	ds_write_b32 v56, v55
	v_add_f32_e32 v55, 1.0, v59
	v_fma_f32 v56, -v58, v58, 1.0
	v_max_f32_e32 v56, 0, v56
	v_rcp_f32_e32 v55, v55
	v_sqrt_f32_e32 v56, v56
	ds_read_b32 v59, v74 offset:4420
	v_mfma_f32_16x16x32_bf16 v[66:69], v[78:81], v[8:11], 0
	v_mul_f32_e32 v55, v55, v56
	v_or_b32_e32 v56, 0x1200, v84
	s_waitcnt lgkmcnt(0)
	v_mul_f32_e32 v55, v55, v59
	v_add_f32_e32 v59, v54, v73
	v_mul_f32_e32 v59, 0xbfb8aa3b, v59
	v_exp_f32_e32 v59, v59
	v_add_u32_e32 v60, 0, v56
	ds_write_b32 v60, v58 offset:62720
	v_add_u32_e32 v56, s0, v56
	v_add_f32_e32 v58, 1.0, v59
	v_rcp_f32_e32 v58, v58
	v_add_f32_e32 v59, v53, v61
	v_mul_f32_e32 v59, 0xbfb8aa3b, v59
	v_exp_f32_e32 v59, v59
	v_mul_f32_e32 v58, 0xc1000000, v58
	v_mul_f32_e32 v58, v57, v58
	v_mul_f32_e32 v58, 0x3fb8aa3b, v58
	v_exp_f32_e32 v58, v58
	ds_write_b32 v56, v55
	v_add_f32_e32 v55, 1.0, v59
	v_rcp_f32_e32 v55, v55
	v_fma_f32 v56, -v58, v58, 1.0
	v_max_f32_e32 v56, 0, v56
	v_sqrt_f32_e32 v56, v56
	ds_read_b32 v59, v74 offset:4680
	v_mfma_f32_16x16x32_bf16 v[24:27], v[24:27], v[0:3], v[66:69]
	v_mul_f32_e32 v55, v55, v56
	v_or_b32_e32 v56, 0x1300, v84
	s_waitcnt lgkmcnt(0)
	v_mul_f32_e32 v55, v55, v59
	v_add_f32_e32 v59, v54, v62
	v_mul_f32_e32 v59, 0xbfb8aa3b, v59
	v_exp_f32_e32 v59, v59
	v_add_u32_e32 v60, 0, v56
	ds_write_b32 v60, v58 offset:62720
	v_add_f32_e32 v24, v53, v24
	v_add_f32_e32 v58, 1.0, v59
	v_rcp_f32_e32 v58, v58
	v_mul_f32_e32 v24, 0xbfb8aa3b, v24
	v_exp_f32_e32 v24, v24
	v_add_u32_e32 v56, s0, v56
	v_mul_f32_e32 v58, 0xc1000000, v58
	v_mul_f32_e32 v58, v57, v58
	v_mul_f32_e32 v58, 0x3fb8aa3b, v58
	v_exp_f32_e32 v58, v58
	ds_write_b32 v56, v55
	v_add_f32_e32 v24, 1.0, v24
	v_rcp_f32_e32 v24, v24
	v_fma_f32 v55, -v58, v58, 1.0
	v_max_f32_e32 v55, 0, v55
	v_sqrt_f32_e32 v55, v55
	ds_read_b32 v56, v74 offset:8060
	v_mfma_f32_16x16x32_bf16 v[12:15], v[20:23], v[12:15], 0
	v_add_f32_e32 v25, v53, v25
	v_mul_f32_e32 v24, v24, v55
	v_mul_f32_e32 v25, 0xbfb8aa3b, v25
	s_waitcnt lgkmcnt(0)
	v_mul_f32_e32 v24, v24, v56
	v_add_f32_e32 v56, v54, v63
	v_mul_f32_e32 v56, 0xbfb8aa3b, v56
	v_exp_f32_e32 v56, v56
	v_mfma_f32_16x16x32_bf16 v[8:11], v[20:23], v[8:11], 0
	v_add_f32_e32 v22, v54, v64
	v_mul_f32_e32 v22, 0xbfb8aa3b, v22
	v_add_f32_e32 v56, 1.0, v56
	v_rcp_f32_e32 v56, v56
	v_exp_f32_e32 v22, v22
	v_exp_f32_e32 v25, v25
	v_or_b32_e32 v55, 0x2000, v84
	v_mul_f32_e32 v56, 0xc1000000, v56
	v_mul_f32_e32 v56, v57, v56
	v_mul_f32_e32 v56, 0x3fb8aa3b, v56
	v_exp_f32_e32 v56, v56
	v_add_f32_e32 v22, 1.0, v22
	v_rcp_f32_e32 v22, v22
	v_mfma_f32_16x16x32_bf16 v[4:7], v[16:19], v[4:7], v[12:15]
	v_add_u32_e32 v59, 0, v55
	v_add_u32_e32 v55, s0, v55
	ds_write_b32 v55, v24
	v_add_f32_e32 v14, v54, v65
	v_mul_f32_e32 v14, 0xbfb8aa3b, v14
	v_add_f32_e32 v24, 1.0, v25
	v_fma_f32 v25, -v56, v56, 1.0
	v_exp_f32_e32 v14, v14
	ds_write_b32 v59, v58 offset:62720
	v_max_f32_e32 v25, 0, v25
	v_or_b32_e32 v21, 0x2100, v84
	v_mul_f32_e32 v22, 0xc1000000, v22
	v_rcp_f32_e32 v24, v24
	v_sqrt_f32_e32 v25, v25
	ds_read_b32 v55, v74 offset:8320
	v_add_u32_e32 v23, 0, v21
	v_mul_f32_e32 v22, v57, v22
	ds_write_b32 v23, v56 offset:62720
	v_add_f32_e32 v23, v53, v26
	v_mul_f32_e32 v22, 0x3fb8aa3b, v22
	v_mul_f32_e32 v23, 0xbfb8aa3b, v23
	v_exp_f32_e32 v22, v22
	v_add_f32_e32 v14, 1.0, v14
	v_exp_f32_e32 v23, v23
	v_rcp_f32_e32 v14, v14
	v_mul_f32_e32 v20, v24, v25
	v_add_f32_e32 v4, v54, v4
	s_waitcnt lgkmcnt(1)
	v_mul_f32_e32 v20, v20, v55
	v_add_u32_e32 v21, s0, v21
	v_mul_f32_e32 v4, 0xbfb8aa3b, v4
	ds_write_b32 v21, v20
	v_fma_f32 v21, -v22, v22, 1.0
	v_exp_f32_e32 v4, v4
	v_add_f32_e32 v20, 1.0, v23
	v_max_f32_e32 v21, 0, v21
	v_or_b32_e32 v13, 0x2200, v84
	v_mul_f32_e32 v14, 0xc1000000, v14
	v_rcp_f32_e32 v20, v20
	v_sqrt_f32_e32 v21, v21
	ds_read_b32 v23, v74 offset:8580
	v_add_u32_e32 v15, 0, v13
	v_mul_f32_e32 v14, v57, v14
	ds_write_b32 v15, v22 offset:62720
	v_add_f32_e32 v15, v53, v27
	v_mul_f32_e32 v14, 0x3fb8aa3b, v14
	v_mul_f32_e32 v15, 0xbfb8aa3b, v15
	v_exp_f32_e32 v14, v14
	v_add_f32_e32 v4, 1.0, v4
	v_exp_f32_e32 v15, v15
	v_rcp_f32_e32 v4, v4
	v_mul_f32_e32 v12, v20, v21
	s_waitcnt lgkmcnt(1)
; __device__ void rg_tile(unsigned char* lds, const Params& p, int l, int b, int ck, int hh, bool outmode) {
;     ...
;   __syncthreads();
;   {
;     float* SEG = XR;
;     const int seg = tid >> 7, d = (tid >> 6) & 1, j = tid & 63;
;     const int ch = hh * 64 + j;
;     const size_t ci = ((size_t)(b * 36 + ck) * 2 + d) * 256 + ch;
;     float H = 0.f, Ap = 1.f;
; #pragma unroll
;     for (int q = 0; q < 16; ++q) {
;       const int pos = seg * 16 + q;
;       const int tt = d == 0 ? pos : 63 - pos;
;       const float a = AA[(d * 64 + tt) * 64 + j];
;       H = a * H + BQ[(d * 64 + tt) * 64 + j];
;       Ap *= a;
;     }
;     SEG[((seg * 2 + d) * 64 + j) * 2 + 0] = Ap;
;     SEG[((seg * 2 + d) * 64 + j) * 2 + 1] = H;
	v_mul_f32_e32 v12, v12, v23
	v_add_u32_e32 v13, s0, v13
	v_mfma_f32_16x16x32_bf16 v[0:3], v[16:19], v[0:3], v[8:11]
	v_add_f32_e32 v5, v54, v5
	ds_write_b32 v13, v12
	v_fma_f32 v13, -v14, v14, 1.0
	v_mul_f32_e32 v5, 0xbfb8aa3b, v5
	v_add_f32_e32 v12, 1.0, v15
	v_max_f32_e32 v13, 0, v13
	v_mul_f32_e32 v4, 0xc1000000, v4
	v_exp_f32_e32 v5, v5
	v_rcp_f32_e32 v12, v12
	v_sqrt_f32_e32 v13, v13
	ds_read_b32 v15, v74 offset:8840
	v_mul_f32_e32 v4, v57, v4
	v_add_f32_e32 v0, v53, v0
	v_mul_f32_e32 v4, 0x3fb8aa3b, v4
	v_mul_f32_e32 v0, 0xbfb8aa3b, v0
	v_exp_f32_e32 v4, v4
	v_exp_f32_e32 v0, v0
	v_add_f32_e32 v5, 1.0, v5
	v_mul_f32_e32 v8, v12, v13
	v_or_b32_e32 v9, 0x2300, v84
	v_rcp_f32_e32 v5, v5
	s_waitcnt lgkmcnt(0)
	v_mul_f32_e32 v8, v8, v15
	v_add_u32_e32 v10, 0, v9
	v_add_u32_e32 v9, s0, v9
	ds_write_b32 v9, v8
	v_fma_f32 v8, -v4, v4, 1.0
	ds_write_b32 v10, v14 offset:62720
	v_add_f32_e32 v0, 1.0, v0
	v_max_f32_e32 v8, 0, v8
	v_rcp_f32_e32 v0, v0
	v_sqrt_f32_e32 v8, v8
	ds_read_b32 v9, v74 offset:12220
	v_mul_f32_e32 v5, 0xc1000000, v5
	v_add_f32_e32 v1, v53, v1
	v_mul_f32_e32 v5, v57, v5
	v_mul_f32_e32 v1, 0xbfb8aa3b, v1
	v_mul_f32_e32 v5, 0x3fb8aa3b, v5
	v_exp_f32_e32 v1, v1
	v_exp_f32_e32 v5, v5
	v_mul_f32_e32 v0, v0, v8
	v_or_b32_e32 v8, 0x3000, v84
	s_waitcnt lgkmcnt(0)
	v_mul_f32_e32 v0, v0, v9
	v_add_u32_e32 v9, 0, v8
	ds_write_b32 v9, v4 offset:62720
	v_add_u32_e32 v4, s0, v8
	ds_write_b32 v4, v0
	v_add_f32_e32 v0, 1.0, v1
	v_fma_f32 v1, -v5, v5, 1.0
	v_max_f32_e32 v1, 0, v1
	v_rcp_f32_e32 v0, v0
	v_sqrt_f32_e32 v1, v1
	ds_read_b32 v4, v74 offset:12480
	v_add_f32_e32 v2, v53, v2
	v_mul_f32_e32 v2, 0xbfb8aa3b, v2
	v_mul_f32_e32 v0, v0, v1
	v_exp_f32_e32 v2, v2
	s_waitcnt lgkmcnt(0)
	v_mul_f32_e32 v0, v0, v4
	v_add_f32_e32 v4, v54, v6
	v_mul_f32_e32 v4, 0xbfb8aa3b, v4
	v_exp_f32_e32 v4, v4
	v_or_b32_e32 v1, 0x3100, v84
	v_add_u32_e32 v6, 0, v1
	v_add_u32_e32 v1, s0, v1
	v_add_f32_e32 v4, 1.0, v4
	v_rcp_f32_e32 v4, v4
	ds_write_b32 v1, v0
	ds_write_b32 v6, v5 offset:62720
	v_add_f32_e32 v0, 1.0, v2
	v_mul_f32_e32 v4, 0xc1000000, v4
	v_mul_f32_e32 v4, v57, v4
	v_mul_f32_e32 v4, 0x3fb8aa3b, v4
	v_exp_f32_e32 v4, v4
	v_rcp_f32_e32 v0, v0
	ds_read_b32 v2, v74 offset:12740
	v_add_f32_e32 v3, v53, v3
	v_fma_f32 v1, -v4, v4, 1.0
	v_max_f32_e32 v1, 0, v1
	v_sqrt_f32_e32 v1, v1
	v_mul_f32_e32 v3, 0xbfb8aa3b, v3
	v_exp_f32_e32 v3, v3
	v_lshlrev_b32_e32 v20, 4, v33
	v_mul_f32_e32 v0, v0, v1
	s_waitcnt lgkmcnt(0)
	v_mul_f32_e32 v0, v0, v2
	v_add_f32_e32 v2, v54, v7
	v_mul_f32_e32 v2, 0xbfb8aa3b, v2
	v_exp_f32_e32 v2, v2
	v_or_b32_e32 v1, 0x3200, v84
	v_add_u32_e32 v5, 0, v1
	v_add_u32_e32 v1, s0, v1
	v_add_f32_e32 v2, 1.0, v2
	v_rcp_f32_e32 v2, v2
	ds_write_b32 v1, v0
	ds_write_b32 v5, v4 offset:62720
	v_add_f32_e32 v0, 1.0, v3
	v_mul_f32_e32 v2, 0xc1000000, v2
	v_mul_f32_e32 v2, v57, v2
	v_mul_f32_e32 v2, 0x3fb8aa3b, v2
	v_exp_f32_e32 v2, v2
	v_rcp_f32_e32 v0, v0
	ds_read_b32 v3, v74 offset:13000
	v_lshl_or_b32 v57, v48, 12, v29
	v_fma_f32 v1, -v2, v2, 1.0
	v_max_f32_e32 v1, 0, v1
	v_sqrt_f32_e32 v1, v1
	v_or_b32_e32 v8, 11, v20
	v_sub_u32_e32 v9, 63, v8
	v_cndmask_b32_e32 v8, v9, v8, vcc
	v_mul_f32_e32 v0, v0, v1
	v_or_b32_e32 v1, 0x3300, v84
	s_waitcnt lgkmcnt(0)
	v_mul_f32_e32 v0, v0, v3
	v_add_u32_e32 v3, 0, v1
	ds_write_b32 v3, v2 offset:62720
	v_or_b32_e32 v2, 1, v20
	v_sub_u32_e32 v3, 63, v2
	v_cndmask_b32_e32 v2, v3, v2, vcc
	v_lshlrev_b32_e32 v2, 6, v2
	v_add_lshl_u32 v2, v2, v57, 2
	v_add_u32_e32 v16, 0, v2
	v_add_u32_e32 v22, s0, v2
	v_or_b32_e32 v2, 2, v20
	v_sub_u32_e32 v3, 63, v2
	v_cndmask_b32_e32 v2, v3, v2, vcc
	v_lshlrev_b32_e32 v2, 6, v2
	v_add_u32_e32 v1, s0, v1
	v_add_lshl_u32 v2, v2, v57, 2
	ds_write_b32 v1, v0
	v_sub_u32_e32 v0, 63, v20
	v_add_u32_e32 v23, 0, v2
	v_add_u32_e32 v24, s0, v2
	v_or_b32_e32 v2, 3, v20
	v_cndmask_b32_e32 v0, v0, v20, vcc
	v_sub_u32_e32 v3, 63, v2
	v_lshlrev_b32_e32 v0, 6, v0
	v_cndmask_b32_e32 v2, v3, v2, vcc
	v_add_lshl_u32 v1, v0, v57, 2
	v_lshlrev_b32_e32 v2, 6, v2
	v_add_u32_e32 v0, 0, v1
	v_add_lshl_u32 v2, v2, v57, 2
	s_waitcnt lgkmcnt(0)
	s_barrier
	s_and_b32 s0, s44, 1
	s_lshr_b32 s1, s44, 1
	v_and_b32_e32 v190, 63, v195
	v_lshlrev_b32_e32 v189, 3, v195
	s_cmp_eq_u32 s0, 0
	s_cbranch_scc0 .Lrgs_p5_b1
	s_lshl_b32 s2, s1, 12
	s_add_i32 s2, s2, 0xf500
	v_lshl_add_u32 v188, v190, 2, s2
	ds_read_b32 v154, v188 offset:0
	ds_read_b32 v170, v188 offset:32768
	ds_read_b32 v155, v188 offset:256
	ds_read_b32 v171, v188 offset:33024
	ds_read_b32 v156, v188 offset:512
	ds_read_b32 v172, v188 offset:33280
	ds_read_b32 v157, v188 offset:768
	ds_read_b32 v173, v188 offset:33536
	ds_read_b32 v158, v188 offset:1024
	ds_read_b32 v174, v188 offset:33792
	ds_read_b32 v159, v188 offset:1280
	ds_read_b32 v175, v188 offset:34048
	ds_read_b32 v160, v188 offset:1536
	ds_read_b32 v176, v188 offset:34304
	s_waitcnt lgkmcnt(12)
	v_mov_b32_e32 v186, v170
	v_mov_b32_e32 v187, v154
	ds_read_b32 v161, v188 offset:1792
	ds_read_b32 v177, v188 offset:34560
	s_waitcnt lgkmcnt(12)
	v_fma_f32 v186, v155, v186, v171
	v_mul_f32_e32 v187, v187, v155
	ds_read_b32 v162, v188 offset:2048
	ds_read_b32 v178, v188 offset:34816
	s_waitcnt lgkmcnt(12)
	v_fma_f32 v186, v156, v186, v172
	v_mul_f32_e32 v187, v187, v156
	ds_read_b32 v163, v188 offset:2304
	ds_read_b32 v179, v188 offset:35072
	s_waitcnt lgkmcnt(12)
	v_fma_f32 v186, v157, v186, v173
	v_mul_f32_e32 v187, v187, v157
	ds_read_b32 v164, v188 offset:2560
	ds_read_b32 v180, v188 offset:35328
	s_waitcnt lgkmcnt(12)
	v_fma_f32 v186, v158, v186, v174
	v_mul_f32_e32 v187, v187, v158
	ds_read_b32 v165, v188 offset:2816
	ds_read_b32 v181, v188 offset:35584
	s_waitcnt lgkmcnt(12)
	v_fma_f32 v186, v159, v186, v175
	v_mul_f32_e32 v187, v187, v159
	ds_read_b32 v166, v188 offset:3072
	ds_read_b32 v182, v188 offset:35840
	s_waitcnt lgkmcnt(12)
	v_fma_f32 v186, v160, v186, v176
	v_mul_f32_e32 v187, v187, v160
	ds_read_b32 v167, v188 offset:3328
	ds_read_b32 v183, v188 offset:36096
	s_waitcnt lgkmcnt(12)
	v_fma_f32 v186, v161, v186, v177
	v_mul_f32_e32 v187, v187, v161
	ds_read_b32 v168, v188 offset:3584
	ds_read_b32 v184, v188 offset:36352
	s_waitcnt lgkmcnt(12)
	v_fma_f32 v186, v162, v186, v178
	v_mul_f32_e32 v187, v187, v162
	ds_read_b32 v169, v188 offset:3840
	ds_read_b32 v185, v188 offset:36608
	s_waitcnt lgkmcnt(12)
	v_fma_f32 v186, v163, v186, v179
	v_mul_f32_e32 v187, v187, v163
	s_waitcnt lgkmcnt(10)
	v_fma_f32 v186, v164, v186, v180
	v_mul_f32_e32 v187, v187, v164
	s_waitcnt lgkmcnt(8)
	v_fma_f32 v186, v165, v186, v181
	v_mul_f32_e32 v187, v187, v165
	s_waitcnt lgkmcnt(6)
	v_fma_f32 v186, v166, v186, v182
	v_mul_f32_e32 v187, v187, v166
	s_waitcnt lgkmcnt(4)
	v_fma_f32 v186, v167, v186, v183
	v_mul_f32_e32 v187, v187, v167
	s_waitcnt lgkmcnt(2)
	v_fma_f32 v186, v168, v186, v184
	v_mul_f32_e32 v187, v187, v168
	s_waitcnt lgkmcnt(0)
	v_fma_f32 v186, v169, v186, v185
	v_mul_f32_e32 v187, v187, v169
	v_mov_b32_e32 v190, v187
	v_mov_b32_e32 v191, v186
	ds_write_b64 v189, v[190:191]
	s_branch .Lrgs_p5_j1
; __device__ void rg_tile(unsigned char* lds, const Params& p, int l, int b, int ck, int hh, bool outmode) {
;     ...
;     __syncthreads();
;     if (!outmode) {
;       if (seg == 0) {
;         float Ht = 0.f, At = 1.f;
; #pragma unroll
;         for (int sgi = 0; sgi < 4; ++sgi) {
;           const float as = SEG[((sgi * 2 + d) * 64 + j) * 2 + 0], hs = SEG[((sgi * 2 + d) * 64 + j) * 2 + 1];
;           Ht = as * Ht + hs;
;           At *= as;
;         }
;         agg[ci * 2 + 0] = At;
;         agg[ci * 2 + 1] = Ht;
;       }
;     } else {
;       float hc = car_pre;
;       for (int sgi = 0; sgi < seg; ++sgi) {
;         const float as = SEG[((sgi * 2 + d) * 64 + j) * 2 + 0], hs = SEG[((sgi * 2 + d) * 64 + j) * 2 + 1];
;         hc = as * hc + hs;
;       }
; #pragma unroll
;       for (int q = 0; q < 16; ++q) {
;         const int pos = seg * 16 + q;
;         const int tt = d == 0 ? pos : 63 - pos;
;         const float a = AA[(d * 64 + tt) * 64 + j];
;         hc = a * hc + BQ[(d * 64 + tt) * 64 + j];
;         AA[(d * 64 + tt) * 64 + j] = hc;
;       }
.Lrgs_p5_b1:
	s_sub_i32 s2, 3, s1
	s_lshl_b32 s2, s2, 12
	s_add_i32 s2, s2, 0x13500
	v_lshl_add_u32 v188, v190, 2, s2
	ds_read_b32 v154, v188 offset:3840
	ds_read_b32 v170, v188 offset:36608
	ds_read_b32 v155, v188 offset:3584
	ds_read_b32 v171, v188 offset:36352
	ds_read_b32 v156, v188 offset:3328
	ds_read_b32 v172, v188 offset:36096
	ds_read_b32 v157, v188 offset:3072
	ds_read_b32 v173, v188 offset:35840
	ds_read_b32 v158, v188 offset:2816
	ds_read_b32 v174, v188 offset:35584
	ds_read_b32 v159, v188 offset:2560
	ds_read_b32 v175, v188 offset:35328
	ds_read_b32 v160, v188 offset:2304
	ds_read_b32 v176, v188 offset:35072
	s_waitcnt lgkmcnt(12)
	v_mov_b32_e32 v186, v170
	v_mov_b32_e32 v187, v154
	ds_read_b32 v161, v188 offset:2048
	ds_read_b32 v177, v188 offset:34816
	s_waitcnt lgkmcnt(12)
	v_fma_f32 v186, v155, v186, v171
	v_mul_f32_e32 v187, v187, v155
	ds_read_b32 v162, v188 offset:1792
	ds_read_b32 v178, v188 offset:34560
	s_waitcnt lgkmcnt(12)
	v_fma_f32 v186, v156, v186, v172
	v_mul_f32_e32 v187, v187, v156
	ds_read_b32 v163, v188 offset:1536
	ds_read_b32 v179, v188 offset:34304
	s_waitcnt lgkmcnt(12)
	v_fma_f32 v186, v157, v186, v173
	v_mul_f32_e32 v187, v187, v157
	ds_read_b32 v164, v188 offset:1280
	ds_read_b32 v180, v188 offset:34048
	s_waitcnt lgkmcnt(12)
	v_fma_f32 v186, v158, v186, v174
	v_mul_f32_e32 v187, v187, v158
	ds_read_b32 v165, v188 offset:1024
	ds_read_b32 v181, v188 offset:33792
	s_waitcnt lgkmcnt(12)
	v_fma_f32 v186, v159, v186, v175
	v_mul_f32_e32 v187, v187, v159
	ds_read_b32 v166, v188 offset:768
	ds_read_b32 v182, v188 offset:33536
	s_waitcnt lgkmcnt(12)
	v_fma_f32 v186, v160, v186, v176
	v_mul_f32_e32 v187, v187, v160
	ds_read_b32 v167, v188 offset:512
	ds_read_b32 v183, v188 offset:33280
	s_waitcnt lgkmcnt(12)
	v_fma_f32 v186, v161, v186, v177
	v_mul_f32_e32 v187, v187, v161
	ds_read_b32 v168, v188 offset:256
	ds_read_b32 v184, v188 offset:33024
	s_waitcnt lgkmcnt(12)
	v_fma_f32 v186, v162, v186, v178
	v_mul_f32_e32 v187, v187, v162
	ds_read_b32 v169, v188 offset:0
	ds_read_b32 v185, v188 offset:32768
	s_waitcnt lgkmcnt(12)
	v_fma_f32 v186, v163, v186, v179
	v_mul_f32_e32 v187, v187, v163
	s_waitcnt lgkmcnt(10)
	v_fma_f32 v186, v164, v186, v180
	v_mul_f32_e32 v187, v187, v164
	s_waitcnt lgkmcnt(8)
	v_fma_f32 v186, v165, v186, v181
	v_mul_f32_e32 v187, v187, v165
	s_waitcnt lgkmcnt(6)
	v_fma_f32 v186, v166, v186, v182
	v_mul_f32_e32 v187, v187, v166
	s_waitcnt lgkmcnt(4)
	v_fma_f32 v186, v167, v186, v183
	v_mul_f32_e32 v187, v187, v167
	s_waitcnt lgkmcnt(2)
	v_fma_f32 v186, v168, v186, v184
	v_mul_f32_e32 v187, v187, v168
	s_waitcnt lgkmcnt(0)
	v_fma_f32 v186, v169, v186, v185
	v_mul_f32_e32 v187, v187, v169
	v_mov_b32_e32 v190, v187
	v_mov_b32_e32 v191, v186
	ds_write_b64 v189, v[190:191]
.Lrgs_p5_j1:
	v_mov_b32_e32 v239, 2
	s_waitcnt lgkmcnt(0)
	s_barrier
	v_and_b32_e32 v190, 63, v195
	v_lshlrev_b32_e32 v190, 3, v190
	s_lshl_b32 s2, s0, 9
	v_add_u32_e32 v190, s2, v190
	s_cmp_eq_u32 s1, 0
	s_cbranch_scc1 .Lrgs_p5_c0
	ds_read_b64 v[186:187], v190
	s_waitcnt lgkmcnt(0)
	v_fma_f32 v51, v186, v51, v187
	s_cmp_eq_u32 s1, 1
	s_cbranch_scc1 .Lrgs_p5_c0
	ds_read_b64 v[186:187], v190 offset:1024
	s_waitcnt lgkmcnt(0)
	v_fma_f32 v51, v186, v51, v187
	s_cmp_eq_u32 s1, 2
	s_cbranch_scc1 .Lrgs_p5_c0
	ds_read_b64 v[186:187], v190 offset:2048
	s_waitcnt lgkmcnt(0)
	v_fma_f32 v51, v186, v51, v187
.Lrgs_p5_c0:
	s_cmp_eq_u32 s0, 0
	s_cbranch_scc0 .Lrgs_p5_b2
	v_fmac_f32_e32 v170, v154, v51
	ds_write_b32 v188, v170 offset:0
	v_fmac_f32_e32 v171, v155, v170
	ds_write_b32 v188, v171 offset:256
	v_fmac_f32_e32 v172, v156, v171
	ds_write_b32 v188, v172 offset:512
	v_fmac_f32_e32 v173, v157, v172
	ds_write_b32 v188, v173 offset:768
	v_fmac_f32_e32 v174, v158, v173
	ds_write_b32 v188, v174 offset:1024
	v_fmac_f32_e32 v175, v159, v174
	ds_write_b32 v188, v175 offset:1280
	v_fmac_f32_e32 v176, v160, v175
	ds_write_b32 v188, v176 offset:1536
	v_fmac_f32_e32 v177, v161, v176
	ds_write_b32 v188, v177 offset:1792
	v_fmac_f32_e32 v178, v162, v177
	ds_write_b32 v188, v178 offset:2048
	v_fmac_f32_e32 v179, v163, v178
	ds_write_b32 v188, v179 offset:2304
	v_fmac_f32_e32 v180, v164, v179
	ds_write_b32 v188, v180 offset:2560
	v_fmac_f32_e32 v181, v165, v180
	ds_write_b32 v188, v181 offset:2816
	v_fmac_f32_e32 v182, v166, v181
	ds_write_b32 v188, v182 offset:3072
	v_fmac_f32_e32 v183, v167, v182
	ds_write_b32 v188, v183 offset:3328
	v_fmac_f32_e32 v184, v168, v183
	ds_write_b32 v188, v184 offset:3584
	v_fmac_f32_e32 v185, v169, v184
	ds_write_b32 v188, v185 offset:3840
	s_branch .Lrgs_p5_j2
.Lrgs_p5_b2:
	v_fmac_f32_e32 v170, v154, v51
	ds_write_b32 v188, v170 offset:3840
	v_fmac_f32_e32 v171, v155, v170
	ds_write_b32 v188, v171 offset:3584
	v_fmac_f32_e32 v172, v156, v171
	ds_write_b32 v188, v172 offset:3328
	v_fmac_f32_e32 v173, v157, v172
	ds_write_b32 v188, v173 offset:3072
	v_fmac_f32_e32 v174, v158, v173
	ds_write_b32 v188, v174 offset:2816
	v_fmac_f32_e32 v175, v159, v174
	ds_write_b32 v188, v175 offset:2560
	v_fmac_f32_e32 v176, v160, v175
	ds_write_b32 v188, v176 offset:2304
	v_fmac_f32_e32 v177, v161, v176
	ds_write_b32 v188, v177 offset:2048
	v_fmac_f32_e32 v178, v162, v177
	ds_write_b32 v188, v178 offset:1792
	v_fmac_f32_e32 v179, v163, v178
	ds_write_b32 v188, v179 offset:1536
	v_fmac_f32_e32 v180, v164, v179
	ds_write_b32 v188, v180 offset:1280
	v_fmac_f32_e32 v181, v165, v180
	ds_write_b32 v188, v181 offset:1024
	v_fmac_f32_e32 v182, v166, v181
	ds_write_b32 v188, v182 offset:768
	v_fmac_f32_e32 v183, v167, v182
	ds_write_b32 v188, v183 offset:512
	v_fmac_f32_e32 v184, v168, v183
	ds_write_b32 v188, v184 offset:256
	v_fmac_f32_e32 v185, v169, v184
	ds_write_b32 v188, v185 offset:0
; __device__ __forceinline__ bf16_t f2bf(float f) { return (bf16_t)(pack2(f, 0.f) & 0xffffu); }
; __device__ void rg_tile(unsigned char* lds, const Params& p, int l, int b, int ck, int hh, bool outmode) {
;     ...
;   if (outmode) {
;     const int ch = hh * 64 + lane;
;     const float gm = p.in[24][(size_t)l * 1024 + 768 + ch];
; #pragma unroll
;     for (int q = 0; q < 8; ++q) {
;       const int tt = w * 8 + q;
;       const int row = rowbase + t0 + tt;
;       const float hr = AA[tt * 64 + lane] + AA[(64 + tt) * 64 + lane];
;       const float v = hr * gelu_tanh(gp_pre[q]);
;       const float ss = wsum(v * v, lane);
;       const float rn = rsqrtf(ss * (1.f / 64.f) + EPSF);
;       y[(size_t)row * 1024 + 768 + ch] = f2bf(v * rn * gm);
;     }
;     __syncthreads();
;   }
.Lrgs_p5_j2:
	s_waitcnt lgkmcnt(0)
	s_barrier
	s_and_b32 s0, s13, 3
	v_bfe_u32 v208, v195, 4, 2
	v_and_b32_e32 v209, 15, v195
	s_lshl_b32 s1, s44, 11
	v_lshlrev_b32_e32 v210, 8, v208
	v_lshl_add_u32 v210, v209, 4, v210
	v_add_u32_e32 v210, s1, v210
	v_add_u32_e32 v210, 0xf500, v210
	ds_read_b128 v[212:215], v210
	ds_read_b128 v[216:219], v210 offset:16384
	ds_read_b128 v[154:157], v210 offset:1024
	ds_read_b128 v[158:161], v210 offset:17408
	v_readlane_b32 s2, v251, 31
	v_readlane_b32 s3, v251, 32
	s_add_i32 s4, s48, s45
	s_lshl_b32 s4, s4, 11
	s_lshl_b32 s5, s0, 7
	s_add_i32 s4, s4, s5
	s_addk_i32 s4, 0x600
	s_add_u32 s2, s2, s4
	s_addc_u32 s3, s3, 0
	v_lshlrev_b32_e32 v211, 11, v208
	v_lshl_add_u32 v211, v209, 3, v211
	v_lshlrev_b32_e32 v162, 16, v204
	v_and_b32_e32 v163, 0xffff0000, v204
	v_lshlrev_b32_e32 v164, 16, v205
	v_and_b32_e32 v165, 0xffff0000, v205
	v_lshlrev_b32_e32 v166, 16, v206
	v_and_b32_e32 v167, 0xffff0000, v206
	v_lshlrev_b32_e32 v168, 16, v207
	v_and_b32_e32 v169, 0xffff0000, v207
	v_mul_f32_e32 v170, 0x3d372713, v162
	v_mul_f32_e32 v171, 0x3d372713, v163
	v_mul_f32_e32 v172, 0x3d372713, v164
	v_mul_f32_e32 v173, 0x3d372713, v165
	v_mul_f32_e32 v174, 0x3d372713, v166
	v_mul_f32_e32 v175, 0x3d372713, v167
	v_mul_f32_e32 v176, 0x3d372713, v168
	v_mul_f32_e32 v177, 0x3d372713, v169
	v_mul_f32_e32 v170, v170, v162
	v_mul_f32_e32 v171, v171, v163
	v_mul_f32_e32 v172, v172, v164
	v_mul_f32_e32 v173, v173, v165
	v_mul_f32_e32 v174, v174, v166
	v_mul_f32_e32 v175, v175, v167
	v_mul_f32_e32 v176, v176, v168
	v_mul_f32_e32 v177, v177, v169
	v_fma_f32 v170, v170, v162, v162
	v_fma_f32 v171, v171, v163, v163
	v_fma_f32 v172, v172, v164, v164
	v_fma_f32 v173, v173, v165, v165
	v_fma_f32 v174, v174, v166, v166
	v_fma_f32 v175, v175, v167, v167
	v_fma_f32 v176, v176, v168, v168
	v_fma_f32 v177, v177, v169, v169
	v_mul_f32_e32 v170, 0x3f4c422a, v170
	v_mul_f32_e32 v171, 0x3f4c422a, v171
	v_mul_f32_e32 v172, 0x3f4c422a, v172
	v_mul_f32_e32 v173, 0x3f4c422a, v173
	v_mul_f32_e32 v174, 0x3f4c422a, v174
	v_mul_f32_e32 v175, 0x3f4c422a, v175
	v_mul_f32_e32 v176, 0x3f4c422a, v176
	v_mul_f32_e32 v177, 0x3f4c422a, v177
	v_add_f32_e32 v170, v170, v170
	v_add_f32_e32 v171, v171, v171
	v_add_f32_e32 v172, v172, v172
	v_add_f32_e32 v173, v173, v173
	v_add_f32_e32 v174, v174, v174
	v_add_f32_e32 v175, v175, v175
	v_add_f32_e32 v176, v176, v176
	v_add_f32_e32 v177, v177, v177
	v_mul_f32_e32 v170, 0x3fb8aa3b, v170
	v_mul_f32_e32 v171, 0x3fb8aa3b, v171
	v_mul_f32_e32 v172, 0x3fb8aa3b, v172
	v_mul_f32_e32 v173, 0x3fb8aa3b, v173
	v_mul_f32_e32 v174, 0x3fb8aa3b, v174
	v_mul_f32_e32 v175, 0x3fb8aa3b, v175
	v_mul_f32_e32 v176, 0x3fb8aa3b, v176
	v_mul_f32_e32 v177, 0x3fb8aa3b, v177
	v_exp_f32_e32 v170, v170
	v_exp_f32_e32 v171, v171
	v_exp_f32_e32 v172, v172
	v_exp_f32_e32 v173, v173
	v_exp_f32_e32 v174, v174
	v_exp_f32_e32 v175, v175
	v_exp_f32_e32 v176, v176
	v_exp_f32_e32 v177, v177
	v_add_f32_e32 v170, 1.0, v170
	v_add_f32_e32 v171, 1.0, v171
	v_add_f32_e32 v172, 1.0, v172
	v_add_f32_e32 v173, 1.0, v173
	v_add_f32_e32 v174, 1.0, v174
	v_add_f32_e32 v175, 1.0, v175
	v_add_f32_e32 v176, 1.0, v176
	v_add_f32_e32 v177, 1.0, v177
	v_rcp_f32_e32 v170, v170
	v_rcp_f32_e32 v171, v171
	v_rcp_f32_e32 v172, v172
	v_rcp_f32_e32 v173, v173
	v_rcp_f32_e32 v174, v174
	v_rcp_f32_e32 v175, v175
	v_rcp_f32_e32 v176, v176
	v_rcp_f32_e32 v177, v177
	v_mul_f32_e32 v162, 0.5, v162
	v_mul_f32_e32 v163, 0.5, v163
	v_mul_f32_e32 v164, 0.5, v164
	v_mul_f32_e32 v165, 0.5, v165
	v_mul_f32_e32 v166, 0.5, v166
	v_mul_f32_e32 v167, 0.5, v167
	v_mul_f32_e32 v168, 0.5, v168
	v_mul_f32_e32 v169, 0.5, v169
	v_fma_f32 v170, v170, -2.0, 1.0
	v_fma_f32 v171, v171, -2.0, 1.0
	v_fma_f32 v172, v172, -2.0, 1.0
	v_fma_f32 v173, v173, -2.0, 1.0
	v_fma_f32 v174, v174, -2.0, 1.0
	v_fma_f32 v175, v175, -2.0, 1.0
	v_fma_f32 v176, v176, -2.0, 1.0
	v_fma_f32 v177, v177, -2.0, 1.0
	v_add_f32_e32 v170, 1.0, v170
	v_add_f32_e32 v171, 1.0, v171
	v_add_f32_e32 v172, 1.0, v172
	v_add_f32_e32 v173, 1.0, v173
	v_add_f32_e32 v174, 1.0, v174
	v_add_f32_e32 v175, 1.0, v175
	v_add_f32_e32 v176, 1.0, v176
	v_add_f32_e32 v177, 1.0, v177
	v_mul_f32_e32 v170, v162, v170
	v_mul_f32_e32 v171, v163, v171
	v_mul_f32_e32 v172, v164, v172
	v_mul_f32_e32 v173, v165, v173
	v_mul_f32_e32 v174, v166, v174
	v_mul_f32_e32 v175, v167, v175
	v_mul_f32_e32 v176, v168, v176
	v_mul_f32_e32 v177, v169, v177
	s_waitcnt lgkmcnt(0)
	v_add_f32_e32 v212, v212, v216
	v_add_f32_e32 v213, v213, v217
	v_add_f32_e32 v214, v214, v218
	v_add_f32_e32 v215, v215, v219
	v_add_f32_e32 v154, v154, v158
	v_add_f32_e32 v155, v155, v159
	v_add_f32_e32 v156, v156, v160
	v_add_f32_e32 v157, v157, v161
	v_mul_f32_e32 v178, v212, v170
	v_mul_f32_e32 v179, v213, v171
	v_mul_f32_e32 v180, v214, v172
	v_mul_f32_e32 v181, v215, v173
	v_mul_f32_e32 v182, v154, v174
	v_mul_f32_e32 v183, v155, v175
	v_mul_f32_e32 v184, v156, v176
	v_mul_f32_e32 v185, v157, v177
	v_mul_f32_e32 v186, v178, v178
	v_mul_f32_e32 v187, v182, v182
	v_fmac_f32_e32 v186, v179, v179
	v_fmac_f32_e32 v187, v183, v183
	v_fmac_f32_e32 v186, v180, v180
	v_fmac_f32_e32 v187, v184, v184
	v_fmac_f32_e32 v186, v181, v181
	v_fmac_f32_e32 v187, v185, v185
	s_nop 1
	v_add_f32_dpp v186, v186, v186 quad_perm:[1,0,3,2] row_mask:0xf bank_mask:0xf
	v_add_f32_dpp v187, v187, v187 quad_perm:[1,0,3,2] row_mask:0xf bank_mask:0xf
	s_nop 0
	v_add_f32_dpp v186, v186, v186 quad_perm:[2,3,0,1] row_mask:0xf bank_mask:0xf
	v_add_f32_dpp v187, v187, v187 quad_perm:[2,3,0,1] row_mask:0xf bank_mask:0xf
	s_nop 0
	v_add_f32_dpp v186, v186, v186 row_half_mirror row_mask:0xf bank_mask:0xf
	v_add_f32_dpp v187, v187, v187 row_half_mirror row_mask:0xf bank_mask:0xf
	s_nop 0
	v_add_f32_dpp v186, v186, v186 row_mirror row_mask:0xf bank_mask:0xf
	v_add_f32_dpp v187, v187, v187 row_mirror row_mask:0xf bank_mask:0xf
	s_nop 0
	v_fmamk_f32 v188, v186, 0x3c800000, v194
	v_fmamk_f32 v189, v187, 0x3c800000, v194
	v_rsq_f32_e32 v188, v188
	v_rsq_f32_e32 v189, v189
	s_nop 0
	v_mul_f32_e32 v178, v178, v188
	v_mul_f32_e32 v179, v179, v188
	v_mul_f32_e32 v180, v180, v188
	v_mul_f32_e32 v181, v181, v188
	v_mul_f32_e32 v182, v182, v189
	v_mul_f32_e32 v183, v183, v189
	v_mul_f32_e32 v184, v184, v189
	v_mul_f32_e32 v185, v185, v189
	v_mul_f32_e32 v178, v178, v200
	v_mul_f32_e32 v179, v179, v201
	v_mul_f32_e32 v180, v180, v202
	v_mul_f32_e32 v181, v181, v203
	v_mul_f32_e32 v182, v182, v200
	v_mul_f32_e32 v183, v183, v201
	v_mul_f32_e32 v184, v184, v202
	v_mul_f32_e32 v185, v185, v203
	v_cvt_pk_bf16_f32 v212, v178, v179
	v_cvt_pk_bf16_f32 v213, v180, v181
	v_cvt_pk_bf16_f32 v154, v182, v183
	v_cvt_pk_bf16_f32 v155, v184, v185
	global_store_dwordx2 v211, v[212:213], s[2:3]
	v_add_u32_e32 v211, 0x2000, v211
	global_store_dwordx2 v211, v[154:155], s[2:3]
	s_barrier
	s_mov_b64 s[0:1], 0

; __device__ __forceinline__ float lo16(unsigned u) { return __uint_as_float(u << 16); }
; __device__ __forceinline__ float hi16(unsigned u) { return __uint_as_float(u & 0xffff0000u); }
; __device__ __forceinline__ float sigm(float x) { return frcp(1.f + fexp(-x)); }
; __device__ void ml_out_tile(unsigned char* lds, const Params& p, int l, int b, int h, int n) {
;     ...
;   {
;     float ss = 0.f;
; #pragma unroll
;     for (int df = 0; df < 8; ++df)
; #pragma unroll
;       for (int j = 0; j < 4; ++j) ss += hsum[df][j] * hsum[df][j];
;     ss += shfl_idx(ss, lane ^ 16);
;     ss += shfl_idx(ss, lane ^ 32);
;     const float rn = rsqrtf(ss * (1.f / 128.f) + EPSF);
;     const float* gm = p.in[24] + (size_t)l * 1024 + 256 + h * 128;
; #pragma unroll
;     for (int df = 0; df < 8; ++df) {
;       const int d = df * 16 + lg * 4;
;       const float4 gg = *(const float4*)(gm + d);
;       float o0 = hsum[df][0] * rn * gg.x * sigm(lo16(ou[df].x));
;       float o1 = hsum[df][1] * rn * gg.y * sigm(hi16(ou[df].x));
;       float o2 = hsum[df][2] * rn * gg.z * sigm(lo16(ou[df].y));
;       float o3 = hsum[df][3] * rn * gg.w * sigm(hi16(ou[df].y));
;       uint2 u; u.x = pack2(o0, o1); u.y = pack2(o2, o3);
;       *(uint2*)(y + (size_t)orow * 1024 + 256 + h * 128 + d) = u;
;     }
;   }
.LBB0_810:
	s_mov_b32 s33, 1
	s_andn2_b64 vcc, exec, s[70:71]
	s_mov_b64 s[72:73], 0
	s_cbranch_vccnz .LBB0_738
	v_readlane_b32 s46, v254, 28
	v_readlane_b32 s44, v254, 9
	v_readlane_b32 s45, v254, 10
	v_lshlrev_b32_e32 v100, 2, v68
	s_lshl_b32 s46, s46, 2
	s_add_u32 s44, s44, s46
	s_addc_u32 s45, s45, 0
	global_load_dwordx4 v[126:129], v100, s[44:45] offset:1024
	global_load_dwordx4 v[130:133], v100, s[44:45] offset:1088
	global_load_dwordx4 v[134:137], v100, s[44:45] offset:1152
	global_load_dwordx4 v[138:141], v100, s[44:45] offset:1216
	global_load_dwordx4 v[142:145], v100, s[44:45] offset:1280
	global_load_dwordx4 v[146:149], v100, s[44:45] offset:1344
	global_load_dwordx4 v[150:153], v100, s[44:45] offset:1408
	global_load_dwordx4 v[154:157], v100, s[44:45] offset:1472
	v_pk_mul_f32 v[0:1], v[84:85], v[84:85]
	v_pk_mul_f32 v[2:3], v[82:83], v[82:83]
	v_add_f32_e32 v0, v0, v1
	v_add_f32_e32 v0, v2, v0
	v_pk_mul_f32 v[4:5], v[78:79], v[78:79]
	v_add_f32_e32 v0, v3, v0
	v_add_f32_e32 v0, v0, v4
	v_pk_mul_f32 v[6:7], v[76:77], v[76:77]
	v_add_f32_e32 v0, v5, v0
	v_add_f32_e32 v0, v6, v0
	v_pk_mul_f32 v[8:9], v[72:73], v[72:73]
	v_add_f32_e32 v0, v7, v0
	v_add_f32_e32 v0, v0, v8
	v_pk_mul_f32 v[10:11], v[70:71], v[70:71]
	v_add_f32_e32 v0, v9, v0
	v_add_f32_e32 v0, v10, v0
	v_pk_mul_f32 v[12:13], v[64:65], v[64:65]
	v_add_f32_e32 v0, v11, v0
	v_add_f32_e32 v0, v0, v12
	v_pk_mul_f32 v[14:15], v[62:63], v[62:63]
	v_add_f32_e32 v0, v13, v0
	v_add_f32_e32 v0, v14, v0
	s_waitcnt vmcnt(0)
	v_pk_mul_f32 v[16:17], v[58:59], v[58:59]
	v_add_f32_e32 v0, v15, v0
	v_add_f32_e32 v0, v0, v16
	v_pk_mul_f32 v[18:19], v[56:57], v[56:57]
	v_add_f32_e32 v0, v17, v0
	v_add_f32_e32 v0, v18, v0
	v_pk_mul_f32 v[20:21], v[52:53], v[52:53]
	v_add_f32_e32 v0, v19, v0
	v_add_f32_e32 v0, v0, v20
	v_pk_mul_f32 v[22:23], v[50:51], v[50:51]
	v_add_f32_e32 v0, v21, v0
	v_add_f32_e32 v0, v22, v0
	v_pk_mul_f32 v[24:25], v[46:47], v[46:47]
	v_add_f32_e32 v0, v23, v0
	v_add_f32_e32 v0, v0, v24
	v_pk_mul_f32 v[26:27], v[44:45], v[44:45]
	v_add_f32_e32 v0, v25, v0
	v_add_f32_e32 v0, v26, v0
	v_pk_mul_f32 v[28:29], v[42:43], v[42:43]
	v_add_f32_e32 v0, v27, v0
	v_add_f32_e32 v0, v0, v28
	v_pk_mul_f32 v[30:31], v[40:41], v[40:41]
	v_add_f32_e32 v0, v29, v0
	v_add_f32_e32 v0, v30, v0
	v_add_f32_e32 v0, v31, v0
	ds_bpermute_b32 v1, v69, v0
	s_mov_b32 s0, 0x800000
	v_readlane_b32 s96, v254, 28
	v_readlane_b32 s2, v254, 9
	v_readlane_b32 s3, v254, 10
	s_waitcnt lgkmcnt(0)
	v_add_f32_e32 v0, v0, v1
	ds_bpermute_b32 v1, v108, v0
	v_readlane_b32 s84, v253, 41
	v_readlane_b32 s97, v254, 29
	v_readlane_b32 s88, v253, 45
	v_readlane_b32 s89, v253, 46
	s_waitcnt lgkmcnt(0)
	v_add_f32_e32 v0, v0, v1
	v_fmamk_f32 v0, v0, 0x3c000000, v194
	v_cmp_gt_f32_e32 vcc, s0, v0
	v_mul_f32_e32 v1, 0x4b800000, v0
	s_lshl_b32 s0, s96, 2
	v_cndmask_b32_e32 v0, v0, v1, vcc
	v_rsq_f32_e32 v0, v0
	s_add_u32 s0, s2, s0
	s_addc_u32 s1, s3, 0
	v_readlane_b32 s2, v254, 30
	v_mul_f32_e32 v1, 0x45800000, v0
	v_cndmask_b32_e32 v4, v0, v1, vcc
	v_lshlrev_b64 v[0:1], 11, v[198:199]
	v_readlane_b32 s3, v254, 31
	v_lshl_add_u64 v[0:1], s[88:89], 0, v[0:1]
	s_mov_b32 s3, s97
	v_lshl_add_u64 v[6:7], v[0:1], 0, s[2:3]
	v_lshlrev_b32_e32 v0, 16, v88
	v_mul_f32_e32 v0, 0xbfb8aa3b, v0
	v_exp_f32_e32 v0, v0
	v_lshlrev_b32_e32 v5, 2, v68
	v_pk_mul_f32 v[10:11], v[84:85], v[4:5] op_sel_hi:[1,0]
	v_lshlrev_b32_e32 v192, 1, v68
	v_add_f32_e32 v0, 1.0, v0
	v_rcp_f32_e32 v8, v0
	v_and_b32_e32 v0, 0xffff0000, v88
	v_mul_f32_e32 v0, 0xbfb8aa3b, v0
	v_exp_f32_e32 v0, v0
	s_mov_b64 s[2:3], 0x8000200
	v_readlane_b32 s91, v253, 48
	v_readlane_b32 s82, v253, 49
	v_add_f32_e32 v0, 1.0, v0
	v_rcp_f32_e32 v9, v0
	v_mov_b64_e32 v[0:1], v[126:127]
	v_mov_b64_e32 v[2:3], v[128:129]
	v_readlane_b32 s85, v253, 42
	v_readlane_b32 s86, v253, 43
	v_readlane_b32 s87, v253, 44
	v_readlane_b32 s90, v253, 47
	v_readlane_b32 s83, v253, 50
	s_movk_i32 s91, 0x80
	s_movk_i32 s92, 0x1a00
	s_movk_i32 s93, 0x110
	v_readlane_b32 s94, v253, 52
	v_readlane_b32 s29, v254, 24
	v_readlane_b32 s30, v254, 18
	v_readlane_b32 s14, v254, 19
	v_readlane_b32 s13, v254, 25
	v_readlane_b32 s15, v254, 20
	v_pk_mul_f32 v[0:1], v[0:1], v[10:11]
	s_nop 0
	v_pk_mul_f32 v[0:1], v[8:9], v[0:1]
	v_lshlrev_b32_e32 v8, 16, v89
	v_and_b32_e32 v9, 0xffff0000, v89
	v_mul_f32_e32 v8, 0xbfb8aa3b, v8
	v_mul_f32_e32 v9, 0xbfb8aa3b, v9
	v_exp_f32_e32 v8, v8
	v_exp_f32_e32 v9, v9
	v_pk_mul_f32 v[10:11], v[82:83], v[4:5] op_sel_hi:[1,0]
	v_add_f32_e32 v8, 1.0, v8
	v_add_f32_e32 v9, 1.0, v9
	v_rcp_f32_e32 v8, v8
	v_rcp_f32_e32 v9, v9
	v_pk_mul_f32 v[2:3], v[2:3], v[10:11]
	v_pk_mul_f32 v[10:11], v[78:79], v[4:5] op_sel_hi:[1,0]
	v_pk_mul_f32 v[2:3], v[8:9], v[2:3]
	s_nop 0
	v_cvt_pk_bf16_f32 v9, v2, v3
	v_lshl_add_u64 v[2:3], v[6:7], 0, v[192:193]
	v_cvt_pk_bf16_f32 v8, v0, v1
	v_lshl_add_u64 v[0:1], v[2:3], 0, s[2:3]
	s_brev_b32 s2, 16
	v_add_co_u32_e32 v2, vcc, s2, v2
	s_nop 1
	v_addc_co_u32_e32 v3, vcc, 0, v3, vcc
	global_store_dwordx2 v[2:3], v[8:9], off offset:512
	v_mov_b64_e32 v[6:7], v[130:131]
	v_mov_b64_e32 v[8:9], v[132:133]
	v_lshlrev_b32_e32 v2, 16, v86
	v_and_b32_e32 v3, 0xffff0000, v86
	v_mul_f32_e32 v2, 0xbfb8aa3b, v2
	v_mul_f32_e32 v3, 0xbfb8aa3b, v3
	v_exp_f32_e32 v2, v2
	v_exp_f32_e32 v3, v3
	v_add_f32_e32 v2, 1.0, v2
	v_add_f32_e32 v3, 1.0, v3
	v_rcp_f32_e32 v2, v2
	v_rcp_f32_e32 v3, v3
	v_pk_mul_f32 v[6:7], v[6:7], v[10:11]
	s_nop 0
	v_pk_mul_f32 v[2:3], v[2:3], v[6:7]
	v_lshlrev_b32_e32 v6, 16, v87
	v_and_b32_e32 v7, 0xffff0000, v87
	v_mul_f32_e32 v6, 0xbfb8aa3b, v6
	v_mul_f32_e32 v7, 0xbfb8aa3b, v7
	v_exp_f32_e32 v6, v6
	v_exp_f32_e32 v7, v7
; __device__ __forceinline__ float lo16(unsigned u) { return __uint_as_float(u << 16); }
; __device__ __forceinline__ float hi16(unsigned u) { return __uint_as_float(u & 0xffff0000u); }
; __device__ __forceinline__ float sigm(float x) { return frcp(1.f + fexp(-x)); }
; __device__ void ml_out_tile(unsigned char* lds, const Params& p, int l, int b, int h, int n) {
;     ...
; #pragma unroll
;     for (int df = 0; df < 8; ++df) {
;       const int d = df * 16 + lg * 4;
;       const float4 gg = *(const float4*)(gm + d);
;       float o0 = hsum[df][0] * rn * gg.x * sigm(lo16(ou[df].x));
;       float o1 = hsum[df][1] * rn * gg.y * sigm(hi16(ou[df].x));
;       float o2 = hsum[df][2] * rn * gg.z * sigm(lo16(ou[df].y));
;       float o3 = hsum[df][3] * rn * gg.w * sigm(hi16(ou[df].y));
;       uint2 u; u.x = pack2(o0, o1); u.y = pack2(o2, o3);
;       *(uint2*)(y + (size_t)orow * 1024 + 256 + h * 128 + d) = u;
;     }
;   }
	v_pk_mul_f32 v[10:11], v[76:77], v[4:5] op_sel_hi:[1,0]
	v_cvt_pk_bf16_f32 v2, v2, v3
	v_add_f32_e32 v6, 1.0, v6
	v_add_f32_e32 v7, 1.0, v7
	v_rcp_f32_e32 v6, v6
	v_rcp_f32_e32 v7, v7
	v_pk_mul_f32 v[8:9], v[8:9], v[10:11]
	v_pk_mul_f32 v[10:11], v[72:73], v[4:5] op_sel_hi:[1,0]
	v_pk_mul_f32 v[6:7], v[6:7], v[8:9]
	s_nop 0
	v_cvt_pk_bf16_f32 v3, v6, v7
	global_store_dwordx2 v[0:1], v[2:3], off offset:32
	v_mov_b64_e32 v[6:7], v[134:135]
	v_mov_b64_e32 v[8:9], v[136:137]
	v_lshlrev_b32_e32 v2, 16, v80
	v_and_b32_e32 v3, 0xffff0000, v80
	v_mul_f32_e32 v2, 0xbfb8aa3b, v2
	v_mul_f32_e32 v3, 0xbfb8aa3b, v3
	v_exp_f32_e32 v2, v2
	v_exp_f32_e32 v3, v3
	v_add_f32_e32 v2, 1.0, v2
	v_add_f32_e32 v3, 1.0, v3
	v_rcp_f32_e32 v2, v2
	v_rcp_f32_e32 v3, v3
	v_pk_mul_f32 v[6:7], v[10:11], v[6:7]
	s_nop 0
	v_pk_mul_f32 v[2:3], v[2:3], v[6:7]
	v_lshlrev_b32_e32 v6, 16, v81
	v_and_b32_e32 v7, 0xffff0000, v81
	v_mul_f32_e32 v6, 0xbfb8aa3b, v6
	v_mul_f32_e32 v7, 0xbfb8aa3b, v7
	v_exp_f32_e32 v6, v6
	v_exp_f32_e32 v7, v7
	v_pk_mul_f32 v[10:11], v[70:71], v[4:5] op_sel_hi:[1,0]
	v_cvt_pk_bf16_f32 v2, v2, v3
	v_add_f32_e32 v6, 1.0, v6
	v_add_f32_e32 v7, 1.0, v7
	v_rcp_f32_e32 v6, v6
	v_rcp_f32_e32 v7, v7
	v_pk_mul_f32 v[8:9], v[10:11], v[8:9]
	v_pk_mul_f32 v[10:11], v[64:65], v[4:5] op_sel_hi:[1,0]
	v_pk_mul_f32 v[6:7], v[6:7], v[8:9]
	s_nop 0
	v_cvt_pk_bf16_f32 v3, v6, v7
	global_store_dwordx2 v[0:1], v[2:3], off offset:64
	v_mov_b64_e32 v[6:7], v[138:139]
	v_mov_b64_e32 v[8:9], v[140:141]
	v_lshlrev_b32_e32 v2, 16, v74
	v_and_b32_e32 v3, 0xffff0000, v74
	v_mul_f32_e32 v2, 0xbfb8aa3b, v2
	v_mul_f32_e32 v3, 0xbfb8aa3b, v3
	v_exp_f32_e32 v2, v2
	v_exp_f32_e32 v3, v3
	v_add_f32_e32 v2, 1.0, v2
	v_add_f32_e32 v3, 1.0, v3
	v_rcp_f32_e32 v2, v2
	v_rcp_f32_e32 v3, v3
	v_pk_mul_f32 v[6:7], v[10:11], v[6:7]
	s_nop 0
	v_pk_mul_f32 v[2:3], v[2:3], v[6:7]
	v_lshlrev_b32_e32 v6, 16, v75
	v_and_b32_e32 v7, 0xffff0000, v75
	v_mul_f32_e32 v6, 0xbfb8aa3b, v6
	v_mul_f32_e32 v7, 0xbfb8aa3b, v7
	v_exp_f32_e32 v6, v6
	v_exp_f32_e32 v7, v7
	v_pk_mul_f32 v[10:11], v[62:63], v[4:5] op_sel_hi:[1,0]
	v_cvt_pk_bf16_f32 v2, v2, v3
	v_add_f32_e32 v6, 1.0, v6
	v_add_f32_e32 v7, 1.0, v7
	v_rcp_f32_e32 v6, v6
	v_rcp_f32_e32 v7, v7
	v_pk_mul_f32 v[8:9], v[10:11], v[8:9]
	v_pk_mul_f32 v[10:11], v[58:59], v[4:5] op_sel_hi:[1,0]
	v_pk_mul_f32 v[6:7], v[6:7], v[8:9]
	s_nop 0
	v_cvt_pk_bf16_f32 v3, v6, v7
	global_store_dwordx2 v[0:1], v[2:3], off offset:96
	v_mov_b64_e32 v[6:7], v[142:143]
	v_mov_b64_e32 v[8:9], v[144:145]
	v_lshlrev_b32_e32 v2, 16, v66
	v_and_b32_e32 v3, 0xffff0000, v66
	v_mul_f32_e32 v2, 0xbfb8aa3b, v2
	v_mul_f32_e32 v3, 0xbfb8aa3b, v3
	v_exp_f32_e32 v2, v2
	v_exp_f32_e32 v3, v3
	v_add_f32_e32 v2, 1.0, v2
	v_add_f32_e32 v3, 1.0, v3
	v_rcp_f32_e32 v2, v2
	v_rcp_f32_e32 v3, v3
	v_pk_mul_f32 v[6:7], v[10:11], v[6:7]
	s_nop 0
	v_pk_mul_f32 v[2:3], v[2:3], v[6:7]
	v_lshlrev_b32_e32 v6, 16, v67
	v_and_b32_e32 v7, 0xffff0000, v67
	v_mul_f32_e32 v6, 0xbfb8aa3b, v6
	v_mul_f32_e32 v7, 0xbfb8aa3b, v7
	v_exp_f32_e32 v6, v6
	v_exp_f32_e32 v7, v7
	v_pk_mul_f32 v[10:11], v[56:57], v[4:5] op_sel_hi:[1,0]
	v_cvt_pk_bf16_f32 v2, v2, v3
	v_add_f32_e32 v6, 1.0, v6
	v_add_f32_e32 v7, 1.0, v7
	v_rcp_f32_e32 v6, v6
	v_rcp_f32_e32 v7, v7
	v_pk_mul_f32 v[8:9], v[10:11], v[8:9]
	v_pk_mul_f32 v[10:11], v[52:53], v[4:5] op_sel_hi:[1,0]
	v_pk_mul_f32 v[6:7], v[6:7], v[8:9]
	s_nop 0
	v_cvt_pk_bf16_f32 v3, v6, v7
	global_store_dwordx2 v[0:1], v[2:3], off offset:128
	v_mov_b64_e32 v[6:7], v[146:147]
	v_mov_b64_e32 v[8:9], v[148:149]
	v_lshlrev_b32_e32 v2, 16, v60
	v_and_b32_e32 v3, 0xffff0000, v60
	v_mul_f32_e32 v2, 0xbfb8aa3b, v2
	v_mul_f32_e32 v3, 0xbfb8aa3b, v3
	v_exp_f32_e32 v2, v2
	v_exp_f32_e32 v3, v3
	v_add_f32_e32 v2, 1.0, v2
	v_add_f32_e32 v3, 1.0, v3
	v_rcp_f32_e32 v2, v2
	v_rcp_f32_e32 v3, v3
	v_pk_mul_f32 v[6:7], v[10:11], v[6:7]
	s_nop 0
	v_pk_mul_f32 v[2:3], v[2:3], v[6:7]
	v_lshlrev_b32_e32 v6, 16, v61
	v_and_b32_e32 v7, 0xffff0000, v61
	v_mul_f32_e32 v6, 0xbfb8aa3b, v6
	v_mul_f32_e32 v7, 0xbfb8aa3b, v7
	v_exp_f32_e32 v6, v6
	v_exp_f32_e32 v7, v7
	v_pk_mul_f32 v[10:11], v[50:51], v[4:5] op_sel_hi:[1,0]
	v_cvt_pk_bf16_f32 v2, v2, v3
	v_add_f32_e32 v6, 1.0, v6
	v_add_f32_e32 v7, 1.0, v7
	v_rcp_f32_e32 v6, v6
	v_rcp_f32_e32 v7, v7
	v_pk_mul_f32 v[8:9], v[10:11], v[8:9]
	v_pk_mul_f32 v[10:11], v[46:47], v[4:5] op_sel_hi:[1,0]
	v_pk_mul_f32 v[6:7], v[6:7], v[8:9]
	s_nop 0
	v_cvt_pk_bf16_f32 v3, v6, v7
	global_store_dwordx2 v[0:1], v[2:3], off offset:160
	v_mov_b64_e32 v[6:7], v[150:151]
	v_mov_b64_e32 v[8:9], v[152:153]
	v_lshlrev_b32_e32 v2, 16, v54
	v_and_b32_e32 v3, 0xffff0000, v54
	v_mul_f32_e32 v2, 0xbfb8aa3b, v2
	v_mul_f32_e32 v3, 0xbfb8aa3b, v3
	v_exp_f32_e32 v2, v2
	v_exp_f32_e32 v3, v3
	v_add_f32_e32 v2, 1.0, v2
	v_add_f32_e32 v3, 1.0, v3
	v_rcp_f32_e32 v2, v2
	v_rcp_f32_e32 v3, v3
	v_pk_mul_f32 v[6:7], v[10:11], v[6:7]
	s_nop 0
	v_pk_mul_f32 v[2:3], v[2:3], v[6:7]
	v_lshlrev_b32_e32 v6, 16, v55
	v_and_b32_e32 v7, 0xffff0000, v55
	v_mul_f32_e32 v6, 0xbfb8aa3b, v6
	v_mul_f32_e32 v7, 0xbfb8aa3b, v7
	v_exp_f32_e32 v6, v6
	v_exp_f32_e32 v7, v7
	v_pk_mul_f32 v[10:11], v[44:45], v[4:5] op_sel_hi:[1,0]
	v_cvt_pk_bf16_f32 v2, v2, v3
	v_add_f32_e32 v6, 1.0, v6
	v_add_f32_e32 v7, 1.0, v7
	v_rcp_f32_e32 v6, v6
	v_rcp_f32_e32 v7, v7
	v_pk_mul_f32 v[8:9], v[10:11], v[8:9]
	v_pk_mul_f32 v[10:11], v[42:43], v[4:5] op_sel_hi:[1,0]
	v_pk_mul_f32 v[6:7], v[6:7], v[8:9]
	s_nop 0
	v_cvt_pk_bf16_f32 v3, v6, v7
	global_store_dwordx2 v[0:1], v[2:3], off offset:192
	v_mov_b64_e32 v[6:7], v[154:155]
	v_mov_b64_e32 v[8:9], v[156:157]
	v_lshlrev_b32_e32 v2, 16, v48
	v_and_b32_e32 v3, 0xffff0000, v48
	v_mul_f32_e32 v2, 0xbfb8aa3b, v2
	v_mul_f32_e32 v3, 0xbfb8aa3b, v3
	v_exp_f32_e32 v2, v2
	v_exp_f32_e32 v3, v3
	v_lshlrev_b32_e32 v5, 16, v49
	v_mul_f32_e32 v5, 0xbfb8aa3b, v5
	v_add_f32_e32 v2, 1.0, v2
	v_add_f32_e32 v3, 1.0, v3
	v_exp_f32_e32 v5, v5
	v_rcp_f32_e32 v2, v2
	v_rcp_f32_e32 v3, v3
	v_add_f32_e32 v5, 1.0, v5
	v_pk_mul_f32 v[6:7], v[10:11], v[6:7]
	s_nop 0
	v_pk_mul_f32 v[2:3], v[2:3], v[6:7]
	v_rcp_f32_e32 v6, v5
	v_and_b32_e32 v5, 0xffff0000, v49
	v_mul_f32_e32 v5, 0xbfb8aa3b, v5
	v_exp_f32_e32 v5, v5
	v_cvt_pk_bf16_f32 v2, v2, v3
	v_add_f32_e32 v5, 1.0, v5
	v_rcp_f32_e32 v7, v5
	v_pk_mul_f32 v[4:5], v[40:41], v[4:5] op_sel_hi:[1,0]
	s_nop 0
	v_pk_mul_f32 v[4:5], v[4:5], v[8:9]
	s_nop 0
	v_pk_mul_f32 v[4:5], v[6:7], v[4:5]
	s_nop 0
	v_cvt_pk_bf16_f32 v3, v4, v5
	global_store_dwordx2 v[0:1], v[2:3], off offset:224
	s_barrier
	s_branch .LBB0_638
